# v70 + conv epilogue store addresses: 64-bit v_mov_b64/v_mad_i64_i32/v_lshl_add_u64 replaced by v_mul_u32_u24 + v_lshl_add_u32 with SGPR-base stores
# speedup vs baseline: 1.0065x; 1.0065x over previous
.LBB0_1161:
	v_pk_mul_f32 v[150:151], v[150:151], v[204:205] op_sel_hi:[1,0]
	v_pk_mul_f32 v[148:149], v[148:149], v[204:205] op_sel_hi:[1,0]
	v_pk_mul_f32 v[134:135], v[134:135], v[204:205] op_sel_hi:[1,0]
	v_pk_mul_f32 v[132:133], v[132:133], v[204:205] op_sel_hi:[1,0]
	v_cmp_gt_i32_e32 vcc, s73, v197
	v_mov_b32_dpp v172, v148 row_shr:1 row_mask:0xf bank_mask:0xf bound_ctrl:1
	v_mov_b32_dpp v168, v148 row_shr:2 row_mask:0xf bank_mask:0xf bound_ctrl:1
	v_mov_b32_dpp v218, v132 row_shr:1 row_mask:0xf bank_mask:0xf bound_ctrl:1
	v_mov_b32_dpp v214, v132 row_shr:2 row_mask:0xf bank_mask:0xf bound_ctrl:1
	v_mov_b32_dpp v173, v149 row_shr:1 row_mask:0xf bank_mask:0xf bound_ctrl:1
	v_mov_b32_dpp v169, v149 row_shr:2 row_mask:0xf bank_mask:0xf bound_ctrl:1
	v_mov_b32_dpp v219, v133 row_shr:1 row_mask:0xf bank_mask:0xf bound_ctrl:1
	v_mov_b32_dpp v215, v133 row_shr:2 row_mask:0xf bank_mask:0xf bound_ctrl:1
	v_mov_b32_dpp v174, v150 row_shr:1 row_mask:0xf bank_mask:0xf bound_ctrl:1
	v_mov_b32_dpp v170, v150 row_shr:2 row_mask:0xf bank_mask:0xf bound_ctrl:1
	v_mov_b32_dpp v220, v134 row_shr:1 row_mask:0xf bank_mask:0xf bound_ctrl:1
	v_mov_b32_dpp v216, v134 row_shr:2 row_mask:0xf bank_mask:0xf bound_ctrl:1
	v_mov_b32_dpp v175, v151 row_shr:1 row_mask:0xf bank_mask:0xf bound_ctrl:1
	v_mov_b32_dpp v171, v151 row_shr:2 row_mask:0xf bank_mask:0xf bound_ctrl:1
	v_mov_b32_dpp v221, v135 row_shr:1 row_mask:0xf bank_mask:0xf bound_ctrl:1
	v_mov_b32_dpp v217, v135 row_shr:2 row_mask:0xf bank_mask:0xf bound_ctrl:1
	s_and_b64 s[0:1], s[10:11], vcc
	v_add_u32_e32 v201, s33, v197
	s_and_saveexec_b64 s[12:13], s[0:1]
	s_cbranch_execz .LBB0_1163
	s_waitcnt lgkmcnt(0)
	v_pk_add_f32 v[160:161], v[160:161], v[168:169]
	v_pk_add_f32 v[162:163], v[162:163], v[170:171]
	v_pk_add_f32 v[174:175], v[208:209], v[174:175]
	v_pk_add_f32 v[172:173], v[206:207], v[172:173]
	s_waitcnt vmcnt(0)
	v_pk_fma_f32 v[162:163], v[126:127], v[162:163], v[130:131]
	v_pk_fma_f32 v[160:161], v[124:125], v[160:161], v[128:129]
	v_pk_fma_f32 v[162:163], v[122:123], v[174:175], v[162:163]
	v_pk_fma_f32 v[160:161], v[120:121], v[172:173], v[160:161]
	v_pk_fma_f32 v[162:163], v[150:151], v[118:119], v[162:163]
	v_pk_fma_f32 v[160:161], v[148:149], v[116:117], v[160:161]
	v_mul_f32_e32 v170, 0xbfb8aa3b, v162
	v_mul_f32_e32 v168, 0xbfb8aa3b, v160
	v_mul_f32_e32 v169, 0xbfb8aa3b, v161
	v_mul_f32_e32 v171, 0xbfb8aa3b, v163
	v_exp_f32_e32 v168, v168
	v_exp_f32_e32 v169, v169
	v_exp_f32_e32 v170, v170
	v_exp_f32_e32 v171, v171
	v_add_f32_e32 v168, 1.0, v168
	v_add_f32_e32 v169, 1.0, v169
	v_add_f32_e32 v170, 1.0, v170
	v_add_f32_e32 v171, 1.0, v171
	v_rcp_f32_e32 v168, v168
	v_rcp_f32_e32 v169, v169
	v_rcp_f32_e32 v170, v170
	v_rcp_f32_e32 v171, v171
	v_pk_add_f32 v[164:165], v[164:165], v[214:215]
	v_pk_add_f32 v[166:167], v[166:167], v[216:217]
	v_pk_add_f32 v[212:213], v[212:213], v[220:221]
	v_pk_add_f32 v[210:211], v[210:211], v[218:219]
	v_pk_fma_f32 v[166:167], v[142:143], v[166:167], v[146:147]
	v_pk_fma_f32 v[164:165], v[140:141], v[164:165], v[144:145]
	v_pk_fma_f32 v[166:167], v[138:139], v[212:213], v[166:167]
	v_pk_fma_f32 v[164:165], v[136:137], v[210:211], v[164:165]
	v_pk_fma_f32 v[166:167], v[134:135], v[114:115], v[166:167]
	v_pk_fma_f32 v[164:165], v[132:133], v[112:113], v[164:165]
	v_pk_mul_f32 v[160:161], v[160:161], v[168:169]
	v_pk_mul_f32 v[162:163], v[162:163], v[170:171]
	v_pk_mul_f32 v[160:161], v[164:165], v[160:161]
	v_pk_mul_f32 v[162:163], v[166:167], v[162:163]
	v_cvt_pk_bf16_f32 v160, v160, v161
	v_cvt_pk_bf16_f32 v161, v162, v163
	v_mul_u32_u24_e32 v162, s92, v201
	v_lshl_add_u32 v162, v192, 1, v162
	global_store_dwordx2 v162, v[160:161], s[34:35]
.LBB0_1163:
	s_or_b64 exec, exec, s[12:13]
	v_pk_mul_f32 v[110:111], v[110:111], v[202:203] op_sel_hi:[1,0]
	v_pk_mul_f32 v[108:109], v[108:109], v[202:203] op_sel_hi:[1,0]
	v_pk_mul_f32 v[98:99], v[98:99], v[202:203] op_sel_hi:[1,0]
	v_pk_mul_f32 v[96:97], v[96:97], v[202:203] op_sel_hi:[1,0]
	v_add_u32_e32 v197, s18, v225
	s_waitcnt lgkmcnt(0)
	v_mov_b32_dpp v164, v148 row_shl:15 row_mask:0xf bank_mask:0xf bound_ctrl:1
	v_mov_b32_dpp v148, v148 row_shl:14 row_mask:0xf bank_mask:0xf bound_ctrl:1
	v_mov_b32_dpp v206, v132 row_shl:15 row_mask:0xf bank_mask:0xf bound_ctrl:1
	v_mov_b32_dpp v172, v132 row_shl:14 row_mask:0xf bank_mask:0xf bound_ctrl:1
	v_mov_b32_dpp v165, v149 row_shl:15 row_mask:0xf bank_mask:0xf bound_ctrl:1
	v_mov_b32_dpp v149, v149 row_shl:14 row_mask:0xf bank_mask:0xf bound_ctrl:1
	v_mov_b32_dpp v207, v133 row_shl:15 row_mask:0xf bank_mask:0xf bound_ctrl:1
	v_mov_b32_dpp v173, v133 row_shl:14 row_mask:0xf bank_mask:0xf bound_ctrl:1
	v_mov_b32_dpp v168, v150 row_shl:15 row_mask:0xf bank_mask:0xf bound_ctrl:1
	v_mov_b32_dpp v150, v150 row_shl:14 row_mask:0xf bank_mask:0xf bound_ctrl:1
	v_mov_b32_dpp v212, v134 row_shl:15 row_mask:0xf bank_mask:0xf bound_ctrl:1
	v_mov_b32_dpp v134, v134 row_shl:14 row_mask:0xf bank_mask:0xf bound_ctrl:1
	v_mov_b32_dpp v169, v151 row_shl:15 row_mask:0xf bank_mask:0xf bound_ctrl:1
	v_mov_b32_dpp v151, v151 row_shl:14 row_mask:0xf bank_mask:0xf bound_ctrl:1
	v_mov_b32_dpp v213, v135 row_shl:15 row_mask:0xf bank_mask:0xf bound_ctrl:1
	v_mov_b32_dpp v135, v135 row_shl:14 row_mask:0xf bank_mask:0xf bound_ctrl:1
	v_add_f32_dpp v162, v108, v164 row_shr:1 row_mask:0xf bank_mask:0xf bound_ctrl:1
	v_add_f32_dpp v148, v108, v148 row_shr:2 row_mask:0xf bank_mask:0xf bound_ctrl:1
	v_add_f32_dpp v174, v96, v206 row_shr:1 row_mask:0xf bank_mask:0xf bound_ctrl:1
	v_add_f32_dpp v170, v96, v172 row_shr:2 row_mask:0xf bank_mask:0xf bound_ctrl:1
	v_add_f32_dpp v163, v109, v165 row_shr:1 row_mask:0xf bank_mask:0xf bound_ctrl:1
	v_add_f32_dpp v149, v109, v149 row_shr:2 row_mask:0xf bank_mask:0xf bound_ctrl:1
	v_add_f32_dpp v175, v97, v207 row_shr:1 row_mask:0xf bank_mask:0xf bound_ctrl:1
	v_add_f32_dpp v171, v97, v173 row_shr:2 row_mask:0xf bank_mask:0xf bound_ctrl:1
	v_add_f32_dpp v166, v110, v168 row_shr:1 row_mask:0xf bank_mask:0xf bound_ctrl:1
	v_add_f32_dpp v132, v110, v150 row_shr:2 row_mask:0xf bank_mask:0xf bound_ctrl:1
	v_add_f32_dpp v210, v98, v212 row_shr:1 row_mask:0xf bank_mask:0xf bound_ctrl:1
	v_add_f32_dpp v134, v98, v134 row_shr:2 row_mask:0xf bank_mask:0xf bound_ctrl:1
	v_add_f32_dpp v167, v111, v169 row_shr:1 row_mask:0xf bank_mask:0xf bound_ctrl:1
	v_add_f32_dpp v133, v111, v151 row_shr:2 row_mask:0xf bank_mask:0xf bound_ctrl:1
	v_add_f32_dpp v211, v99, v213 row_shr:1 row_mask:0xf bank_mask:0xf bound_ctrl:1
	v_add_f32_dpp v135, v99, v135 row_shr:2 row_mask:0xf bank_mask:0xf bound_ctrl:1
	v_cmp_gt_i32_e64 s[12:13], s73, v197
	v_add_u32_e32 v199, s33, v197
	s_and_saveexec_b64 s[14:15], s[12:13]
	s_cbranch_execz .LBB0_1165
	s_waitcnt vmcnt(0)
	v_pk_fma_f32 v[132:133], v[126:127], v[132:133], v[130:131]
	v_pk_fma_f32 v[132:133], v[122:123], v[166:167], v[132:133]
	v_pk_fma_f32 v[148:149], v[124:125], v[148:149], v[128:129]
	v_pk_fma_f32 v[132:133], v[110:111], v[118:119], v[132:133]
	v_pk_fma_f32 v[148:149], v[120:121], v[162:163], v[148:149]
	v_mul_f32_e32 v160, 0xbfb8aa3b, v132
	v_mul_f32_e32 v161, 0xbfb8aa3b, v133
	v_pk_fma_f32 v[148:149], v[108:109], v[116:117], v[148:149]
	v_exp_f32_e32 v160, v160
	v_exp_f32_e32 v161, v161
	v_mul_f32_e32 v150, 0xbfb8aa3b, v148
	v_mul_f32_e32 v151, 0xbfb8aa3b, v149
	v_exp_f32_e32 v150, v150
	v_exp_f32_e32 v151, v151
	v_add_f32_e32 v160, 1.0, v160
	v_add_f32_e32 v161, 1.0, v161
	v_rcp_f32_e32 v160, v160
	v_rcp_f32_e32 v161, v161
	v_add_f32_e32 v150, 1.0, v150
	v_add_f32_e32 v151, 1.0, v151
	v_pk_fma_f32 v[134:135], v[142:143], v[134:135], v[146:147]
	v_rcp_f32_e32 v150, v150
	v_rcp_f32_e32 v151, v151
	v_pk_fma_f32 v[134:135], v[138:139], v[210:211], v[134:135]
	v_pk_fma_f32 v[170:171], v[140:141], v[170:171], v[144:145]
	v_pk_fma_f32 v[134:135], v[98:99], v[114:115], v[134:135]
	v_pk_mul_f32 v[132:133], v[132:133], v[160:161]
	v_pk_fma_f32 v[170:171], v[136:137], v[174:175], v[170:171]
	v_pk_mul_f32 v[132:133], v[134:135], v[132:133]
	v_pk_fma_f32 v[162:163], v[96:97], v[112:113], v[170:171]
	v_pk_mul_f32 v[148:149], v[148:149], v[150:151]
	v_cvt_pk_bf16_f32 v135, v132, v133
	v_pk_mul_f32 v[148:149], v[162:163], v[148:149]
	v_mul_u32_u24_e32 v132, s92, v199
	v_cvt_pk_bf16_f32 v134, v148, v149
	v_lshl_add_u32 v132, v192, 1, v132
	global_store_dwordx2 v132, v[134:135], s[34:35]
.LBB0_1165:
	s_or_b64 exec, exec, s[14:15]
	v_pk_mul_f32 v[94:95], v[94:95], v[200:201] op_sel_hi:[1,0]
	v_pk_mul_f32 v[92:93], v[92:93], v[200:201] op_sel_hi:[1,0]
	v_pk_mul_f32 v[90:91], v[90:91], v[200:201] op_sel_hi:[1,0]
	v_pk_mul_f32 v[88:89], v[88:89], v[200:201] op_sel_hi:[1,0]
	v_add_u32_e32 v197, s18, v226
	v_mov_b32_dpp v148, v108 row_shl:15 row_mask:0xf bank_mask:0xf bound_ctrl:1
	v_mov_b32_dpp v108, v108 row_shl:14 row_mask:0xf bank_mask:0xf bound_ctrl:1
	v_mov_b32_dpp v168, v96 row_shl:15 row_mask:0xf bank_mask:0xf bound_ctrl:1
	v_mov_b32_dpp v164, v96 row_shl:14 row_mask:0xf bank_mask:0xf bound_ctrl:1
	v_mov_b32_dpp v149, v109 row_shl:15 row_mask:0xf bank_mask:0xf bound_ctrl:1
	v_mov_b32_dpp v109, v109 row_shl:14 row_mask:0xf bank_mask:0xf bound_ctrl:1
	v_mov_b32_dpp v169, v97 row_shl:15 row_mask:0xf bank_mask:0xf bound_ctrl:1
	v_mov_b32_dpp v165, v97 row_shl:14 row_mask:0xf bank_mask:0xf bound_ctrl:1
	v_mov_b32_dpp v160, v110 row_shl:15 row_mask:0xf bank_mask:0xf bound_ctrl:1
	v_mov_b32_dpp v110, v110 row_shl:14 row_mask:0xf bank_mask:0xf bound_ctrl:1
	v_mov_b32_dpp v174, v98 row_shl:15 row_mask:0xf bank_mask:0xf bound_ctrl:1
	v_mov_b32_dpp v98, v98 row_shl:14 row_mask:0xf bank_mask:0xf bound_ctrl:1
	v_mov_b32_dpp v161, v111 row_shl:15 row_mask:0xf bank_mask:0xf bound_ctrl:1
	v_mov_b32_dpp v111, v111 row_shl:14 row_mask:0xf bank_mask:0xf bound_ctrl:1
	v_mov_b32_dpp v175, v99 row_shl:15 row_mask:0xf bank_mask:0xf bound_ctrl:1
	v_mov_b32_dpp v99, v99 row_shl:14 row_mask:0xf bank_mask:0xf bound_ctrl:1
	v_add_f32_dpp v134, v92, v148 row_shr:1 row_mask:0xf bank_mask:0xf bound_ctrl:1
	v_add_f32_dpp v108, v92, v108 row_shr:2 row_mask:0xf bank_mask:0xf bound_ctrl:1
	v_add_f32_dpp v166, v88, v168 row_shr:1 row_mask:0xf bank_mask:0xf bound_ctrl:1
	v_add_f32_dpp v162, v88, v164 row_shr:2 row_mask:0xf bank_mask:0xf bound_ctrl:1
	v_add_f32_dpp v135, v93, v149 row_shr:1 row_mask:0xf bank_mask:0xf bound_ctrl:1
	v_add_f32_dpp v109, v93, v109 row_shr:2 row_mask:0xf bank_mask:0xf bound_ctrl:1
	v_add_f32_dpp v167, v89, v169 row_shr:1 row_mask:0xf bank_mask:0xf bound_ctrl:1
	v_add_f32_dpp v163, v89, v165 row_shr:2 row_mask:0xf bank_mask:0xf bound_ctrl:1
	v_add_f32_dpp v150, v94, v160 row_shr:1 row_mask:0xf bank_mask:0xf bound_ctrl:1
	v_add_f32_dpp v96, v94, v110 row_shr:2 row_mask:0xf bank_mask:0xf bound_ctrl:1
	v_add_f32_dpp v172, v90, v174 row_shr:1 row_mask:0xf bank_mask:0xf bound_ctrl:1
	v_add_f32_dpp v98, v90, v98 row_shr:2 row_mask:0xf bank_mask:0xf bound_ctrl:1
	v_add_f32_dpp v151, v95, v161 row_shr:1 row_mask:0xf bank_mask:0xf bound_ctrl:1
	v_add_f32_dpp v97, v95, v111 row_shr:2 row_mask:0xf bank_mask:0xf bound_ctrl:1
	v_add_f32_dpp v173, v91, v175 row_shr:1 row_mask:0xf bank_mask:0xf bound_ctrl:1
	v_add_f32_dpp v99, v91, v99 row_shr:2 row_mask:0xf bank_mask:0xf bound_ctrl:1
	v_cmp_gt_i32_e64 s[14:15], s73, v197
	v_add_u32_e32 v197, s33, v197
	s_and_saveexec_b64 s[16:17], s[14:15]
	s_cbranch_execz .LBB0_1167
	s_waitcnt vmcnt(0)
	v_pk_fma_f32 v[96:97], v[126:127], v[96:97], v[130:131]
	v_pk_fma_f32 v[96:97], v[122:123], v[150:151], v[96:97]
	v_pk_fma_f32 v[108:109], v[124:125], v[108:109], v[128:129]
	v_pk_fma_f32 v[96:97], v[94:95], v[118:119], v[96:97]
	v_pk_fma_f32 v[108:109], v[120:121], v[134:135], v[108:109]
	v_mul_f32_e32 v132, 0xbfb8aa3b, v96
	v_mul_f32_e32 v133, 0xbfb8aa3b, v97
	v_pk_fma_f32 v[108:109], v[92:93], v[116:117], v[108:109]
	v_exp_f32_e32 v132, v132
	v_exp_f32_e32 v133, v133
	v_mul_f32_e32 v110, 0xbfb8aa3b, v108
	v_mul_f32_e32 v111, 0xbfb8aa3b, v109
	v_exp_f32_e32 v110, v110
	v_exp_f32_e32 v111, v111
	v_add_f32_e32 v132, 1.0, v132
	v_add_f32_e32 v133, 1.0, v133
	v_rcp_f32_e32 v132, v132
	v_rcp_f32_e32 v133, v133
	v_add_f32_e32 v110, 1.0, v110
	v_add_f32_e32 v111, 1.0, v111
	v_pk_fma_f32 v[98:99], v[142:143], v[98:99], v[146:147]
	v_rcp_f32_e32 v110, v110
	v_rcp_f32_e32 v111, v111
	v_pk_fma_f32 v[98:99], v[138:139], v[172:173], v[98:99]
	v_pk_fma_f32 v[162:163], v[140:141], v[162:163], v[144:145]
	v_pk_fma_f32 v[98:99], v[90:91], v[114:115], v[98:99]
	v_pk_mul_f32 v[96:97], v[96:97], v[132:133]
	v_pk_fma_f32 v[162:163], v[136:137], v[166:167], v[162:163]
	v_pk_mul_f32 v[96:97], v[98:99], v[96:97]
	v_pk_fma_f32 v[134:135], v[88:89], v[112:113], v[162:163]
	v_pk_mul_f32 v[108:109], v[108:109], v[110:111]
	v_cvt_pk_bf16_f32 v99, v96, v97
	v_pk_mul_f32 v[108:109], v[134:135], v[108:109]
	v_mul_u32_u24_e32 v96, s92, v197
	v_cvt_pk_bf16_f32 v98, v108, v109
	v_lshl_add_u32 v96, v192, 1, v96
	global_store_dwordx2 v96, v[98:99], s[34:35]
.LBB0_1167:
	s_or_b64 exec, exec, s[16:17]
	v_add_u32_e32 v168, s18, v227
	v_mov_b32_dpp v108, v92 row_shl:15 row_mask:0xf bank_mask:0xf bound_ctrl:1
	v_mov_b32_dpp v92, v92 row_shl:14 row_mask:0xf bank_mask:0xf bound_ctrl:1
	v_mov_b32_dpp v160, v88 row_shl:15 row_mask:0xf bank_mask:0xf bound_ctrl:1
	v_mov_b32_dpp v148, v88 row_shl:14 row_mask:0xf bank_mask:0xf bound_ctrl:1
	v_mov_b32_dpp v109, v93 row_shl:15 row_mask:0xf bank_mask:0xf bound_ctrl:1
	v_mov_b32_dpp v93, v93 row_shl:14 row_mask:0xf bank_mask:0xf bound_ctrl:1
	v_mov_b32_dpp v161, v89 row_shl:15 row_mask:0xf bank_mask:0xf bound_ctrl:1
	v_mov_b32_dpp v149, v89 row_shl:14 row_mask:0xf bank_mask:0xf bound_ctrl:1
	v_mov_b32_dpp v132, v94 row_shl:15 row_mask:0xf bank_mask:0xf bound_ctrl:1
	v_mov_b32_dpp v94, v94 row_shl:14 row_mask:0xf bank_mask:0xf bound_ctrl:1
	v_mov_b32_dpp v166, v90 row_shl:15 row_mask:0xf bank_mask:0xf bound_ctrl:1
	v_mov_b32_dpp v90, v90 row_shl:14 row_mask:0xf bank_mask:0xf bound_ctrl:1
	v_mov_b32_dpp v133, v95 row_shl:15 row_mask:0xf bank_mask:0xf bound_ctrl:1
	v_mov_b32_dpp v95, v95 row_shl:14 row_mask:0xf bank_mask:0xf bound_ctrl:1
	v_mov_b32_dpp v167, v91 row_shl:15 row_mask:0xf bank_mask:0xf bound_ctrl:1
	v_mov_b32_dpp v91, v91 row_shl:14 row_mask:0xf bank_mask:0xf bound_ctrl:1
	v_add_f32_dpp v98, v156, v108 row_shr:1 row_mask:0xf bank_mask:0xf bound_ctrl:1
	v_add_f32_dpp v92, v156, v92 row_shr:2 row_mask:0xf bank_mask:0xf bound_ctrl:1
	v_add_f32_dpp v150, v152, v160 row_shr:1 row_mask:0xf bank_mask:0xf bound_ctrl:1
	v_add_f32_dpp v134, v152, v148 row_shr:2 row_mask:0xf bank_mask:0xf bound_ctrl:1
	v_add_f32_dpp v99, v157, v109 row_shr:1 row_mask:0xf bank_mask:0xf bound_ctrl:1
	v_add_f32_dpp v93, v157, v93 row_shr:2 row_mask:0xf bank_mask:0xf bound_ctrl:1
	v_add_f32_dpp v151, v153, v161 row_shr:1 row_mask:0xf bank_mask:0xf bound_ctrl:1
	v_add_f32_dpp v135, v153, v149 row_shr:2 row_mask:0xf bank_mask:0xf bound_ctrl:1
	v_add_f32_dpp v110, v158, v132 row_shr:1 row_mask:0xf bank_mask:0xf bound_ctrl:1
	v_add_f32_dpp v88, v158, v94 row_shr:2 row_mask:0xf bank_mask:0xf bound_ctrl:1
	v_add_f32_dpp v164, v154, v166 row_shr:1 row_mask:0xf bank_mask:0xf bound_ctrl:1
	v_add_f32_dpp v90, v154, v90 row_shr:2 row_mask:0xf bank_mask:0xf bound_ctrl:1
	v_add_f32_dpp v111, v159, v133 row_shr:1 row_mask:0xf bank_mask:0xf bound_ctrl:1
	v_add_f32_dpp v89, v159, v95 row_shr:2 row_mask:0xf bank_mask:0xf bound_ctrl:1
	v_add_f32_dpp v165, v155, v167 row_shr:1 row_mask:0xf bank_mask:0xf bound_ctrl:1
	v_add_f32_dpp v91, v155, v91 row_shr:2 row_mask:0xf bank_mask:0xf bound_ctrl:1
	v_cmp_gt_i32_e64 s[22:23], s73, v168
	v_add_u32_e32 v168, s33, v168
	s_and_saveexec_b64 s[16:17], s[22:23]
	s_cbranch_execz .LBB0_1169
	s_waitcnt vmcnt(0)
	v_pk_fma_f32 v[88:89], v[126:127], v[88:89], v[130:131]
	v_pk_fma_f32 v[88:89], v[122:123], v[110:111], v[88:89]
	v_pk_fma_f32 v[92:93], v[124:125], v[92:93], v[128:129]
	v_pk_fma_f32 v[88:89], v[158:159], v[118:119], v[88:89]
	v_pk_fma_f32 v[92:93], v[120:121], v[98:99], v[92:93]
	v_mul_f32_e32 v96, 0xbfb8aa3b, v88
	v_mul_f32_e32 v97, 0xbfb8aa3b, v89
	v_pk_fma_f32 v[92:93], v[156:157], v[116:117], v[92:93]
	v_exp_f32_e32 v96, v96
	v_exp_f32_e32 v97, v97
	v_mul_f32_e32 v94, 0xbfb8aa3b, v92
	v_mul_f32_e32 v95, 0xbfb8aa3b, v93
	v_exp_f32_e32 v94, v94
	v_exp_f32_e32 v95, v95
	v_add_f32_e32 v96, 1.0, v96
	v_add_f32_e32 v97, 1.0, v97
	v_rcp_f32_e32 v96, v96
	v_rcp_f32_e32 v97, v97
	v_add_f32_e32 v94, 1.0, v94
	v_add_f32_e32 v95, 1.0, v95
	v_pk_fma_f32 v[90:91], v[142:143], v[90:91], v[146:147]
	v_rcp_f32_e32 v94, v94
	v_rcp_f32_e32 v95, v95
	v_pk_fma_f32 v[90:91], v[138:139], v[164:165], v[90:91]
	v_pk_fma_f32 v[134:135], v[140:141], v[134:135], v[144:145]
	v_pk_fma_f32 v[90:91], v[154:155], v[114:115], v[90:91]
	v_pk_mul_f32 v[88:89], v[88:89], v[96:97]
	v_pk_fma_f32 v[134:135], v[136:137], v[150:151], v[134:135]
	v_pk_mul_f32 v[88:89], v[90:91], v[88:89]
	v_pk_fma_f32 v[98:99], v[152:153], v[112:113], v[134:135]
	v_pk_mul_f32 v[92:93], v[92:93], v[94:95]
	v_cvt_pk_bf16_f32 v91, v88, v89
	v_pk_mul_f32 v[92:93], v[98:99], v[92:93]
	v_mul_u32_u24_e32 v88, s92, v168
	v_cvt_pk_bf16_f32 v90, v92, v93
	v_lshl_add_u32 v88, v192, 1, v88
	global_store_dwordx2 v88, v[90:91], s[34:35]

.LBB0_1175:
	s_or_b64 exec, exec, s[16:17]
	v_pk_mul_f32 v[86:87], v[86:87], v[198:199] op_sel_hi:[1,0]
	v_pk_mul_f32 v[84:85], v[84:85], v[198:199] op_sel_hi:[1,0]
	v_pk_mul_f32 v[82:83], v[82:83], v[198:199] op_sel_hi:[1,0]
	v_pk_mul_f32 v[80:81], v[80:81], v[198:199] op_sel_hi:[1,0]
	v_mov_b32_dpp v108, v84 row_shr:1 row_mask:0xf bank_mask:0xf bound_ctrl:1
	v_mov_b32_dpp v96, v84 row_shr:2 row_mask:0xf bank_mask:0xf bound_ctrl:1
	v_mov_b32_dpp v156, v80 row_shr:1 row_mask:0xf bank_mask:0xf bound_ctrl:1
	v_mov_b32_dpp v152, v80 row_shr:2 row_mask:0xf bank_mask:0xf bound_ctrl:1
	v_mov_b32_dpp v109, v85 row_shr:1 row_mask:0xf bank_mask:0xf bound_ctrl:1
	v_mov_b32_dpp v97, v85 row_shr:2 row_mask:0xf bank_mask:0xf bound_ctrl:1
	v_mov_b32_dpp v157, v81 row_shr:1 row_mask:0xf bank_mask:0xf bound_ctrl:1
	v_mov_b32_dpp v153, v81 row_shr:2 row_mask:0xf bank_mask:0xf bound_ctrl:1
	v_mov_b32_dpp v110, v86 row_shr:1 row_mask:0xf bank_mask:0xf bound_ctrl:1
	v_mov_b32_dpp v98, v86 row_shr:2 row_mask:0xf bank_mask:0xf bound_ctrl:1
	v_mov_b32_dpp v158, v82 row_shr:1 row_mask:0xf bank_mask:0xf bound_ctrl:1
	v_mov_b32_dpp v154, v82 row_shr:2 row_mask:0xf bank_mask:0xf bound_ctrl:1
	v_mov_b32_dpp v111, v87 row_shr:1 row_mask:0xf bank_mask:0xf bound_ctrl:1
	v_mov_b32_dpp v99, v87 row_shr:2 row_mask:0xf bank_mask:0xf bound_ctrl:1
	v_mov_b32_dpp v159, v83 row_shr:1 row_mask:0xf bank_mask:0xf bound_ctrl:1
	v_mov_b32_dpp v155, v83 row_shr:2 row_mask:0xf bank_mask:0xf bound_ctrl:1
	v_cmp_gt_i32_e64 s[24:25], s73, v241
	v_add_u32_e32 v160, s33, v241
	s_and_saveexec_b64 s[16:17], s[24:25]
	s_cbranch_execz .LBB0_1177
	s_waitcnt lgkmcnt(0)
	v_pk_add_f32 v[88:89], v[88:89], v[96:97]
	v_pk_add_f32 v[90:91], v[90:91], v[98:99]
	v_pk_add_f32 v[110:111], v[134:135], v[110:111]
	v_pk_add_f32 v[108:109], v[132:133], v[108:109]
	s_waitcnt vmcnt(0)
	v_pk_fma_f32 v[90:91], v[126:127], v[90:91], v[130:131]
	v_pk_fma_f32 v[88:89], v[124:125], v[88:89], v[128:129]
	v_pk_fma_f32 v[90:91], v[122:123], v[110:111], v[90:91]
	v_pk_fma_f32 v[88:89], v[120:121], v[108:109], v[88:89]
	v_pk_fma_f32 v[90:91], v[86:87], v[118:119], v[90:91]
	v_pk_fma_f32 v[88:89], v[84:85], v[116:117], v[88:89]
	v_mul_f32_e32 v98, 0xbfb8aa3b, v90
	v_mul_f32_e32 v96, 0xbfb8aa3b, v88
	v_mul_f32_e32 v97, 0xbfb8aa3b, v89
	v_mul_f32_e32 v99, 0xbfb8aa3b, v91
	v_exp_f32_e32 v96, v96
	v_exp_f32_e32 v97, v97
	v_exp_f32_e32 v98, v98
	v_exp_f32_e32 v99, v99
	v_add_f32_e32 v96, 1.0, v96
	v_add_f32_e32 v97, 1.0, v97
	v_add_f32_e32 v98, 1.0, v98
	v_add_f32_e32 v99, 1.0, v99
	v_rcp_f32_e32 v96, v96
	v_rcp_f32_e32 v97, v97
	v_rcp_f32_e32 v98, v98
	v_rcp_f32_e32 v99, v99
	v_pk_add_f32 v[92:93], v[92:93], v[152:153]
	v_pk_add_f32 v[94:95], v[94:95], v[154:155]
	v_pk_add_f32 v[150:151], v[150:151], v[158:159]
	v_pk_add_f32 v[148:149], v[148:149], v[156:157]
	v_pk_fma_f32 v[94:95], v[142:143], v[94:95], v[146:147]
	v_pk_fma_f32 v[92:93], v[140:141], v[92:93], v[144:145]
	v_pk_fma_f32 v[94:95], v[138:139], v[150:151], v[94:95]
	v_pk_fma_f32 v[92:93], v[136:137], v[148:149], v[92:93]
	v_pk_fma_f32 v[94:95], v[82:83], v[114:115], v[94:95]
	v_pk_fma_f32 v[92:93], v[80:81], v[112:113], v[92:93]
	v_pk_mul_f32 v[88:89], v[88:89], v[96:97]
	v_pk_mul_f32 v[90:91], v[90:91], v[98:99]
	v_pk_mul_f32 v[88:89], v[92:93], v[88:89]
	v_pk_mul_f32 v[90:91], v[94:95], v[90:91]
	v_cvt_pk_bf16_f32 v88, v88, v89
	v_cvt_pk_bf16_f32 v89, v90, v91
	v_mul_u32_u24_e32 v90, s92, v160
	v_lshl_add_u32 v90, v192, 1, v90
	global_store_dwordx2 v90, v[88:89], s[34:35]
.LBB0_1177:
	s_or_b64 exec, exec, s[16:17]
	v_pk_mul_f32 v[70:71], v[70:71], v[196:197] op_sel_hi:[1,0]
	v_pk_mul_f32 v[68:69], v[68:69], v[196:197] op_sel_hi:[1,0]
	v_pk_mul_f32 v[66:67], v[66:67], v[196:197] op_sel_hi:[1,0]
	v_pk_mul_f32 v[64:65], v[64:65], v[196:197] op_sel_hi:[1,0]
	s_waitcnt lgkmcnt(0)
	v_mov_b32_dpp v92, v84 row_shl:15 row_mask:0xf bank_mask:0xf bound_ctrl:1
	v_mov_b32_dpp v84, v84 row_shl:14 row_mask:0xf bank_mask:0xf bound_ctrl:1
	v_mov_b32_dpp v132, v80 row_shl:15 row_mask:0xf bank_mask:0xf bound_ctrl:1
	v_mov_b32_dpp v108, v80 row_shl:14 row_mask:0xf bank_mask:0xf bound_ctrl:1
	v_mov_b32_dpp v93, v85 row_shl:15 row_mask:0xf bank_mask:0xf bound_ctrl:1
	v_mov_b32_dpp v85, v85 row_shl:14 row_mask:0xf bank_mask:0xf bound_ctrl:1
	v_mov_b32_dpp v133, v81 row_shl:15 row_mask:0xf bank_mask:0xf bound_ctrl:1
	v_mov_b32_dpp v109, v81 row_shl:14 row_mask:0xf bank_mask:0xf bound_ctrl:1
	v_mov_b32_dpp v96, v86 row_shl:15 row_mask:0xf bank_mask:0xf bound_ctrl:1
	v_mov_b32_dpp v86, v86 row_shl:14 row_mask:0xf bank_mask:0xf bound_ctrl:1
	v_mov_b32_dpp v150, v82 row_shl:15 row_mask:0xf bank_mask:0xf bound_ctrl:1
	v_mov_b32_dpp v82, v82 row_shl:14 row_mask:0xf bank_mask:0xf bound_ctrl:1
	v_mov_b32_dpp v97, v87 row_shl:15 row_mask:0xf bank_mask:0xf bound_ctrl:1
	v_mov_b32_dpp v87, v87 row_shl:14 row_mask:0xf bank_mask:0xf bound_ctrl:1
	v_mov_b32_dpp v151, v83 row_shl:15 row_mask:0xf bank_mask:0xf bound_ctrl:1
	v_mov_b32_dpp v83, v83 row_shl:14 row_mask:0xf bank_mask:0xf bound_ctrl:1
	v_add_f32_dpp v90, v68, v92 row_shr:1 row_mask:0xf bank_mask:0xf bound_ctrl:1
	v_add_f32_dpp v84, v68, v84 row_shr:2 row_mask:0xf bank_mask:0xf bound_ctrl:1
	v_add_f32_dpp v110, v64, v132 row_shr:1 row_mask:0xf bank_mask:0xf bound_ctrl:1
	v_add_f32_dpp v98, v64, v108 row_shr:2 row_mask:0xf bank_mask:0xf bound_ctrl:1
	v_add_f32_dpp v91, v69, v93 row_shr:1 row_mask:0xf bank_mask:0xf bound_ctrl:1
	v_add_f32_dpp v85, v69, v85 row_shr:2 row_mask:0xf bank_mask:0xf bound_ctrl:1
	v_add_f32_dpp v111, v65, v133 row_shr:1 row_mask:0xf bank_mask:0xf bound_ctrl:1
	v_add_f32_dpp v99, v65, v109 row_shr:2 row_mask:0xf bank_mask:0xf bound_ctrl:1
	v_add_f32_dpp v94, v70, v96 row_shr:1 row_mask:0xf bank_mask:0xf bound_ctrl:1
	v_add_f32_dpp v80, v70, v86 row_shr:2 row_mask:0xf bank_mask:0xf bound_ctrl:1
	v_add_f32_dpp v148, v66, v150 row_shr:1 row_mask:0xf bank_mask:0xf bound_ctrl:1
	v_add_f32_dpp v82, v66, v82 row_shr:2 row_mask:0xf bank_mask:0xf bound_ctrl:1
	v_add_f32_dpp v95, v71, v97 row_shr:1 row_mask:0xf bank_mask:0xf bound_ctrl:1
	v_add_f32_dpp v81, v71, v87 row_shr:2 row_mask:0xf bank_mask:0xf bound_ctrl:1
	v_add_f32_dpp v149, v67, v151 row_shr:1 row_mask:0xf bank_mask:0xf bound_ctrl:1
	v_add_f32_dpp v83, v67, v83 row_shr:2 row_mask:0xf bank_mask:0xf bound_ctrl:1
	v_cmp_gt_i32_e64 s[18:19], s73, v240
	v_add_u32_e32 v152, s33, v240
	s_and_saveexec_b64 s[16:17], s[18:19]
	s_cbranch_execz .LBB0_1179
	s_waitcnt vmcnt(0)
	v_pk_fma_f32 v[80:81], v[126:127], v[80:81], v[130:131]
	v_pk_fma_f32 v[80:81], v[122:123], v[94:95], v[80:81]
	v_pk_fma_f32 v[84:85], v[124:125], v[84:85], v[128:129]
	v_pk_fma_f32 v[80:81], v[70:71], v[118:119], v[80:81]
	v_pk_fma_f32 v[84:85], v[120:121], v[90:91], v[84:85]
	v_mul_f32_e32 v88, 0xbfb8aa3b, v80
	v_mul_f32_e32 v89, 0xbfb8aa3b, v81
	v_pk_fma_f32 v[84:85], v[68:69], v[116:117], v[84:85]
	v_exp_f32_e32 v88, v88
	v_exp_f32_e32 v89, v89
	v_mul_f32_e32 v86, 0xbfb8aa3b, v84
	v_mul_f32_e32 v87, 0xbfb8aa3b, v85
	v_exp_f32_e32 v86, v86
	v_exp_f32_e32 v87, v87
	v_add_f32_e32 v88, 1.0, v88
	v_add_f32_e32 v89, 1.0, v89
	v_rcp_f32_e32 v88, v88
	v_rcp_f32_e32 v89, v89
	v_add_f32_e32 v86, 1.0, v86
	v_add_f32_e32 v87, 1.0, v87
	v_pk_fma_f32 v[82:83], v[142:143], v[82:83], v[146:147]
	v_rcp_f32_e32 v86, v86
	v_rcp_f32_e32 v87, v87
	v_pk_fma_f32 v[82:83], v[138:139], v[148:149], v[82:83]
	v_pk_fma_f32 v[98:99], v[140:141], v[98:99], v[144:145]
	v_pk_fma_f32 v[82:83], v[66:67], v[114:115], v[82:83]
	v_pk_mul_f32 v[80:81], v[80:81], v[88:89]
	v_pk_fma_f32 v[98:99], v[136:137], v[110:111], v[98:99]
	v_pk_mul_f32 v[80:81], v[82:83], v[80:81]
	v_pk_fma_f32 v[90:91], v[64:65], v[112:113], v[98:99]
	v_pk_mul_f32 v[84:85], v[84:85], v[86:87]
	v_cvt_pk_bf16_f32 v83, v80, v81
	v_pk_mul_f32 v[84:85], v[90:91], v[84:85]
	v_mul_u32_u24_e32 v80, s92, v152
	v_cvt_pk_bf16_f32 v82, v84, v85
	v_lshl_add_u32 v80, v192, 1, v80
	global_store_dwordx2 v80, v[82:83], s[34:35]
.LBB0_1179:
	s_or_b64 exec, exec, s[16:17]
	v_pk_mul_f32 v[62:63], v[62:63], v[194:195] op_sel_hi:[1,0]
	v_pk_mul_f32 v[60:61], v[60:61], v[194:195] op_sel_hi:[1,0]
	v_pk_mul_f32 v[58:59], v[58:59], v[194:195] op_sel_hi:[1,0]
	v_pk_mul_f32 v[56:57], v[56:57], v[194:195] op_sel_hi:[1,0]
	v_mov_b32_dpp v84, v68 row_shl:15 row_mask:0xf bank_mask:0xf bound_ctrl:1
	v_mov_b32_dpp v68, v68 row_shl:14 row_mask:0xf bank_mask:0xf bound_ctrl:1
	v_mov_b32_dpp v96, v64 row_shl:15 row_mask:0xf bank_mask:0xf bound_ctrl:1
	v_mov_b32_dpp v92, v64 row_shl:14 row_mask:0xf bank_mask:0xf bound_ctrl:1
	v_mov_b32_dpp v85, v69 row_shl:15 row_mask:0xf bank_mask:0xf bound_ctrl:1
	v_mov_b32_dpp v69, v69 row_shl:14 row_mask:0xf bank_mask:0xf bound_ctrl:1
	v_mov_b32_dpp v97, v65 row_shl:15 row_mask:0xf bank_mask:0xf bound_ctrl:1
	v_mov_b32_dpp v93, v65 row_shl:14 row_mask:0xf bank_mask:0xf bound_ctrl:1
	v_mov_b32_dpp v88, v70 row_shl:15 row_mask:0xf bank_mask:0xf bound_ctrl:1
	v_mov_b32_dpp v70, v70 row_shl:14 row_mask:0xf bank_mask:0xf bound_ctrl:1
	v_mov_b32_dpp v110, v66 row_shl:15 row_mask:0xf bank_mask:0xf bound_ctrl:1
	v_mov_b32_dpp v66, v66 row_shl:14 row_mask:0xf bank_mask:0xf bound_ctrl:1
	v_mov_b32_dpp v89, v71 row_shl:15 row_mask:0xf bank_mask:0xf bound_ctrl:1
	v_mov_b32_dpp v71, v71 row_shl:14 row_mask:0xf bank_mask:0xf bound_ctrl:1
	v_mov_b32_dpp v111, v67 row_shl:15 row_mask:0xf bank_mask:0xf bound_ctrl:1
	v_mov_b32_dpp v67, v67 row_shl:14 row_mask:0xf bank_mask:0xf bound_ctrl:1
	v_add_f32_dpp v82, v60, v84 row_shr:1 row_mask:0xf bank_mask:0xf bound_ctrl:1
	v_add_f32_dpp v68, v60, v68 row_shr:2 row_mask:0xf bank_mask:0xf bound_ctrl:1
	v_add_f32_dpp v94, v56, v96 row_shr:1 row_mask:0xf bank_mask:0xf bound_ctrl:1
	v_add_f32_dpp v90, v56, v92 row_shr:2 row_mask:0xf bank_mask:0xf bound_ctrl:1
	v_add_f32_dpp v83, v61, v85 row_shr:1 row_mask:0xf bank_mask:0xf bound_ctrl:1
	v_add_f32_dpp v69, v61, v69 row_shr:2 row_mask:0xf bank_mask:0xf bound_ctrl:1
	v_add_f32_dpp v95, v57, v97 row_shr:1 row_mask:0xf bank_mask:0xf bound_ctrl:1
	v_add_f32_dpp v91, v57, v93 row_shr:2 row_mask:0xf bank_mask:0xf bound_ctrl:1
	v_add_f32_dpp v86, v62, v88 row_shr:1 row_mask:0xf bank_mask:0xf bound_ctrl:1
	v_add_f32_dpp v64, v62, v70 row_shr:2 row_mask:0xf bank_mask:0xf bound_ctrl:1
	v_add_f32_dpp v108, v58, v110 row_shr:1 row_mask:0xf bank_mask:0xf bound_ctrl:1
	v_add_f32_dpp v66, v58, v66 row_shr:2 row_mask:0xf bank_mask:0xf bound_ctrl:1
	v_add_f32_dpp v87, v63, v89 row_shr:1 row_mask:0xf bank_mask:0xf bound_ctrl:1
	v_add_f32_dpp v65, v63, v71 row_shr:2 row_mask:0xf bank_mask:0xf bound_ctrl:1
	v_add_f32_dpp v109, v59, v111 row_shr:1 row_mask:0xf bank_mask:0xf bound_ctrl:1
	v_add_f32_dpp v67, v59, v67 row_shr:2 row_mask:0xf bank_mask:0xf bound_ctrl:1
	v_cmp_gt_i32_e64 s[16:17], s73, v205
	v_add_u32_e32 v132, s33, v205
	s_and_saveexec_b64 s[26:27], s[16:17]
	s_cbranch_execz .LBB0_1181
	s_waitcnt vmcnt(0)
	v_pk_fma_f32 v[64:65], v[126:127], v[64:65], v[130:131]
	v_pk_fma_f32 v[64:65], v[122:123], v[86:87], v[64:65]
	v_pk_fma_f32 v[68:69], v[124:125], v[68:69], v[128:129]
	v_pk_fma_f32 v[64:65], v[62:63], v[118:119], v[64:65]
	v_pk_fma_f32 v[68:69], v[120:121], v[82:83], v[68:69]
	v_mul_f32_e32 v80, 0xbfb8aa3b, v64
	v_mul_f32_e32 v81, 0xbfb8aa3b, v65
	v_pk_fma_f32 v[68:69], v[60:61], v[116:117], v[68:69]
	v_exp_f32_e32 v80, v80
	v_exp_f32_e32 v81, v81
	v_mul_f32_e32 v70, 0xbfb8aa3b, v68
	v_mul_f32_e32 v71, 0xbfb8aa3b, v69
	v_exp_f32_e32 v70, v70
	v_exp_f32_e32 v71, v71
	v_add_f32_e32 v80, 1.0, v80
	v_add_f32_e32 v81, 1.0, v81
	v_rcp_f32_e32 v80, v80
	v_rcp_f32_e32 v81, v81
	v_add_f32_e32 v70, 1.0, v70
	v_add_f32_e32 v71, 1.0, v71
	v_pk_fma_f32 v[66:67], v[142:143], v[66:67], v[146:147]
	v_rcp_f32_e32 v70, v70
	v_rcp_f32_e32 v71, v71
	v_pk_fma_f32 v[66:67], v[138:139], v[108:109], v[66:67]
	v_pk_fma_f32 v[90:91], v[140:141], v[90:91], v[144:145]
	v_pk_fma_f32 v[66:67], v[58:59], v[114:115], v[66:67]
	v_pk_mul_f32 v[64:65], v[64:65], v[80:81]
	v_pk_fma_f32 v[90:91], v[136:137], v[94:95], v[90:91]
	v_pk_mul_f32 v[64:65], v[66:67], v[64:65]
	v_pk_fma_f32 v[82:83], v[56:57], v[112:113], v[90:91]
	v_pk_mul_f32 v[68:69], v[68:69], v[70:71]
	v_cvt_pk_bf16_f32 v67, v64, v65
	v_pk_mul_f32 v[68:69], v[82:83], v[68:69]
	v_mul_u32_u24_e32 v64, s92, v132
	v_cvt_pk_bf16_f32 v66, v68, v69
	v_lshl_add_u32 v64, v192, 1, v64
	global_store_dwordx2 v64, v[66:67], s[34:35]
.LBB0_1181:
	s_or_b64 exec, exec, s[26:27]
	v_mov_b32_dpp v68, v60 row_shl:15 row_mask:0xf bank_mask:0xf bound_ctrl:1
	v_mov_b32_dpp v60, v60 row_shl:14 row_mask:0xf bank_mask:0xf bound_ctrl:1
	v_mov_b32_dpp v88, v56 row_shl:15 row_mask:0xf bank_mask:0xf bound_ctrl:1
	v_mov_b32_dpp v84, v56 row_shl:14 row_mask:0xf bank_mask:0xf bound_ctrl:1
	v_mov_b32_dpp v69, v61 row_shl:15 row_mask:0xf bank_mask:0xf bound_ctrl:1
	v_mov_b32_dpp v61, v61 row_shl:14 row_mask:0xf bank_mask:0xf bound_ctrl:1
	v_mov_b32_dpp v89, v57 row_shl:15 row_mask:0xf bank_mask:0xf bound_ctrl:1
	v_mov_b32_dpp v85, v57 row_shl:14 row_mask:0xf bank_mask:0xf bound_ctrl:1
	v_mov_b32_dpp v80, v62 row_shl:15 row_mask:0xf bank_mask:0xf bound_ctrl:1
	v_mov_b32_dpp v62, v62 row_shl:14 row_mask:0xf bank_mask:0xf bound_ctrl:1
	v_mov_b32_dpp v94, v58 row_shl:15 row_mask:0xf bank_mask:0xf bound_ctrl:1
	v_mov_b32_dpp v58, v58 row_shl:14 row_mask:0xf bank_mask:0xf bound_ctrl:1
	v_mov_b32_dpp v81, v63 row_shl:15 row_mask:0xf bank_mask:0xf bound_ctrl:1
	v_mov_b32_dpp v63, v63 row_shl:14 row_mask:0xf bank_mask:0xf bound_ctrl:1
	v_mov_b32_dpp v95, v59 row_shl:15 row_mask:0xf bank_mask:0xf bound_ctrl:1
	v_mov_b32_dpp v59, v59 row_shl:14 row_mask:0xf bank_mask:0xf bound_ctrl:1
	v_add_f32_dpp v66, v104, v68 row_shr:1 row_mask:0xf bank_mask:0xf bound_ctrl:1
	v_add_f32_dpp v60, v104, v60 row_shr:2 row_mask:0xf bank_mask:0xf bound_ctrl:1
	v_add_f32_dpp v86, v100, v88 row_shr:1 row_mask:0xf bank_mask:0xf bound_ctrl:1
	v_add_f32_dpp v82, v100, v84 row_shr:2 row_mask:0xf bank_mask:0xf bound_ctrl:1
	v_add_f32_dpp v67, v105, v69 row_shr:1 row_mask:0xf bank_mask:0xf bound_ctrl:1
	v_add_f32_dpp v61, v105, v61 row_shr:2 row_mask:0xf bank_mask:0xf bound_ctrl:1
	v_add_f32_dpp v87, v101, v89 row_shr:1 row_mask:0xf bank_mask:0xf bound_ctrl:1
	v_add_f32_dpp v83, v101, v85 row_shr:2 row_mask:0xf bank_mask:0xf bound_ctrl:1
	v_add_f32_dpp v70, v106, v80 row_shr:1 row_mask:0xf bank_mask:0xf bound_ctrl:1
	v_add_f32_dpp v56, v106, v62 row_shr:2 row_mask:0xf bank_mask:0xf bound_ctrl:1
	v_add_f32_dpp v92, v102, v94 row_shr:1 row_mask:0xf bank_mask:0xf bound_ctrl:1
	v_add_f32_dpp v58, v102, v58 row_shr:2 row_mask:0xf bank_mask:0xf bound_ctrl:1
	v_add_f32_dpp v71, v107, v81 row_shr:1 row_mask:0xf bank_mask:0xf bound_ctrl:1
	v_add_f32_dpp v57, v107, v63 row_shr:2 row_mask:0xf bank_mask:0xf bound_ctrl:1
	v_add_f32_dpp v93, v103, v95 row_shr:1 row_mask:0xf bank_mask:0xf bound_ctrl:1
	v_add_f32_dpp v59, v103, v59 row_shr:2 row_mask:0xf bank_mask:0xf bound_ctrl:1
	v_cmp_gt_i32_e64 s[26:27], s73, v203
	v_add_u32_e32 v133, s33, v203
	s_and_saveexec_b64 s[64:65], s[26:27]
	s_cbranch_execz .LBB0_1183
	s_waitcnt vmcnt(0)
	v_pk_fma_f32 v[56:57], v[126:127], v[56:57], v[130:131]
	v_pk_fma_f32 v[56:57], v[122:123], v[70:71], v[56:57]
	v_pk_fma_f32 v[60:61], v[124:125], v[60:61], v[128:129]
	v_pk_fma_f32 v[56:57], v[106:107], v[118:119], v[56:57]
	v_pk_fma_f32 v[60:61], v[120:121], v[66:67], v[60:61]
	v_mul_f32_e32 v64, 0xbfb8aa3b, v56
	v_mul_f32_e32 v65, 0xbfb8aa3b, v57
	v_pk_fma_f32 v[60:61], v[104:105], v[116:117], v[60:61]
	v_exp_f32_e32 v64, v64
	v_exp_f32_e32 v65, v65
	v_mul_f32_e32 v62, 0xbfb8aa3b, v60
	v_mul_f32_e32 v63, 0xbfb8aa3b, v61
	v_exp_f32_e32 v62, v62
	v_exp_f32_e32 v63, v63
	v_add_f32_e32 v64, 1.0, v64
	v_add_f32_e32 v65, 1.0, v65
	v_rcp_f32_e32 v64, v64
	v_rcp_f32_e32 v65, v65
	v_add_f32_e32 v62, 1.0, v62
	v_add_f32_e32 v63, 1.0, v63
	v_pk_fma_f32 v[58:59], v[142:143], v[58:59], v[146:147]
	v_rcp_f32_e32 v62, v62
	v_rcp_f32_e32 v63, v63
	v_pk_fma_f32 v[58:59], v[138:139], v[92:93], v[58:59]
	v_pk_fma_f32 v[82:83], v[140:141], v[82:83], v[144:145]
	v_pk_fma_f32 v[58:59], v[102:103], v[114:115], v[58:59]
	v_pk_mul_f32 v[56:57], v[56:57], v[64:65]
	v_pk_fma_f32 v[82:83], v[136:137], v[86:87], v[82:83]
	v_pk_mul_f32 v[56:57], v[58:59], v[56:57]
	v_pk_fma_f32 v[66:67], v[100:101], v[112:113], v[82:83]
	v_pk_mul_f32 v[60:61], v[60:61], v[62:63]
	v_cvt_pk_bf16_f32 v59, v56, v57
	v_pk_mul_f32 v[60:61], v[66:67], v[60:61]
	v_mul_u32_u24_e32 v56, s92, v133
	v_cvt_pk_bf16_f32 v58, v60, v61
	v_lshl_add_u32 v56, v192, 1, v56
	global_store_dwordx2 v56, v[58:59], s[34:35]

.LBB0_1191:
	v_mov_b32_e32 v205, v204
	v_mov_b32_e32 v104, v204
	v_mov_b32_e32 v105, v204
	v_pk_mul_f32 v[54:55], v[54:55], v[104:105]
	v_pk_mul_f32 v[52:53], v[52:53], v[204:205]
	v_pk_mul_f32 v[50:51], v[50:51], v[104:105]
	v_pk_mul_f32 v[48:49], v[48:49], v[204:205]
	s_waitcnt lgkmcnt(0)
	v_mov_b32_dpp v108, v52 row_shr:1 row_mask:0xf bank_mask:0xf bound_ctrl:1
	v_mov_b32_dpp v104, v52 row_shr:2 row_mask:0xf bank_mask:0xf bound_ctrl:1
	v_mov_b32_dpp v124, v48 row_shr:1 row_mask:0xf bank_mask:0xf bound_ctrl:1
	v_mov_b32_dpp v120, v48 row_shr:2 row_mask:0xf bank_mask:0xf bound_ctrl:1
	v_mov_b32_dpp v109, v53 row_shr:1 row_mask:0xf bank_mask:0xf bound_ctrl:1
	v_mov_b32_dpp v105, v53 row_shr:2 row_mask:0xf bank_mask:0xf bound_ctrl:1
	v_mov_b32_dpp v125, v49 row_shr:1 row_mask:0xf bank_mask:0xf bound_ctrl:1
	v_mov_b32_dpp v121, v49 row_shr:2 row_mask:0xf bank_mask:0xf bound_ctrl:1
	v_mov_b32_dpp v110, v54 row_shr:1 row_mask:0xf bank_mask:0xf bound_ctrl:1
	v_mov_b32_dpp v106, v54 row_shr:2 row_mask:0xf bank_mask:0xf bound_ctrl:1
	v_mov_b32_dpp v126, v50 row_shr:1 row_mask:0xf bank_mask:0xf bound_ctrl:1
	v_mov_b32_dpp v122, v50 row_shr:2 row_mask:0xf bank_mask:0xf bound_ctrl:1
	v_mov_b32_dpp v111, v55 row_shr:1 row_mask:0xf bank_mask:0xf bound_ctrl:1
	v_mov_b32_dpp v107, v55 row_shr:2 row_mask:0xf bank_mask:0xf bound_ctrl:1
	v_mov_b32_dpp v127, v51 row_shr:1 row_mask:0xf bank_mask:0xf bound_ctrl:1
	v_mov_b32_dpp v123, v51 row_shr:2 row_mask:0xf bank_mask:0xf bound_ctrl:1
	s_and_saveexec_b64 s[20:21], s[0:1]
	s_cbranch_execz .LBB0_1193
	v_pk_add_f32 v[96:97], v[96:97], v[104:105]
	v_pk_add_f32 v[98:99], v[98:99], v[106:107]
	v_pk_add_f32 v[110:111], v[114:115], v[110:111]
	v_pk_add_f32 v[108:109], v[112:113], v[108:109]
	v_pk_fma_f32 v[98:99], v[70:71], v[98:99], v[82:83]
	v_pk_fma_f32 v[96:97], v[68:69], v[96:97], v[80:81]
	v_pk_fma_f32 v[98:99], v[66:67], v[110:111], v[98:99]
	v_pk_fma_f32 v[96:97], v[64:65], v[108:109], v[96:97]
	v_pk_fma_f32 v[98:99], v[54:55], v[62:63], v[98:99]
	v_pk_fma_f32 v[96:97], v[52:53], v[60:61], v[96:97]
	v_mul_f32_e32 v106, 0xbfb8aa3b, v98
	v_mul_f32_e32 v104, 0xbfb8aa3b, v96
	v_mul_f32_e32 v105, 0xbfb8aa3b, v97
	v_mul_f32_e32 v107, 0xbfb8aa3b, v99
	v_exp_f32_e32 v104, v104
	v_exp_f32_e32 v105, v105
	v_exp_f32_e32 v106, v106
	v_exp_f32_e32 v107, v107
	v_add_f32_e32 v104, 1.0, v104
	v_add_f32_e32 v105, 1.0, v105
	v_add_f32_e32 v106, 1.0, v106
	v_add_f32_e32 v107, 1.0, v107
	v_rcp_f32_e32 v104, v104
	v_rcp_f32_e32 v105, v105
	v_rcp_f32_e32 v106, v106
	v_rcp_f32_e32 v107, v107
	v_pk_add_f32 v[100:101], v[100:101], v[120:121]
	v_pk_add_f32 v[102:103], v[102:103], v[122:123]
	v_pk_add_f32 v[118:119], v[118:119], v[126:127]
	v_pk_add_f32 v[116:117], v[116:117], v[124:125]
	v_pk_fma_f32 v[102:103], v[90:91], v[102:103], v[94:95]
	v_pk_fma_f32 v[100:101], v[88:89], v[100:101], v[92:93]
	v_pk_fma_f32 v[102:103], v[86:87], v[118:119], v[102:103]
	v_pk_fma_f32 v[100:101], v[84:85], v[116:117], v[100:101]
	v_pk_fma_f32 v[102:103], v[50:51], v[58:59], v[102:103]
	v_pk_fma_f32 v[100:101], v[48:49], v[56:57], v[100:101]
	v_pk_mul_f32 v[96:97], v[96:97], v[104:105]
	v_pk_mul_f32 v[98:99], v[98:99], v[106:107]
	v_pk_mul_f32 v[96:97], v[100:101], v[96:97]
	v_pk_mul_f32 v[98:99], v[102:103], v[98:99]
	v_cvt_pk_bf16_f32 v96, v96, v97
	v_cvt_pk_bf16_f32 v97, v98, v99
	v_mul_u32_u24_e32 v98, s92, v201
	v_lshl_add_u32 v98, v192, 1, v98
	global_store_dwordx2 v98, v[96:97], s[34:35] offset:8
.LBB0_1193:
	s_or_b64 exec, exec, s[20:21]
	v_mov_b32_e32 v203, v202
	v_mov_b32_e32 v96, v202
	v_mov_b32_e32 v97, v202
	v_pk_mul_f32 v[38:39], v[38:39], v[96:97]
	v_pk_mul_f32 v[36:37], v[36:37], v[202:203]
	v_pk_mul_f32 v[34:35], v[34:35], v[96:97]
	v_pk_mul_f32 v[32:33], v[32:33], v[202:203]
	v_mov_b32_dpp v100, v52 row_shl:15 row_mask:0xf bank_mask:0xf bound_ctrl:1
	v_mov_b32_dpp v52, v52 row_shl:14 row_mask:0xf bank_mask:0xf bound_ctrl:1
	v_mov_b32_dpp v112, v48 row_shl:15 row_mask:0xf bank_mask:0xf bound_ctrl:1
	v_mov_b32_dpp v108, v48 row_shl:14 row_mask:0xf bank_mask:0xf bound_ctrl:1
	v_mov_b32_dpp v101, v53 row_shl:15 row_mask:0xf bank_mask:0xf bound_ctrl:1
	v_mov_b32_dpp v53, v53 row_shl:14 row_mask:0xf bank_mask:0xf bound_ctrl:1
	v_mov_b32_dpp v113, v49 row_shl:15 row_mask:0xf bank_mask:0xf bound_ctrl:1
	v_mov_b32_dpp v109, v49 row_shl:14 row_mask:0xf bank_mask:0xf bound_ctrl:1
	v_mov_b32_dpp v104, v54 row_shl:15 row_mask:0xf bank_mask:0xf bound_ctrl:1
	v_mov_b32_dpp v54, v54 row_shl:14 row_mask:0xf bank_mask:0xf bound_ctrl:1
	v_mov_b32_dpp v118, v50 row_shl:15 row_mask:0xf bank_mask:0xf bound_ctrl:1
	v_mov_b32_dpp v50, v50 row_shl:14 row_mask:0xf bank_mask:0xf bound_ctrl:1
	v_mov_b32_dpp v105, v55 row_shl:15 row_mask:0xf bank_mask:0xf bound_ctrl:1
	v_mov_b32_dpp v55, v55 row_shl:14 row_mask:0xf bank_mask:0xf bound_ctrl:1
	v_mov_b32_dpp v119, v51 row_shl:15 row_mask:0xf bank_mask:0xf bound_ctrl:1
	v_mov_b32_dpp v51, v51 row_shl:14 row_mask:0xf bank_mask:0xf bound_ctrl:1
	v_add_f32_dpp v98, v36, v100 row_shr:1 row_mask:0xf bank_mask:0xf bound_ctrl:1
	v_add_f32_dpp v52, v36, v52 row_shr:2 row_mask:0xf bank_mask:0xf bound_ctrl:1
	v_add_f32_dpp v110, v32, v112 row_shr:1 row_mask:0xf bank_mask:0xf bound_ctrl:1
	v_add_f32_dpp v106, v32, v108 row_shr:2 row_mask:0xf bank_mask:0xf bound_ctrl:1
	v_add_f32_dpp v99, v37, v101 row_shr:1 row_mask:0xf bank_mask:0xf bound_ctrl:1
	v_add_f32_dpp v53, v37, v53 row_shr:2 row_mask:0xf bank_mask:0xf bound_ctrl:1
	v_add_f32_dpp v111, v33, v113 row_shr:1 row_mask:0xf bank_mask:0xf bound_ctrl:1
	v_add_f32_dpp v107, v33, v109 row_shr:2 row_mask:0xf bank_mask:0xf bound_ctrl:1
	v_add_f32_dpp v102, v38, v104 row_shr:1 row_mask:0xf bank_mask:0xf bound_ctrl:1
	v_add_f32_dpp v48, v38, v54 row_shr:2 row_mask:0xf bank_mask:0xf bound_ctrl:1
	v_add_f32_dpp v116, v34, v118 row_shr:1 row_mask:0xf bank_mask:0xf bound_ctrl:1
	v_add_f32_dpp v50, v34, v50 row_shr:2 row_mask:0xf bank_mask:0xf bound_ctrl:1
	v_add_f32_dpp v103, v39, v105 row_shr:1 row_mask:0xf bank_mask:0xf bound_ctrl:1
	v_add_f32_dpp v49, v39, v55 row_shr:2 row_mask:0xf bank_mask:0xf bound_ctrl:1
	v_add_f32_dpp v117, v35, v119 row_shr:1 row_mask:0xf bank_mask:0xf bound_ctrl:1
	v_add_f32_dpp v51, v35, v51 row_shr:2 row_mask:0xf bank_mask:0xf bound_ctrl:1
	s_and_saveexec_b64 s[0:1], s[12:13]
	s_cbranch_execz .LBB0_1195
	v_pk_fma_f32 v[48:49], v[70:71], v[48:49], v[82:83]
	v_pk_fma_f32 v[48:49], v[66:67], v[102:103], v[48:49]
	v_pk_fma_f32 v[52:53], v[68:69], v[52:53], v[80:81]
	v_pk_fma_f32 v[48:49], v[38:39], v[62:63], v[48:49]
	v_pk_fma_f32 v[52:53], v[64:65], v[98:99], v[52:53]
	v_mul_f32_e32 v96, 0xbfb8aa3b, v48
	v_mul_f32_e32 v97, 0xbfb8aa3b, v49
	v_pk_fma_f32 v[52:53], v[36:37], v[60:61], v[52:53]
	v_exp_f32_e32 v96, v96
	v_exp_f32_e32 v97, v97
	v_mul_f32_e32 v54, 0xbfb8aa3b, v52
	v_mul_f32_e32 v55, 0xbfb8aa3b, v53
	v_exp_f32_e32 v54, v54
	v_exp_f32_e32 v55, v55
	v_add_f32_e32 v96, 1.0, v96
	v_add_f32_e32 v97, 1.0, v97
	v_rcp_f32_e32 v96, v96
	v_rcp_f32_e32 v97, v97
	v_add_f32_e32 v54, 1.0, v54
	v_add_f32_e32 v55, 1.0, v55
	v_pk_fma_f32 v[50:51], v[90:91], v[50:51], v[94:95]
	v_rcp_f32_e32 v54, v54
	v_rcp_f32_e32 v55, v55
	v_pk_fma_f32 v[50:51], v[86:87], v[116:117], v[50:51]
	v_pk_fma_f32 v[106:107], v[88:89], v[106:107], v[92:93]
	v_pk_fma_f32 v[50:51], v[34:35], v[58:59], v[50:51]
	v_pk_mul_f32 v[48:49], v[48:49], v[96:97]
	v_pk_fma_f32 v[106:107], v[84:85], v[110:111], v[106:107]
	v_pk_mul_f32 v[48:49], v[50:51], v[48:49]
	v_pk_fma_f32 v[98:99], v[32:33], v[56:57], v[106:107]
	v_pk_mul_f32 v[52:53], v[52:53], v[54:55]
	v_cvt_pk_bf16_f32 v51, v48, v49
	v_pk_mul_f32 v[52:53], v[98:99], v[52:53]
	v_mul_u32_u24_e32 v48, s92, v199
	v_cvt_pk_bf16_f32 v50, v52, v53
	v_lshl_add_u32 v48, v192, 1, v48
	global_store_dwordx2 v48, v[50:51], s[34:35] offset:8
.LBB0_1195:
	s_or_b64 exec, exec, s[0:1]
	v_mov_b32_e32 v201, v200
	v_mov_b32_e32 v48, v200
	v_mov_b32_e32 v49, v200
	v_pk_mul_f32 v[30:31], v[30:31], v[48:49]
	v_pk_mul_f32 v[28:29], v[28:29], v[200:201]
	v_pk_mul_f32 v[26:27], v[26:27], v[48:49]
	v_pk_mul_f32 v[24:25], v[24:25], v[200:201]
	v_mov_b32_dpp v52, v36 row_shl:15 row_mask:0xf bank_mask:0xf bound_ctrl:1
	v_mov_b32_dpp v36, v36 row_shl:14 row_mask:0xf bank_mask:0xf bound_ctrl:1
	v_mov_b32_dpp v104, v32 row_shl:15 row_mask:0xf bank_mask:0xf bound_ctrl:1
	v_mov_b32_dpp v100, v32 row_shl:14 row_mask:0xf bank_mask:0xf bound_ctrl:1
	v_mov_b32_dpp v53, v37 row_shl:15 row_mask:0xf bank_mask:0xf bound_ctrl:1
	v_mov_b32_dpp v37, v37 row_shl:14 row_mask:0xf bank_mask:0xf bound_ctrl:1
	v_mov_b32_dpp v105, v33 row_shl:15 row_mask:0xf bank_mask:0xf bound_ctrl:1
	v_mov_b32_dpp v101, v33 row_shl:14 row_mask:0xf bank_mask:0xf bound_ctrl:1
	v_mov_b32_dpp v96, v38 row_shl:15 row_mask:0xf bank_mask:0xf bound_ctrl:1
	v_mov_b32_dpp v38, v38 row_shl:14 row_mask:0xf bank_mask:0xf bound_ctrl:1
	v_mov_b32_dpp v110, v34 row_shl:15 row_mask:0xf bank_mask:0xf bound_ctrl:1
	v_mov_b32_dpp v34, v34 row_shl:14 row_mask:0xf bank_mask:0xf bound_ctrl:1
	v_mov_b32_dpp v97, v39 row_shl:15 row_mask:0xf bank_mask:0xf bound_ctrl:1
	v_mov_b32_dpp v39, v39 row_shl:14 row_mask:0xf bank_mask:0xf bound_ctrl:1
	v_mov_b32_dpp v111, v35 row_shl:15 row_mask:0xf bank_mask:0xf bound_ctrl:1
	v_mov_b32_dpp v35, v35 row_shl:14 row_mask:0xf bank_mask:0xf bound_ctrl:1
	v_add_f32_dpp v50, v28, v52 row_shr:1 row_mask:0xf bank_mask:0xf bound_ctrl:1
	v_add_f32_dpp v36, v28, v36 row_shr:2 row_mask:0xf bank_mask:0xf bound_ctrl:1
	v_add_f32_dpp v102, v24, v104 row_shr:1 row_mask:0xf bank_mask:0xf bound_ctrl:1
	v_add_f32_dpp v98, v24, v100 row_shr:2 row_mask:0xf bank_mask:0xf bound_ctrl:1
	v_add_f32_dpp v51, v29, v53 row_shr:1 row_mask:0xf bank_mask:0xf bound_ctrl:1
	v_add_f32_dpp v37, v29, v37 row_shr:2 row_mask:0xf bank_mask:0xf bound_ctrl:1
	v_add_f32_dpp v103, v25, v105 row_shr:1 row_mask:0xf bank_mask:0xf bound_ctrl:1
	v_add_f32_dpp v99, v25, v101 row_shr:2 row_mask:0xf bank_mask:0xf bound_ctrl:1
	v_add_f32_dpp v54, v30, v96 row_shr:1 row_mask:0xf bank_mask:0xf bound_ctrl:1
	v_add_f32_dpp v32, v30, v38 row_shr:2 row_mask:0xf bank_mask:0xf bound_ctrl:1
	v_add_f32_dpp v108, v26, v110 row_shr:1 row_mask:0xf bank_mask:0xf bound_ctrl:1
	v_add_f32_dpp v34, v26, v34 row_shr:2 row_mask:0xf bank_mask:0xf bound_ctrl:1
	v_add_f32_dpp v55, v31, v97 row_shr:1 row_mask:0xf bank_mask:0xf bound_ctrl:1
	v_add_f32_dpp v33, v31, v39 row_shr:2 row_mask:0xf bank_mask:0xf bound_ctrl:1
	v_add_f32_dpp v109, v27, v111 row_shr:1 row_mask:0xf bank_mask:0xf bound_ctrl:1
	v_add_f32_dpp v35, v27, v35 row_shr:2 row_mask:0xf bank_mask:0xf bound_ctrl:1
	s_and_saveexec_b64 s[0:1], s[14:15]
	s_cbranch_execz .LBB0_1197
	v_pk_fma_f32 v[32:33], v[70:71], v[32:33], v[82:83]
	v_pk_fma_f32 v[32:33], v[66:67], v[54:55], v[32:33]
	v_pk_fma_f32 v[36:37], v[68:69], v[36:37], v[80:81]
	v_pk_fma_f32 v[32:33], v[30:31], v[62:63], v[32:33]
	v_pk_fma_f32 v[36:37], v[64:65], v[50:51], v[36:37]
	v_mul_f32_e32 v48, 0xbfb8aa3b, v32
	v_mul_f32_e32 v49, 0xbfb8aa3b, v33
	v_pk_fma_f32 v[36:37], v[28:29], v[60:61], v[36:37]
	v_exp_f32_e32 v48, v48
	v_exp_f32_e32 v49, v49
	v_mul_f32_e32 v38, 0xbfb8aa3b, v36
	v_mul_f32_e32 v39, 0xbfb8aa3b, v37
	v_exp_f32_e32 v38, v38
	v_exp_f32_e32 v39, v39
	v_add_f32_e32 v48, 1.0, v48
	v_add_f32_e32 v49, 1.0, v49
	v_rcp_f32_e32 v48, v48
	v_rcp_f32_e32 v49, v49
	v_add_f32_e32 v38, 1.0, v38
	v_add_f32_e32 v39, 1.0, v39
	v_pk_fma_f32 v[34:35], v[90:91], v[34:35], v[94:95]
	v_rcp_f32_e32 v38, v38
	v_rcp_f32_e32 v39, v39
	v_pk_fma_f32 v[34:35], v[86:87], v[108:109], v[34:35]
	v_pk_fma_f32 v[98:99], v[88:89], v[98:99], v[92:93]
	v_pk_fma_f32 v[34:35], v[26:27], v[58:59], v[34:35]
	v_pk_mul_f32 v[32:33], v[32:33], v[48:49]
	v_pk_fma_f32 v[98:99], v[84:85], v[102:103], v[98:99]
	v_pk_mul_f32 v[32:33], v[34:35], v[32:33]
	v_pk_fma_f32 v[50:51], v[24:25], v[56:57], v[98:99]
	v_pk_mul_f32 v[36:37], v[36:37], v[38:39]
	v_cvt_pk_bf16_f32 v35, v32, v33
	v_pk_mul_f32 v[36:37], v[50:51], v[36:37]
	v_mul_u32_u24_e32 v32, s92, v197
	v_cvt_pk_bf16_f32 v34, v36, v37
	v_lshl_add_u32 v32, v192, 1, v32
	global_store_dwordx2 v32, v[34:35], s[34:35] offset:8
.LBB0_1197:
	s_or_b64 exec, exec, s[0:1]
	v_mov_b32_dpp v36, v28 row_shl:15 row_mask:0xf bank_mask:0xf bound_ctrl:1
	v_mov_b32_dpp v28, v28 row_shl:14 row_mask:0xf bank_mask:0xf bound_ctrl:1
	v_mov_b32_dpp v96, v24 row_shl:15 row_mask:0xf bank_mask:0xf bound_ctrl:1
	v_mov_b32_dpp v52, v24 row_shl:14 row_mask:0xf bank_mask:0xf bound_ctrl:1
	v_mov_b32_dpp v37, v29 row_shl:15 row_mask:0xf bank_mask:0xf bound_ctrl:1
	v_mov_b32_dpp v29, v29 row_shl:14 row_mask:0xf bank_mask:0xf bound_ctrl:1
	v_mov_b32_dpp v97, v25 row_shl:15 row_mask:0xf bank_mask:0xf bound_ctrl:1
	v_mov_b32_dpp v53, v25 row_shl:14 row_mask:0xf bank_mask:0xf bound_ctrl:1
	v_mov_b32_dpp v48, v30 row_shl:15 row_mask:0xf bank_mask:0xf bound_ctrl:1
	v_mov_b32_dpp v30, v30 row_shl:14 row_mask:0xf bank_mask:0xf bound_ctrl:1
	v_mov_b32_dpp v102, v26 row_shl:15 row_mask:0xf bank_mask:0xf bound_ctrl:1
	v_mov_b32_dpp v26, v26 row_shl:14 row_mask:0xf bank_mask:0xf bound_ctrl:1
	v_mov_b32_dpp v49, v31 row_shl:15 row_mask:0xf bank_mask:0xf bound_ctrl:1
	v_mov_b32_dpp v31, v31 row_shl:14 row_mask:0xf bank_mask:0xf bound_ctrl:1
	v_mov_b32_dpp v103, v27 row_shl:15 row_mask:0xf bank_mask:0xf bound_ctrl:1
	v_mov_b32_dpp v27, v27 row_shl:14 row_mask:0xf bank_mask:0xf bound_ctrl:1
	v_add_f32_dpp v34, v76, v36 row_shr:1 row_mask:0xf bank_mask:0xf bound_ctrl:1
	v_add_f32_dpp v28, v76, v28 row_shr:2 row_mask:0xf bank_mask:0xf bound_ctrl:1
	v_add_f32_dpp v54, v72, v96 row_shr:1 row_mask:0xf bank_mask:0xf bound_ctrl:1
	v_add_f32_dpp v50, v72, v52 row_shr:2 row_mask:0xf bank_mask:0xf bound_ctrl:1
	v_add_f32_dpp v35, v77, v37 row_shr:1 row_mask:0xf bank_mask:0xf bound_ctrl:1
	v_add_f32_dpp v29, v77, v29 row_shr:2 row_mask:0xf bank_mask:0xf bound_ctrl:1
	v_add_f32_dpp v55, v73, v97 row_shr:1 row_mask:0xf bank_mask:0xf bound_ctrl:1
	v_add_f32_dpp v51, v73, v53 row_shr:2 row_mask:0xf bank_mask:0xf bound_ctrl:1
	v_add_f32_dpp v38, v78, v48 row_shr:1 row_mask:0xf bank_mask:0xf bound_ctrl:1
	v_add_f32_dpp v24, v78, v30 row_shr:2 row_mask:0xf bank_mask:0xf bound_ctrl:1
	v_add_f32_dpp v100, v74, v102 row_shr:1 row_mask:0xf bank_mask:0xf bound_ctrl:1
	v_add_f32_dpp v26, v74, v26 row_shr:2 row_mask:0xf bank_mask:0xf bound_ctrl:1
	v_add_f32_dpp v39, v79, v49 row_shr:1 row_mask:0xf bank_mask:0xf bound_ctrl:1
	v_add_f32_dpp v25, v79, v31 row_shr:2 row_mask:0xf bank_mask:0xf bound_ctrl:1
	v_add_f32_dpp v101, v75, v103 row_shr:1 row_mask:0xf bank_mask:0xf bound_ctrl:1
	v_add_f32_dpp v27, v75, v27 row_shr:2 row_mask:0xf bank_mask:0xf bound_ctrl:1
	s_and_saveexec_b64 s[0:1], s[22:23]
	s_cbranch_execz .LBB0_1199
	v_pk_fma_f32 v[24:25], v[70:71], v[24:25], v[82:83]
	v_pk_fma_f32 v[24:25], v[66:67], v[38:39], v[24:25]
	v_pk_fma_f32 v[28:29], v[68:69], v[28:29], v[80:81]
	v_pk_fma_f32 v[24:25], v[78:79], v[62:63], v[24:25]
	v_pk_fma_f32 v[28:29], v[64:65], v[34:35], v[28:29]
	v_mul_f32_e32 v32, 0xbfb8aa3b, v24
	v_mul_f32_e32 v33, 0xbfb8aa3b, v25
	v_pk_fma_f32 v[28:29], v[76:77], v[60:61], v[28:29]
	v_exp_f32_e32 v32, v32
	v_exp_f32_e32 v33, v33
	v_mul_f32_e32 v30, 0xbfb8aa3b, v28
	v_mul_f32_e32 v31, 0xbfb8aa3b, v29
	v_exp_f32_e32 v30, v30
	v_exp_f32_e32 v31, v31
	v_add_f32_e32 v32, 1.0, v32
	v_add_f32_e32 v33, 1.0, v33
	v_rcp_f32_e32 v32, v32
	v_rcp_f32_e32 v33, v33
	v_add_f32_e32 v30, 1.0, v30
	v_add_f32_e32 v31, 1.0, v31
	v_pk_fma_f32 v[26:27], v[90:91], v[26:27], v[94:95]
	v_rcp_f32_e32 v30, v30
	v_rcp_f32_e32 v31, v31
	v_pk_fma_f32 v[26:27], v[86:87], v[100:101], v[26:27]
	v_pk_fma_f32 v[50:51], v[88:89], v[50:51], v[92:93]
	v_pk_fma_f32 v[26:27], v[74:75], v[58:59], v[26:27]
	v_pk_mul_f32 v[24:25], v[24:25], v[32:33]
	v_pk_fma_f32 v[50:51], v[84:85], v[54:55], v[50:51]
	v_pk_mul_f32 v[24:25], v[26:27], v[24:25]
	v_pk_fma_f32 v[34:35], v[72:73], v[56:57], v[50:51]
	v_pk_mul_f32 v[28:29], v[28:29], v[30:31]
	v_cvt_pk_bf16_f32 v27, v24, v25
	v_pk_mul_f32 v[28:29], v[34:35], v[28:29]
	v_mul_u32_u24_e32 v24, s92, v168
	v_cvt_pk_bf16_f32 v26, v28, v29
	v_lshl_add_u32 v24, v192, 1, v24
	global_store_dwordx2 v24, v[26:27], s[34:35] offset:8

.LBB0_1205:
	s_or_b64 exec, exec, s[0:1]
	v_mov_b32_e32 v199, v198
	s_waitcnt lgkmcnt(0)
	v_mov_b32_e32 v32, v198
	v_mov_b32_e32 v33, v198
	v_pk_mul_f32 v[22:23], v[22:23], v[32:33]
	v_pk_mul_f32 v[20:21], v[20:21], v[198:199]
	v_pk_mul_f32 v[18:19], v[18:19], v[32:33]
	v_pk_mul_f32 v[16:17], v[16:17], v[198:199]
	v_mov_b32_dpp v36, v20 row_shr:1 row_mask:0xf bank_mask:0xf bound_ctrl:1
	v_mov_b32_dpp v32, v20 row_shr:2 row_mask:0xf bank_mask:0xf bound_ctrl:1
	v_mov_b32_dpp v76, v16 row_shr:1 row_mask:0xf bank_mask:0xf bound_ctrl:1
	v_mov_b32_dpp v72, v16 row_shr:2 row_mask:0xf bank_mask:0xf bound_ctrl:1
	v_mov_b32_dpp v37, v21 row_shr:1 row_mask:0xf bank_mask:0xf bound_ctrl:1
	v_mov_b32_dpp v33, v21 row_shr:2 row_mask:0xf bank_mask:0xf bound_ctrl:1
	v_mov_b32_dpp v77, v17 row_shr:1 row_mask:0xf bank_mask:0xf bound_ctrl:1
	v_mov_b32_dpp v73, v17 row_shr:2 row_mask:0xf bank_mask:0xf bound_ctrl:1
	v_mov_b32_dpp v38, v22 row_shr:1 row_mask:0xf bank_mask:0xf bound_ctrl:1
	v_mov_b32_dpp v34, v22 row_shr:2 row_mask:0xf bank_mask:0xf bound_ctrl:1
	v_mov_b32_dpp v78, v18 row_shr:1 row_mask:0xf bank_mask:0xf bound_ctrl:1
	v_mov_b32_dpp v74, v18 row_shr:2 row_mask:0xf bank_mask:0xf bound_ctrl:1
	v_mov_b32_dpp v39, v23 row_shr:1 row_mask:0xf bank_mask:0xf bound_ctrl:1
	v_mov_b32_dpp v35, v23 row_shr:2 row_mask:0xf bank_mask:0xf bound_ctrl:1
	v_mov_b32_dpp v79, v19 row_shr:1 row_mask:0xf bank_mask:0xf bound_ctrl:1
	v_mov_b32_dpp v75, v19 row_shr:2 row_mask:0xf bank_mask:0xf bound_ctrl:1
	s_and_saveexec_b64 s[0:1], s[24:25]
	s_cbranch_execz .LBB0_1207
	v_pk_add_f32 v[24:25], v[24:25], v[32:33]
	v_pk_add_f32 v[26:27], v[26:27], v[34:35]
	v_pk_add_f32 v[38:39], v[50:51], v[38:39]
	v_pk_add_f32 v[36:37], v[48:49], v[36:37]
	v_pk_fma_f32 v[26:27], v[70:71], v[26:27], v[82:83]
	v_pk_fma_f32 v[24:25], v[68:69], v[24:25], v[80:81]
	v_pk_fma_f32 v[26:27], v[66:67], v[38:39], v[26:27]
	v_pk_fma_f32 v[24:25], v[64:65], v[36:37], v[24:25]
	v_pk_fma_f32 v[26:27], v[22:23], v[62:63], v[26:27]
	v_pk_fma_f32 v[24:25], v[20:21], v[60:61], v[24:25]
	v_mul_f32_e32 v34, 0xbfb8aa3b, v26
	v_mul_f32_e32 v32, 0xbfb8aa3b, v24
	v_mul_f32_e32 v33, 0xbfb8aa3b, v25
	v_mul_f32_e32 v35, 0xbfb8aa3b, v27
	v_exp_f32_e32 v32, v32
	v_exp_f32_e32 v33, v33
	v_exp_f32_e32 v34, v34
	v_exp_f32_e32 v35, v35
	v_add_f32_e32 v32, 1.0, v32
	v_add_f32_e32 v33, 1.0, v33
	v_add_f32_e32 v34, 1.0, v34
	v_add_f32_e32 v35, 1.0, v35
	v_rcp_f32_e32 v32, v32
	v_rcp_f32_e32 v33, v33
	v_rcp_f32_e32 v34, v34
	v_rcp_f32_e32 v35, v35
	v_pk_add_f32 v[28:29], v[28:29], v[72:73]
	v_pk_add_f32 v[30:31], v[30:31], v[74:75]
	v_pk_add_f32 v[54:55], v[54:55], v[78:79]
	v_pk_add_f32 v[52:53], v[52:53], v[76:77]
	v_pk_fma_f32 v[30:31], v[90:91], v[30:31], v[94:95]
	v_pk_fma_f32 v[28:29], v[88:89], v[28:29], v[92:93]
	v_pk_fma_f32 v[30:31], v[86:87], v[54:55], v[30:31]
	v_pk_fma_f32 v[28:29], v[84:85], v[52:53], v[28:29]
	v_pk_fma_f32 v[30:31], v[18:19], v[58:59], v[30:31]
	v_pk_fma_f32 v[28:29], v[16:17], v[56:57], v[28:29]
	v_pk_mul_f32 v[24:25], v[24:25], v[32:33]
	v_pk_mul_f32 v[26:27], v[26:27], v[34:35]
	v_pk_mul_f32 v[24:25], v[28:29], v[24:25]
	v_pk_mul_f32 v[26:27], v[30:31], v[26:27]
	v_cvt_pk_bf16_f32 v24, v24, v25
	v_cvt_pk_bf16_f32 v25, v26, v27
	v_mul_u32_u24_e32 v26, s92, v160
	v_lshl_add_u32 v26, v192, 1, v26
	global_store_dwordx2 v26, v[24:25], s[34:35] offset:8
.LBB0_1207:
	s_or_b64 exec, exec, s[0:1]
	v_mov_b32_e32 v197, v196
	v_mov_b32_e32 v24, v196
	v_mov_b32_e32 v25, v196
	v_pk_mul_f32 v[14:15], v[14:15], v[24:25]
	v_pk_mul_f32 v[12:13], v[12:13], v[196:197]
	v_pk_mul_f32 v[10:11], v[10:11], v[24:25]
	v_pk_mul_f32 v[8:9], v[8:9], v[196:197]
	v_mov_b32_dpp v28, v20 row_shl:15 row_mask:0xf bank_mask:0xf bound_ctrl:1
	v_mov_b32_dpp v20, v20 row_shl:14 row_mask:0xf bank_mask:0xf bound_ctrl:1
	v_mov_b32_dpp v48, v16 row_shl:15 row_mask:0xf bank_mask:0xf bound_ctrl:1
	v_mov_b32_dpp v36, v16 row_shl:14 row_mask:0xf bank_mask:0xf bound_ctrl:1
	v_mov_b32_dpp v29, v21 row_shl:15 row_mask:0xf bank_mask:0xf bound_ctrl:1
	v_mov_b32_dpp v21, v21 row_shl:14 row_mask:0xf bank_mask:0xf bound_ctrl:1
	v_mov_b32_dpp v49, v17 row_shl:15 row_mask:0xf bank_mask:0xf bound_ctrl:1
	v_mov_b32_dpp v37, v17 row_shl:14 row_mask:0xf bank_mask:0xf bound_ctrl:1
	v_mov_b32_dpp v32, v22 row_shl:15 row_mask:0xf bank_mask:0xf bound_ctrl:1
	v_mov_b32_dpp v22, v22 row_shl:14 row_mask:0xf bank_mask:0xf bound_ctrl:1
	v_mov_b32_dpp v54, v18 row_shl:15 row_mask:0xf bank_mask:0xf bound_ctrl:1
	v_mov_b32_dpp v18, v18 row_shl:14 row_mask:0xf bank_mask:0xf bound_ctrl:1
	v_mov_b32_dpp v33, v23 row_shl:15 row_mask:0xf bank_mask:0xf bound_ctrl:1
	v_mov_b32_dpp v23, v23 row_shl:14 row_mask:0xf bank_mask:0xf bound_ctrl:1
	v_mov_b32_dpp v55, v19 row_shl:15 row_mask:0xf bank_mask:0xf bound_ctrl:1
	v_mov_b32_dpp v19, v19 row_shl:14 row_mask:0xf bank_mask:0xf bound_ctrl:1
	v_add_f32_dpp v26, v12, v28 row_shr:1 row_mask:0xf bank_mask:0xf bound_ctrl:1
	v_add_f32_dpp v20, v12, v20 row_shr:2 row_mask:0xf bank_mask:0xf bound_ctrl:1
	v_add_f32_dpp v38, v8, v48 row_shr:1 row_mask:0xf bank_mask:0xf bound_ctrl:1
	v_add_f32_dpp v34, v8, v36 row_shr:2 row_mask:0xf bank_mask:0xf bound_ctrl:1
	v_add_f32_dpp v27, v13, v29 row_shr:1 row_mask:0xf bank_mask:0xf bound_ctrl:1
	v_add_f32_dpp v21, v13, v21 row_shr:2 row_mask:0xf bank_mask:0xf bound_ctrl:1
	v_add_f32_dpp v39, v9, v49 row_shr:1 row_mask:0xf bank_mask:0xf bound_ctrl:1
	v_add_f32_dpp v35, v9, v37 row_shr:2 row_mask:0xf bank_mask:0xf bound_ctrl:1
	v_add_f32_dpp v30, v14, v32 row_shr:1 row_mask:0xf bank_mask:0xf bound_ctrl:1
	v_add_f32_dpp v16, v14, v22 row_shr:2 row_mask:0xf bank_mask:0xf bound_ctrl:1
	v_add_f32_dpp v52, v10, v54 row_shr:1 row_mask:0xf bank_mask:0xf bound_ctrl:1
	v_add_f32_dpp v18, v10, v18 row_shr:2 row_mask:0xf bank_mask:0xf bound_ctrl:1
	v_add_f32_dpp v31, v15, v33 row_shr:1 row_mask:0xf bank_mask:0xf bound_ctrl:1
	v_add_f32_dpp v17, v15, v23 row_shr:2 row_mask:0xf bank_mask:0xf bound_ctrl:1
	v_add_f32_dpp v53, v11, v55 row_shr:1 row_mask:0xf bank_mask:0xf bound_ctrl:1
	v_add_f32_dpp v19, v11, v19 row_shr:2 row_mask:0xf bank_mask:0xf bound_ctrl:1
	s_and_saveexec_b64 s[0:1], s[18:19]
	s_cbranch_execz .LBB0_1209
	v_pk_fma_f32 v[16:17], v[70:71], v[16:17], v[82:83]
	v_pk_fma_f32 v[16:17], v[66:67], v[30:31], v[16:17]
	v_pk_fma_f32 v[20:21], v[68:69], v[20:21], v[80:81]
	v_pk_fma_f32 v[16:17], v[14:15], v[62:63], v[16:17]
	v_pk_fma_f32 v[20:21], v[64:65], v[26:27], v[20:21]
	v_mul_f32_e32 v24, 0xbfb8aa3b, v16
	v_mul_f32_e32 v25, 0xbfb8aa3b, v17
	v_pk_fma_f32 v[20:21], v[12:13], v[60:61], v[20:21]
	v_exp_f32_e32 v24, v24
	v_exp_f32_e32 v25, v25
	v_mul_f32_e32 v22, 0xbfb8aa3b, v20
	v_mul_f32_e32 v23, 0xbfb8aa3b, v21
	v_exp_f32_e32 v22, v22
	v_exp_f32_e32 v23, v23
	v_add_f32_e32 v24, 1.0, v24
	v_add_f32_e32 v25, 1.0, v25
	v_rcp_f32_e32 v24, v24
	v_rcp_f32_e32 v25, v25
	v_add_f32_e32 v22, 1.0, v22
	v_add_f32_e32 v23, 1.0, v23
	v_pk_fma_f32 v[18:19], v[90:91], v[18:19], v[94:95]
	v_rcp_f32_e32 v22, v22
	v_rcp_f32_e32 v23, v23
	v_pk_fma_f32 v[18:19], v[86:87], v[52:53], v[18:19]
	v_pk_fma_f32 v[34:35], v[88:89], v[34:35], v[92:93]
	v_pk_fma_f32 v[18:19], v[10:11], v[58:59], v[18:19]
	v_pk_mul_f32 v[16:17], v[16:17], v[24:25]
	v_pk_fma_f32 v[34:35], v[84:85], v[38:39], v[34:35]
	v_pk_mul_f32 v[16:17], v[18:19], v[16:17]
	v_pk_fma_f32 v[26:27], v[8:9], v[56:57], v[34:35]
	v_pk_mul_f32 v[20:21], v[20:21], v[22:23]
	v_cvt_pk_bf16_f32 v19, v16, v17
	v_pk_mul_f32 v[20:21], v[26:27], v[20:21]
	v_mul_u32_u24_e32 v16, s92, v152
	v_cvt_pk_bf16_f32 v18, v20, v21
	v_lshl_add_u32 v16, v192, 1, v16
	global_store_dwordx2 v16, v[18:19], s[34:35] offset:8
.LBB0_1209:
	s_or_b64 exec, exec, s[0:1]
	v_mov_b32_e32 v195, v194
	v_mov_b32_e32 v16, v194
	v_mov_b32_e32 v17, v194
	v_pk_mul_f32 v[6:7], v[6:7], v[16:17]
	v_pk_mul_f32 v[4:5], v[4:5], v[194:195]
	v_pk_mul_f32 v[2:3], v[2:3], v[16:17]
	v_pk_mul_f32 v[0:1], v[0:1], v[194:195]
	v_mov_b32_dpp v20, v12 row_shl:15 row_mask:0xf bank_mask:0xf bound_ctrl:1
	v_mov_b32_dpp v12, v12 row_shl:14 row_mask:0xf bank_mask:0xf bound_ctrl:1
	v_mov_b32_dpp v32, v8 row_shl:15 row_mask:0xf bank_mask:0xf bound_ctrl:1
	v_mov_b32_dpp v28, v8 row_shl:14 row_mask:0xf bank_mask:0xf bound_ctrl:1
	v_mov_b32_dpp v21, v13 row_shl:15 row_mask:0xf bank_mask:0xf bound_ctrl:1
	v_mov_b32_dpp v13, v13 row_shl:14 row_mask:0xf bank_mask:0xf bound_ctrl:1
	v_mov_b32_dpp v33, v9 row_shl:15 row_mask:0xf bank_mask:0xf bound_ctrl:1
	v_mov_b32_dpp v29, v9 row_shl:14 row_mask:0xf bank_mask:0xf bound_ctrl:1
	v_mov_b32_dpp v24, v14 row_shl:15 row_mask:0xf bank_mask:0xf bound_ctrl:1
	v_mov_b32_dpp v14, v14 row_shl:14 row_mask:0xf bank_mask:0xf bound_ctrl:1
	v_mov_b32_dpp v38, v10 row_shl:15 row_mask:0xf bank_mask:0xf bound_ctrl:1
	v_mov_b32_dpp v10, v10 row_shl:14 row_mask:0xf bank_mask:0xf bound_ctrl:1
	v_mov_b32_dpp v25, v15 row_shl:15 row_mask:0xf bank_mask:0xf bound_ctrl:1
	v_mov_b32_dpp v15, v15 row_shl:14 row_mask:0xf bank_mask:0xf bound_ctrl:1
	v_mov_b32_dpp v39, v11 row_shl:15 row_mask:0xf bank_mask:0xf bound_ctrl:1
	v_mov_b32_dpp v11, v11 row_shl:14 row_mask:0xf bank_mask:0xf bound_ctrl:1
	v_add_f32_dpp v18, v4, v20 row_shr:1 row_mask:0xf bank_mask:0xf bound_ctrl:1
	v_add_f32_dpp v12, v4, v12 row_shr:2 row_mask:0xf bank_mask:0xf bound_ctrl:1
	v_add_f32_dpp v30, v0, v32 row_shr:1 row_mask:0xf bank_mask:0xf bound_ctrl:1
	v_add_f32_dpp v26, v0, v28 row_shr:2 row_mask:0xf bank_mask:0xf bound_ctrl:1
	v_add_f32_dpp v19, v5, v21 row_shr:1 row_mask:0xf bank_mask:0xf bound_ctrl:1
	v_add_f32_dpp v13, v5, v13 row_shr:2 row_mask:0xf bank_mask:0xf bound_ctrl:1
	v_add_f32_dpp v31, v1, v33 row_shr:1 row_mask:0xf bank_mask:0xf bound_ctrl:1
	v_add_f32_dpp v27, v1, v29 row_shr:2 row_mask:0xf bank_mask:0xf bound_ctrl:1
	v_add_f32_dpp v22, v6, v24 row_shr:1 row_mask:0xf bank_mask:0xf bound_ctrl:1
	v_add_f32_dpp v8, v6, v14 row_shr:2 row_mask:0xf bank_mask:0xf bound_ctrl:1
	v_add_f32_dpp v36, v2, v38 row_shr:1 row_mask:0xf bank_mask:0xf bound_ctrl:1
	v_add_f32_dpp v10, v2, v10 row_shr:2 row_mask:0xf bank_mask:0xf bound_ctrl:1
	v_add_f32_dpp v23, v7, v25 row_shr:1 row_mask:0xf bank_mask:0xf bound_ctrl:1
	v_add_f32_dpp v9, v7, v15 row_shr:2 row_mask:0xf bank_mask:0xf bound_ctrl:1
	v_add_f32_dpp v37, v3, v39 row_shr:1 row_mask:0xf bank_mask:0xf bound_ctrl:1
	v_add_f32_dpp v11, v3, v11 row_shr:2 row_mask:0xf bank_mask:0xf bound_ctrl:1
	s_and_saveexec_b64 s[0:1], s[16:17]
	s_cbranch_execz .LBB0_1211
	v_pk_fma_f32 v[8:9], v[70:71], v[8:9], v[82:83]
	v_pk_fma_f32 v[8:9], v[66:67], v[22:23], v[8:9]
	v_pk_fma_f32 v[12:13], v[68:69], v[12:13], v[80:81]
	v_pk_fma_f32 v[8:9], v[6:7], v[62:63], v[8:9]
	v_pk_fma_f32 v[12:13], v[64:65], v[18:19], v[12:13]
	v_mul_f32_e32 v16, 0xbfb8aa3b, v8
	v_mul_f32_e32 v17, 0xbfb8aa3b, v9
	v_pk_fma_f32 v[12:13], v[4:5], v[60:61], v[12:13]
	v_exp_f32_e32 v16, v16
	v_exp_f32_e32 v17, v17
	v_mul_f32_e32 v14, 0xbfb8aa3b, v12
	v_mul_f32_e32 v15, 0xbfb8aa3b, v13
	v_exp_f32_e32 v14, v14
	v_exp_f32_e32 v15, v15
	v_add_f32_e32 v16, 1.0, v16
	v_add_f32_e32 v17, 1.0, v17
	v_rcp_f32_e32 v16, v16
	v_rcp_f32_e32 v17, v17
	v_add_f32_e32 v14, 1.0, v14
	v_add_f32_e32 v15, 1.0, v15
	v_pk_fma_f32 v[10:11], v[90:91], v[10:11], v[94:95]
	v_rcp_f32_e32 v14, v14
	v_rcp_f32_e32 v15, v15
	v_pk_fma_f32 v[10:11], v[86:87], v[36:37], v[10:11]
	v_pk_fma_f32 v[26:27], v[88:89], v[26:27], v[92:93]
	v_pk_fma_f32 v[10:11], v[2:3], v[58:59], v[10:11]
	v_pk_mul_f32 v[8:9], v[8:9], v[16:17]
	v_pk_fma_f32 v[26:27], v[84:85], v[30:31], v[26:27]
	v_pk_mul_f32 v[8:9], v[10:11], v[8:9]
	v_pk_fma_f32 v[18:19], v[0:1], v[56:57], v[26:27]
	v_pk_mul_f32 v[12:13], v[12:13], v[14:15]
	v_cvt_pk_bf16_f32 v11, v8, v9
	v_pk_mul_f32 v[12:13], v[18:19], v[12:13]
	v_mul_u32_u24_e32 v8, s92, v132
	v_cvt_pk_bf16_f32 v10, v12, v13
	v_lshl_add_u32 v8, v192, 1, v8
	global_store_dwordx2 v8, v[10:11], s[34:35] offset:8
.LBB0_1211:
	s_or_b64 exec, exec, s[0:1]
	v_mov_b32_dpp v12, v4 row_shl:15 row_mask:0xf bank_mask:0xf bound_ctrl:1
	v_mov_b32_dpp v4, v4 row_shl:14 row_mask:0xf bank_mask:0xf bound_ctrl:1
	v_mov_b32_dpp v24, v0 row_shl:15 row_mask:0xf bank_mask:0xf bound_ctrl:1
	v_mov_b32_dpp v20, v0 row_shl:14 row_mask:0xf bank_mask:0xf bound_ctrl:1
	v_mov_b32_dpp v13, v5 row_shl:15 row_mask:0xf bank_mask:0xf bound_ctrl:1
	v_mov_b32_dpp v5, v5 row_shl:14 row_mask:0xf bank_mask:0xf bound_ctrl:1
	v_mov_b32_dpp v25, v1 row_shl:15 row_mask:0xf bank_mask:0xf bound_ctrl:1
	v_mov_b32_dpp v21, v1 row_shl:14 row_mask:0xf bank_mask:0xf bound_ctrl:1
	v_mov_b32_dpp v16, v6 row_shl:15 row_mask:0xf bank_mask:0xf bound_ctrl:1
	v_mov_b32_dpp v6, v6 row_shl:14 row_mask:0xf bank_mask:0xf bound_ctrl:1
	v_mov_b32_dpp v30, v2 row_shl:15 row_mask:0xf bank_mask:0xf bound_ctrl:1
	v_mov_b32_dpp v2, v2 row_shl:14 row_mask:0xf bank_mask:0xf bound_ctrl:1
	v_mov_b32_dpp v17, v7 row_shl:15 row_mask:0xf bank_mask:0xf bound_ctrl:1
	v_mov_b32_dpp v7, v7 row_shl:14 row_mask:0xf bank_mask:0xf bound_ctrl:1
	v_mov_b32_dpp v31, v3 row_shl:15 row_mask:0xf bank_mask:0xf bound_ctrl:1
	v_mov_b32_dpp v3, v3 row_shl:14 row_mask:0xf bank_mask:0xf bound_ctrl:1
	v_add_f32_dpp v10, v44, v12 row_shr:1 row_mask:0xf bank_mask:0xf bound_ctrl:1
	v_add_f32_dpp v4, v44, v4 row_shr:2 row_mask:0xf bank_mask:0xf bound_ctrl:1
	v_add_f32_dpp v22, v40, v24 row_shr:1 row_mask:0xf bank_mask:0xf bound_ctrl:1
	v_add_f32_dpp v18, v40, v20 row_shr:2 row_mask:0xf bank_mask:0xf bound_ctrl:1
	v_add_f32_dpp v11, v45, v13 row_shr:1 row_mask:0xf bank_mask:0xf bound_ctrl:1
	v_add_f32_dpp v5, v45, v5 row_shr:2 row_mask:0xf bank_mask:0xf bound_ctrl:1
	v_add_f32_dpp v23, v41, v25 row_shr:1 row_mask:0xf bank_mask:0xf bound_ctrl:1
	v_add_f32_dpp v19, v41, v21 row_shr:2 row_mask:0xf bank_mask:0xf bound_ctrl:1
	v_add_f32_dpp v14, v46, v16 row_shr:1 row_mask:0xf bank_mask:0xf bound_ctrl:1
	v_add_f32_dpp v0, v46, v6 row_shr:2 row_mask:0xf bank_mask:0xf bound_ctrl:1
	v_add_f32_dpp v28, v42, v30 row_shr:1 row_mask:0xf bank_mask:0xf bound_ctrl:1
	v_add_f32_dpp v2, v42, v2 row_shr:2 row_mask:0xf bank_mask:0xf bound_ctrl:1
	v_add_f32_dpp v15, v47, v17 row_shr:1 row_mask:0xf bank_mask:0xf bound_ctrl:1
	v_add_f32_dpp v1, v47, v7 row_shr:2 row_mask:0xf bank_mask:0xf bound_ctrl:1
	v_add_f32_dpp v29, v43, v31 row_shr:1 row_mask:0xf bank_mask:0xf bound_ctrl:1
	v_add_f32_dpp v3, v43, v3 row_shr:2 row_mask:0xf bank_mask:0xf bound_ctrl:1
	s_and_saveexec_b64 s[0:1], s[26:27]
	s_cbranch_execz .LBB0_1213
	v_pk_fma_f32 v[0:1], v[70:71], v[0:1], v[82:83]
	v_pk_fma_f32 v[0:1], v[66:67], v[14:15], v[0:1]
	v_pk_fma_f32 v[4:5], v[68:69], v[4:5], v[80:81]
	v_pk_fma_f32 v[0:1], v[46:47], v[62:63], v[0:1]
	v_pk_fma_f32 v[4:5], v[64:65], v[10:11], v[4:5]
	v_mul_f32_e32 v8, 0xbfb8aa3b, v0
	v_mul_f32_e32 v9, 0xbfb8aa3b, v1
	v_pk_fma_f32 v[4:5], v[44:45], v[60:61], v[4:5]
	v_exp_f32_e32 v8, v8
	v_exp_f32_e32 v9, v9
	v_mul_f32_e32 v6, 0xbfb8aa3b, v4
	v_mul_f32_e32 v7, 0xbfb8aa3b, v5
	v_exp_f32_e32 v6, v6
	v_exp_f32_e32 v7, v7
	v_add_f32_e32 v8, 1.0, v8
	v_add_f32_e32 v9, 1.0, v9
	v_rcp_f32_e32 v8, v8
	v_rcp_f32_e32 v9, v9
	v_add_f32_e32 v6, 1.0, v6
	v_add_f32_e32 v7, 1.0, v7
	v_pk_fma_f32 v[2:3], v[90:91], v[2:3], v[94:95]
	v_rcp_f32_e32 v6, v6
	v_rcp_f32_e32 v7, v7
	v_pk_fma_f32 v[2:3], v[86:87], v[28:29], v[2:3]
	v_pk_fma_f32 v[18:19], v[88:89], v[18:19], v[92:93]
	v_pk_fma_f32 v[2:3], v[42:43], v[58:59], v[2:3]
	v_pk_mul_f32 v[0:1], v[0:1], v[8:9]
	v_pk_fma_f32 v[18:19], v[84:85], v[22:23], v[18:19]
	v_pk_mul_f32 v[0:1], v[2:3], v[0:1]
	v_pk_fma_f32 v[10:11], v[40:41], v[56:57], v[18:19]
	v_pk_mul_f32 v[4:5], v[4:5], v[6:7]
	v_cvt_pk_bf16_f32 v3, v0, v1
	v_pk_mul_f32 v[4:5], v[10:11], v[4:5]
	v_mul_u32_u24_e32 v0, s92, v133
	v_cvt_pk_bf16_f32 v2, v4, v5
	v_lshl_add_u32 v0, v192, 1, v0
	global_store_dwordx2 v0, v[2:3], s[34:35] offset:8

.LBB0_2264:
	v_pk_mul_f32 v[150:151], v[150:151], v[202:203] op_sel_hi:[1,0]
	v_pk_mul_f32 v[148:149], v[148:149], v[202:203] op_sel_hi:[1,0]
	v_pk_mul_f32 v[146:147], v[146:147], v[202:203] op_sel_hi:[1,0]
	v_pk_mul_f32 v[144:145], v[144:145], v[202:203] op_sel_hi:[1,0]
	v_cmp_gt_i32_e32 vcc, s79, v195
	v_mov_b32_dpp v172, v148 row_shr:1 row_mask:0xf bank_mask:0xf bound_ctrl:1
	v_mov_b32_dpp v168, v148 row_shr:2 row_mask:0xf bank_mask:0xf bound_ctrl:1
	v_mov_b32_dpp v216, v144 row_shr:1 row_mask:0xf bank_mask:0xf bound_ctrl:1
	v_mov_b32_dpp v212, v144 row_shr:2 row_mask:0xf bank_mask:0xf bound_ctrl:1
	v_mov_b32_dpp v173, v149 row_shr:1 row_mask:0xf bank_mask:0xf bound_ctrl:1
	v_mov_b32_dpp v169, v149 row_shr:2 row_mask:0xf bank_mask:0xf bound_ctrl:1
	v_mov_b32_dpp v217, v145 row_shr:1 row_mask:0xf bank_mask:0xf bound_ctrl:1
	v_mov_b32_dpp v213, v145 row_shr:2 row_mask:0xf bank_mask:0xf bound_ctrl:1
	v_mov_b32_dpp v174, v150 row_shr:1 row_mask:0xf bank_mask:0xf bound_ctrl:1
	v_mov_b32_dpp v170, v150 row_shr:2 row_mask:0xf bank_mask:0xf bound_ctrl:1
	v_mov_b32_dpp v218, v146 row_shr:1 row_mask:0xf bank_mask:0xf bound_ctrl:1
	v_mov_b32_dpp v214, v146 row_shr:2 row_mask:0xf bank_mask:0xf bound_ctrl:1
	v_mov_b32_dpp v175, v151 row_shr:1 row_mask:0xf bank_mask:0xf bound_ctrl:1
	v_mov_b32_dpp v171, v151 row_shr:2 row_mask:0xf bank_mask:0xf bound_ctrl:1
	v_mov_b32_dpp v219, v147 row_shr:1 row_mask:0xf bank_mask:0xf bound_ctrl:1
	v_mov_b32_dpp v215, v147 row_shr:2 row_mask:0xf bank_mask:0xf bound_ctrl:1
	s_and_b64 s[0:1], s[10:11], vcc
	v_add_u32_e32 v199, s33, v195
	s_and_saveexec_b64 s[12:13], s[0:1]
	s_cbranch_execz .LBB0_2266
	s_waitcnt lgkmcnt(0)
	v_pk_add_f32 v[160:161], v[160:161], v[168:169]
	v_pk_add_f32 v[162:163], v[162:163], v[170:171]
	v_pk_add_f32 v[174:175], v[206:207], v[174:175]
	v_pk_add_f32 v[172:173], v[204:205], v[172:173]
	s_waitcnt vmcnt(0)
	v_pk_fma_f32 v[162:163], v[126:127], v[162:163], v[130:131]
	v_pk_fma_f32 v[160:161], v[124:125], v[160:161], v[128:129]
	v_pk_fma_f32 v[162:163], v[122:123], v[174:175], v[162:163]
	v_pk_fma_f32 v[160:161], v[120:121], v[172:173], v[160:161]
	v_pk_fma_f32 v[162:163], v[150:151], v[118:119], v[162:163]
	v_pk_fma_f32 v[160:161], v[148:149], v[116:117], v[160:161]
	v_mul_f32_e32 v170, 0xbfb8aa3b, v162
	v_mul_f32_e32 v168, 0xbfb8aa3b, v160
	v_mul_f32_e32 v169, 0xbfb8aa3b, v161
	v_mul_f32_e32 v171, 0xbfb8aa3b, v163
	v_exp_f32_e32 v168, v168
	v_exp_f32_e32 v169, v169
	v_exp_f32_e32 v170, v170
	v_exp_f32_e32 v171, v171
	v_add_f32_e32 v168, 1.0, v168
	v_add_f32_e32 v169, 1.0, v169
	v_add_f32_e32 v170, 1.0, v170
	v_add_f32_e32 v171, 1.0, v171
	v_rcp_f32_e32 v168, v168
	v_rcp_f32_e32 v169, v169
	v_rcp_f32_e32 v170, v170
	v_rcp_f32_e32 v171, v171
	v_pk_add_f32 v[164:165], v[164:165], v[212:213]
	v_pk_add_f32 v[166:167], v[166:167], v[214:215]
	v_pk_add_f32 v[210:211], v[210:211], v[218:219]
	v_pk_add_f32 v[208:209], v[208:209], v[216:217]
	v_pk_fma_f32 v[166:167], v[138:139], v[166:167], v[142:143]
	v_pk_fma_f32 v[164:165], v[136:137], v[164:165], v[140:141]
	v_pk_fma_f32 v[166:167], v[134:135], v[210:211], v[166:167]
	v_pk_fma_f32 v[164:165], v[132:133], v[208:209], v[164:165]
	v_pk_fma_f32 v[166:167], v[146:147], v[114:115], v[166:167]
	v_pk_fma_f32 v[164:165], v[144:145], v[112:113], v[164:165]
	v_pk_mul_f32 v[160:161], v[160:161], v[168:169]
	v_pk_mul_f32 v[162:163], v[162:163], v[170:171]
	v_pk_mul_f32 v[160:161], v[164:165], v[160:161]
	v_pk_mul_f32 v[162:163], v[166:167], v[162:163]
	v_cvt_pk_bf16_f32 v160, v160, v161
	v_cvt_pk_bf16_f32 v161, v162, v163
	v_mul_u32_u24_e32 v162, s96, v199
	v_lshl_add_u32 v162, v190, 1, v162
	global_store_dwordx2 v162, v[160:161], s[36:37]
.LBB0_2266:
	s_or_b64 exec, exec, s[12:13]
	v_pk_mul_f32 v[110:111], v[110:111], v[200:201] op_sel_hi:[1,0]
	v_pk_mul_f32 v[108:109], v[108:109], v[200:201] op_sel_hi:[1,0]
	v_pk_mul_f32 v[106:107], v[106:107], v[200:201] op_sel_hi:[1,0]
	v_pk_mul_f32 v[104:105], v[104:105], v[200:201] op_sel_hi:[1,0]
	v_add_u32_e32 v195, s18, v225
	s_waitcnt lgkmcnt(0)
	v_mov_b32_dpp v164, v148 row_shl:15 row_mask:0xf bank_mask:0xf bound_ctrl:1
	v_mov_b32_dpp v148, v148 row_shl:14 row_mask:0xf bank_mask:0xf bound_ctrl:1
	v_mov_b32_dpp v204, v144 row_shl:15 row_mask:0xf bank_mask:0xf bound_ctrl:1
	v_mov_b32_dpp v172, v144 row_shl:14 row_mask:0xf bank_mask:0xf bound_ctrl:1
	v_mov_b32_dpp v165, v149 row_shl:15 row_mask:0xf bank_mask:0xf bound_ctrl:1
	v_mov_b32_dpp v149, v149 row_shl:14 row_mask:0xf bank_mask:0xf bound_ctrl:1
	v_mov_b32_dpp v205, v145 row_shl:15 row_mask:0xf bank_mask:0xf bound_ctrl:1
	v_mov_b32_dpp v173, v145 row_shl:14 row_mask:0xf bank_mask:0xf bound_ctrl:1
	v_mov_b32_dpp v168, v150 row_shl:15 row_mask:0xf bank_mask:0xf bound_ctrl:1
	v_mov_b32_dpp v150, v150 row_shl:14 row_mask:0xf bank_mask:0xf bound_ctrl:1
	v_mov_b32_dpp v210, v146 row_shl:15 row_mask:0xf bank_mask:0xf bound_ctrl:1
	v_mov_b32_dpp v146, v146 row_shl:14 row_mask:0xf bank_mask:0xf bound_ctrl:1
	v_mov_b32_dpp v169, v151 row_shl:15 row_mask:0xf bank_mask:0xf bound_ctrl:1
	v_mov_b32_dpp v151, v151 row_shl:14 row_mask:0xf bank_mask:0xf bound_ctrl:1
	v_mov_b32_dpp v211, v147 row_shl:15 row_mask:0xf bank_mask:0xf bound_ctrl:1
	v_mov_b32_dpp v147, v147 row_shl:14 row_mask:0xf bank_mask:0xf bound_ctrl:1
	v_add_f32_dpp v162, v108, v164 row_shr:1 row_mask:0xf bank_mask:0xf bound_ctrl:1
	v_add_f32_dpp v148, v108, v148 row_shr:2 row_mask:0xf bank_mask:0xf bound_ctrl:1
	v_add_f32_dpp v174, v104, v204 row_shr:1 row_mask:0xf bank_mask:0xf bound_ctrl:1
	v_add_f32_dpp v170, v104, v172 row_shr:2 row_mask:0xf bank_mask:0xf bound_ctrl:1
	v_add_f32_dpp v163, v109, v165 row_shr:1 row_mask:0xf bank_mask:0xf bound_ctrl:1
	v_add_f32_dpp v149, v109, v149 row_shr:2 row_mask:0xf bank_mask:0xf bound_ctrl:1
	v_add_f32_dpp v175, v105, v205 row_shr:1 row_mask:0xf bank_mask:0xf bound_ctrl:1
	v_add_f32_dpp v171, v105, v173 row_shr:2 row_mask:0xf bank_mask:0xf bound_ctrl:1
	v_add_f32_dpp v166, v110, v168 row_shr:1 row_mask:0xf bank_mask:0xf bound_ctrl:1
	v_add_f32_dpp v144, v110, v150 row_shr:2 row_mask:0xf bank_mask:0xf bound_ctrl:1
	v_add_f32_dpp v208, v106, v210 row_shr:1 row_mask:0xf bank_mask:0xf bound_ctrl:1
	v_add_f32_dpp v146, v106, v146 row_shr:2 row_mask:0xf bank_mask:0xf bound_ctrl:1
	v_add_f32_dpp v167, v111, v169 row_shr:1 row_mask:0xf bank_mask:0xf bound_ctrl:1
	v_add_f32_dpp v145, v111, v151 row_shr:2 row_mask:0xf bank_mask:0xf bound_ctrl:1
	v_add_f32_dpp v209, v107, v211 row_shr:1 row_mask:0xf bank_mask:0xf bound_ctrl:1
	v_add_f32_dpp v147, v107, v147 row_shr:2 row_mask:0xf bank_mask:0xf bound_ctrl:1
	v_cmp_gt_i32_e64 s[12:13], s79, v195
	v_add_u32_e32 v197, s33, v195
	s_and_saveexec_b64 s[14:15], s[12:13]
	s_cbranch_execz .LBB0_2268
	s_waitcnt vmcnt(0)
	v_pk_fma_f32 v[144:145], v[126:127], v[144:145], v[130:131]
	v_pk_fma_f32 v[144:145], v[122:123], v[166:167], v[144:145]
	v_pk_fma_f32 v[148:149], v[124:125], v[148:149], v[128:129]
	v_pk_fma_f32 v[144:145], v[110:111], v[118:119], v[144:145]
	v_pk_fma_f32 v[148:149], v[120:121], v[162:163], v[148:149]
	v_mul_f32_e32 v160, 0xbfb8aa3b, v144
	v_mul_f32_e32 v161, 0xbfb8aa3b, v145
	v_pk_fma_f32 v[148:149], v[108:109], v[116:117], v[148:149]
	v_exp_f32_e32 v160, v160
	v_exp_f32_e32 v161, v161
	v_mul_f32_e32 v150, 0xbfb8aa3b, v148
	v_mul_f32_e32 v151, 0xbfb8aa3b, v149
	v_exp_f32_e32 v150, v150
	v_exp_f32_e32 v151, v151
	v_add_f32_e32 v160, 1.0, v160
	v_add_f32_e32 v161, 1.0, v161
	v_rcp_f32_e32 v160, v160
	v_rcp_f32_e32 v161, v161
	v_add_f32_e32 v150, 1.0, v150
	v_add_f32_e32 v151, 1.0, v151
	v_pk_fma_f32 v[146:147], v[138:139], v[146:147], v[142:143]
	v_rcp_f32_e32 v150, v150
	v_rcp_f32_e32 v151, v151
	v_pk_fma_f32 v[146:147], v[134:135], v[208:209], v[146:147]
	v_pk_fma_f32 v[170:171], v[136:137], v[170:171], v[140:141]
	v_pk_fma_f32 v[146:147], v[106:107], v[114:115], v[146:147]
	v_pk_mul_f32 v[144:145], v[144:145], v[160:161]
	v_pk_fma_f32 v[170:171], v[132:133], v[174:175], v[170:171]
	v_pk_mul_f32 v[144:145], v[146:147], v[144:145]
	v_pk_fma_f32 v[162:163], v[104:105], v[112:113], v[170:171]
	v_pk_mul_f32 v[148:149], v[148:149], v[150:151]
	v_cvt_pk_bf16_f32 v147, v144, v145
	v_pk_mul_f32 v[148:149], v[162:163], v[148:149]
	v_mul_u32_u24_e32 v144, s96, v197
	v_cvt_pk_bf16_f32 v146, v148, v149
	v_lshl_add_u32 v144, v190, 1, v144
	global_store_dwordx2 v144, v[146:147], s[36:37]
.LBB0_2268:
	s_or_b64 exec, exec, s[14:15]
	v_pk_mul_f32 v[94:95], v[94:95], v[198:199] op_sel_hi:[1,0]
	v_pk_mul_f32 v[92:93], v[92:93], v[198:199] op_sel_hi:[1,0]
	v_pk_mul_f32 v[90:91], v[90:91], v[198:199] op_sel_hi:[1,0]
	v_pk_mul_f32 v[88:89], v[88:89], v[198:199] op_sel_hi:[1,0]
	v_add_u32_e32 v195, s18, v226
	v_mov_b32_dpp v148, v108 row_shl:15 row_mask:0xf bank_mask:0xf bound_ctrl:1
	v_mov_b32_dpp v108, v108 row_shl:14 row_mask:0xf bank_mask:0xf bound_ctrl:1
	v_mov_b32_dpp v168, v104 row_shl:15 row_mask:0xf bank_mask:0xf bound_ctrl:1
	v_mov_b32_dpp v164, v104 row_shl:14 row_mask:0xf bank_mask:0xf bound_ctrl:1
	v_mov_b32_dpp v149, v109 row_shl:15 row_mask:0xf bank_mask:0xf bound_ctrl:1
	v_mov_b32_dpp v109, v109 row_shl:14 row_mask:0xf bank_mask:0xf bound_ctrl:1
	v_mov_b32_dpp v169, v105 row_shl:15 row_mask:0xf bank_mask:0xf bound_ctrl:1
	v_mov_b32_dpp v165, v105 row_shl:14 row_mask:0xf bank_mask:0xf bound_ctrl:1
	v_mov_b32_dpp v160, v110 row_shl:15 row_mask:0xf bank_mask:0xf bound_ctrl:1
	v_mov_b32_dpp v110, v110 row_shl:14 row_mask:0xf bank_mask:0xf bound_ctrl:1
	v_mov_b32_dpp v174, v106 row_shl:15 row_mask:0xf bank_mask:0xf bound_ctrl:1
	v_mov_b32_dpp v106, v106 row_shl:14 row_mask:0xf bank_mask:0xf bound_ctrl:1
	v_mov_b32_dpp v161, v111 row_shl:15 row_mask:0xf bank_mask:0xf bound_ctrl:1
	v_mov_b32_dpp v111, v111 row_shl:14 row_mask:0xf bank_mask:0xf bound_ctrl:1
	v_mov_b32_dpp v175, v107 row_shl:15 row_mask:0xf bank_mask:0xf bound_ctrl:1
	v_mov_b32_dpp v107, v107 row_shl:14 row_mask:0xf bank_mask:0xf bound_ctrl:1
	v_add_f32_dpp v146, v92, v148 row_shr:1 row_mask:0xf bank_mask:0xf bound_ctrl:1
	v_add_f32_dpp v108, v92, v108 row_shr:2 row_mask:0xf bank_mask:0xf bound_ctrl:1
	v_add_f32_dpp v166, v88, v168 row_shr:1 row_mask:0xf bank_mask:0xf bound_ctrl:1
	v_add_f32_dpp v162, v88, v164 row_shr:2 row_mask:0xf bank_mask:0xf bound_ctrl:1
	v_add_f32_dpp v147, v93, v149 row_shr:1 row_mask:0xf bank_mask:0xf bound_ctrl:1
	v_add_f32_dpp v109, v93, v109 row_shr:2 row_mask:0xf bank_mask:0xf bound_ctrl:1
	v_add_f32_dpp v167, v89, v169 row_shr:1 row_mask:0xf bank_mask:0xf bound_ctrl:1
	v_add_f32_dpp v163, v89, v165 row_shr:2 row_mask:0xf bank_mask:0xf bound_ctrl:1
	v_add_f32_dpp v150, v94, v160 row_shr:1 row_mask:0xf bank_mask:0xf bound_ctrl:1
	v_add_f32_dpp v104, v94, v110 row_shr:2 row_mask:0xf bank_mask:0xf bound_ctrl:1
	v_add_f32_dpp v172, v90, v174 row_shr:1 row_mask:0xf bank_mask:0xf bound_ctrl:1
	v_add_f32_dpp v106, v90, v106 row_shr:2 row_mask:0xf bank_mask:0xf bound_ctrl:1
	v_add_f32_dpp v151, v95, v161 row_shr:1 row_mask:0xf bank_mask:0xf bound_ctrl:1
	v_add_f32_dpp v105, v95, v111 row_shr:2 row_mask:0xf bank_mask:0xf bound_ctrl:1
	v_add_f32_dpp v173, v91, v175 row_shr:1 row_mask:0xf bank_mask:0xf bound_ctrl:1
	v_add_f32_dpp v107, v91, v107 row_shr:2 row_mask:0xf bank_mask:0xf bound_ctrl:1
	v_cmp_gt_i32_e64 s[14:15], s79, v195
	v_add_u32_e32 v195, s33, v195
	s_and_saveexec_b64 s[16:17], s[14:15]
	s_cbranch_execz .LBB0_2270
	s_waitcnt vmcnt(0)
	v_pk_fma_f32 v[104:105], v[126:127], v[104:105], v[130:131]
	v_pk_fma_f32 v[104:105], v[122:123], v[150:151], v[104:105]
	v_pk_fma_f32 v[108:109], v[124:125], v[108:109], v[128:129]
	v_pk_fma_f32 v[104:105], v[94:95], v[118:119], v[104:105]
	v_pk_fma_f32 v[108:109], v[120:121], v[146:147], v[108:109]
	v_mul_f32_e32 v144, 0xbfb8aa3b, v104
	v_mul_f32_e32 v145, 0xbfb8aa3b, v105
	v_pk_fma_f32 v[108:109], v[92:93], v[116:117], v[108:109]
	v_exp_f32_e32 v144, v144
	v_exp_f32_e32 v145, v145
	v_mul_f32_e32 v110, 0xbfb8aa3b, v108
	v_mul_f32_e32 v111, 0xbfb8aa3b, v109
	v_exp_f32_e32 v110, v110
	v_exp_f32_e32 v111, v111
	v_add_f32_e32 v144, 1.0, v144
	v_add_f32_e32 v145, 1.0, v145
	v_rcp_f32_e32 v144, v144
	v_rcp_f32_e32 v145, v145
	v_add_f32_e32 v110, 1.0, v110
	v_add_f32_e32 v111, 1.0, v111
	v_pk_fma_f32 v[106:107], v[138:139], v[106:107], v[142:143]
	v_rcp_f32_e32 v110, v110
	v_rcp_f32_e32 v111, v111
	v_pk_fma_f32 v[106:107], v[134:135], v[172:173], v[106:107]
	v_pk_fma_f32 v[162:163], v[136:137], v[162:163], v[140:141]
	v_pk_fma_f32 v[106:107], v[90:91], v[114:115], v[106:107]
	v_pk_mul_f32 v[104:105], v[104:105], v[144:145]
	v_pk_fma_f32 v[162:163], v[132:133], v[166:167], v[162:163]
	v_pk_mul_f32 v[104:105], v[106:107], v[104:105]
	v_pk_fma_f32 v[146:147], v[88:89], v[112:113], v[162:163]
	v_pk_mul_f32 v[108:109], v[108:109], v[110:111]
	v_cvt_pk_bf16_f32 v107, v104, v105
	v_pk_mul_f32 v[108:109], v[146:147], v[108:109]
	v_mul_u32_u24_e32 v104, s96, v195
	v_cvt_pk_bf16_f32 v106, v108, v109
	v_lshl_add_u32 v104, v190, 1, v104
	global_store_dwordx2 v104, v[106:107], s[36:37]
.LBB0_2270:
	s_or_b64 exec, exec, s[16:17]
	v_add_u32_e32 v168, s18, v227
	v_mov_b32_dpp v108, v92 row_shl:15 row_mask:0xf bank_mask:0xf bound_ctrl:1
	v_mov_b32_dpp v92, v92 row_shl:14 row_mask:0xf bank_mask:0xf bound_ctrl:1
	v_mov_b32_dpp v160, v88 row_shl:15 row_mask:0xf bank_mask:0xf bound_ctrl:1
	v_mov_b32_dpp v148, v88 row_shl:14 row_mask:0xf bank_mask:0xf bound_ctrl:1
	v_mov_b32_dpp v109, v93 row_shl:15 row_mask:0xf bank_mask:0xf bound_ctrl:1
	v_mov_b32_dpp v93, v93 row_shl:14 row_mask:0xf bank_mask:0xf bound_ctrl:1
	v_mov_b32_dpp v161, v89 row_shl:15 row_mask:0xf bank_mask:0xf bound_ctrl:1
	v_mov_b32_dpp v149, v89 row_shl:14 row_mask:0xf bank_mask:0xf bound_ctrl:1
	v_mov_b32_dpp v144, v94 row_shl:15 row_mask:0xf bank_mask:0xf bound_ctrl:1
	v_mov_b32_dpp v94, v94 row_shl:14 row_mask:0xf bank_mask:0xf bound_ctrl:1
	v_mov_b32_dpp v166, v90 row_shl:15 row_mask:0xf bank_mask:0xf bound_ctrl:1
	v_mov_b32_dpp v90, v90 row_shl:14 row_mask:0xf bank_mask:0xf bound_ctrl:1
	v_mov_b32_dpp v145, v95 row_shl:15 row_mask:0xf bank_mask:0xf bound_ctrl:1
	v_mov_b32_dpp v95, v95 row_shl:14 row_mask:0xf bank_mask:0xf bound_ctrl:1
	v_mov_b32_dpp v167, v91 row_shl:15 row_mask:0xf bank_mask:0xf bound_ctrl:1
	v_mov_b32_dpp v91, v91 row_shl:14 row_mask:0xf bank_mask:0xf bound_ctrl:1
	v_add_f32_dpp v106, v156, v108 row_shr:1 row_mask:0xf bank_mask:0xf bound_ctrl:1
	v_add_f32_dpp v92, v156, v92 row_shr:2 row_mask:0xf bank_mask:0xf bound_ctrl:1
	v_add_f32_dpp v150, v152, v160 row_shr:1 row_mask:0xf bank_mask:0xf bound_ctrl:1
	v_add_f32_dpp v146, v152, v148 row_shr:2 row_mask:0xf bank_mask:0xf bound_ctrl:1
	v_add_f32_dpp v107, v157, v109 row_shr:1 row_mask:0xf bank_mask:0xf bound_ctrl:1
	v_add_f32_dpp v93, v157, v93 row_shr:2 row_mask:0xf bank_mask:0xf bound_ctrl:1
	v_add_f32_dpp v151, v153, v161 row_shr:1 row_mask:0xf bank_mask:0xf bound_ctrl:1
	v_add_f32_dpp v147, v153, v149 row_shr:2 row_mask:0xf bank_mask:0xf bound_ctrl:1
	v_add_f32_dpp v110, v158, v144 row_shr:1 row_mask:0xf bank_mask:0xf bound_ctrl:1
	v_add_f32_dpp v88, v158, v94 row_shr:2 row_mask:0xf bank_mask:0xf bound_ctrl:1
	v_add_f32_dpp v164, v154, v166 row_shr:1 row_mask:0xf bank_mask:0xf bound_ctrl:1
	v_add_f32_dpp v90, v154, v90 row_shr:2 row_mask:0xf bank_mask:0xf bound_ctrl:1
	v_add_f32_dpp v111, v159, v145 row_shr:1 row_mask:0xf bank_mask:0xf bound_ctrl:1
	v_add_f32_dpp v89, v159, v95 row_shr:2 row_mask:0xf bank_mask:0xf bound_ctrl:1
	v_add_f32_dpp v165, v155, v167 row_shr:1 row_mask:0xf bank_mask:0xf bound_ctrl:1
	v_add_f32_dpp v91, v155, v91 row_shr:2 row_mask:0xf bank_mask:0xf bound_ctrl:1
	v_cmp_gt_i32_e64 s[22:23], s79, v168
	v_add_u32_e32 v168, s33, v168
	s_and_saveexec_b64 s[16:17], s[22:23]
	s_cbranch_execz .LBB0_2272
	s_waitcnt vmcnt(0)
	v_pk_fma_f32 v[88:89], v[126:127], v[88:89], v[130:131]
	v_pk_fma_f32 v[88:89], v[122:123], v[110:111], v[88:89]
	v_pk_fma_f32 v[92:93], v[124:125], v[92:93], v[128:129]
	v_pk_fma_f32 v[88:89], v[158:159], v[118:119], v[88:89]
	v_pk_fma_f32 v[92:93], v[120:121], v[106:107], v[92:93]
	v_mul_f32_e32 v104, 0xbfb8aa3b, v88
	v_mul_f32_e32 v105, 0xbfb8aa3b, v89
	v_pk_fma_f32 v[92:93], v[156:157], v[116:117], v[92:93]
	v_exp_f32_e32 v104, v104
	v_exp_f32_e32 v105, v105
	v_mul_f32_e32 v94, 0xbfb8aa3b, v92
	v_mul_f32_e32 v95, 0xbfb8aa3b, v93
	v_exp_f32_e32 v94, v94
	v_exp_f32_e32 v95, v95
	v_add_f32_e32 v104, 1.0, v104
	v_add_f32_e32 v105, 1.0, v105
	v_rcp_f32_e32 v104, v104
	v_rcp_f32_e32 v105, v105
	v_add_f32_e32 v94, 1.0, v94
	v_add_f32_e32 v95, 1.0, v95
	v_pk_fma_f32 v[90:91], v[138:139], v[90:91], v[142:143]
	v_rcp_f32_e32 v94, v94
	v_rcp_f32_e32 v95, v95
	v_pk_fma_f32 v[90:91], v[134:135], v[164:165], v[90:91]
	v_pk_fma_f32 v[146:147], v[136:137], v[146:147], v[140:141]
	v_pk_fma_f32 v[90:91], v[154:155], v[114:115], v[90:91]
	v_pk_mul_f32 v[88:89], v[88:89], v[104:105]
	v_pk_fma_f32 v[146:147], v[132:133], v[150:151], v[146:147]
	v_pk_mul_f32 v[88:89], v[90:91], v[88:89]
	v_pk_fma_f32 v[106:107], v[152:153], v[112:113], v[146:147]
	v_pk_mul_f32 v[92:93], v[92:93], v[94:95]
	v_cvt_pk_bf16_f32 v91, v88, v89
	v_pk_mul_f32 v[92:93], v[106:107], v[92:93]
	v_mul_u32_u24_e32 v88, s96, v168
	v_cvt_pk_bf16_f32 v90, v92, v93
	v_lshl_add_u32 v88, v190, 1, v88
	global_store_dwordx2 v88, v[90:91], s[36:37]

.LBB0_2278:
	s_or_b64 exec, exec, s[16:17]
	v_pk_mul_f32 v[86:87], v[86:87], v[196:197] op_sel_hi:[1,0]
	v_pk_mul_f32 v[84:85], v[84:85], v[196:197] op_sel_hi:[1,0]
	v_pk_mul_f32 v[82:83], v[82:83], v[196:197] op_sel_hi:[1,0]
	v_pk_mul_f32 v[80:81], v[80:81], v[196:197] op_sel_hi:[1,0]
	v_mov_b32_dpp v108, v84 row_shr:1 row_mask:0xf bank_mask:0xf bound_ctrl:1
	v_mov_b32_dpp v104, v84 row_shr:2 row_mask:0xf bank_mask:0xf bound_ctrl:1
	v_mov_b32_dpp v156, v80 row_shr:1 row_mask:0xf bank_mask:0xf bound_ctrl:1
	v_mov_b32_dpp v152, v80 row_shr:2 row_mask:0xf bank_mask:0xf bound_ctrl:1
	v_mov_b32_dpp v109, v85 row_shr:1 row_mask:0xf bank_mask:0xf bound_ctrl:1
	v_mov_b32_dpp v105, v85 row_shr:2 row_mask:0xf bank_mask:0xf bound_ctrl:1
	v_mov_b32_dpp v157, v81 row_shr:1 row_mask:0xf bank_mask:0xf bound_ctrl:1
	v_mov_b32_dpp v153, v81 row_shr:2 row_mask:0xf bank_mask:0xf bound_ctrl:1
	v_mov_b32_dpp v110, v86 row_shr:1 row_mask:0xf bank_mask:0xf bound_ctrl:1
	v_mov_b32_dpp v106, v86 row_shr:2 row_mask:0xf bank_mask:0xf bound_ctrl:1
	v_mov_b32_dpp v158, v82 row_shr:1 row_mask:0xf bank_mask:0xf bound_ctrl:1
	v_mov_b32_dpp v154, v82 row_shr:2 row_mask:0xf bank_mask:0xf bound_ctrl:1
	v_mov_b32_dpp v111, v87 row_shr:1 row_mask:0xf bank_mask:0xf bound_ctrl:1
	v_mov_b32_dpp v107, v87 row_shr:2 row_mask:0xf bank_mask:0xf bound_ctrl:1
	v_mov_b32_dpp v159, v83 row_shr:1 row_mask:0xf bank_mask:0xf bound_ctrl:1
	v_mov_b32_dpp v155, v83 row_shr:2 row_mask:0xf bank_mask:0xf bound_ctrl:1
	v_cmp_gt_i32_e64 s[24:25], s79, v241
	v_add_u32_e32 v160, s33, v241
	s_and_saveexec_b64 s[16:17], s[24:25]
	s_cbranch_execz .LBB0_2280
	s_waitcnt lgkmcnt(0)
	v_pk_add_f32 v[88:89], v[88:89], v[104:105]
	v_pk_add_f32 v[90:91], v[90:91], v[106:107]
	v_pk_add_f32 v[110:111], v[146:147], v[110:111]
	v_pk_add_f32 v[108:109], v[144:145], v[108:109]
	s_waitcnt vmcnt(0)
	v_pk_fma_f32 v[90:91], v[126:127], v[90:91], v[130:131]
	v_pk_fma_f32 v[88:89], v[124:125], v[88:89], v[128:129]
	v_pk_fma_f32 v[90:91], v[122:123], v[110:111], v[90:91]
	v_pk_fma_f32 v[88:89], v[120:121], v[108:109], v[88:89]
	v_pk_fma_f32 v[90:91], v[86:87], v[118:119], v[90:91]
	v_pk_fma_f32 v[88:89], v[84:85], v[116:117], v[88:89]
	v_mul_f32_e32 v106, 0xbfb8aa3b, v90
	v_mul_f32_e32 v104, 0xbfb8aa3b, v88
	v_mul_f32_e32 v105, 0xbfb8aa3b, v89
	v_mul_f32_e32 v107, 0xbfb8aa3b, v91
	v_exp_f32_e32 v104, v104
	v_exp_f32_e32 v105, v105
	v_exp_f32_e32 v106, v106
	v_exp_f32_e32 v107, v107
	v_add_f32_e32 v104, 1.0, v104
	v_add_f32_e32 v105, 1.0, v105
	v_add_f32_e32 v106, 1.0, v106
	v_add_f32_e32 v107, 1.0, v107
	v_rcp_f32_e32 v104, v104
	v_rcp_f32_e32 v105, v105
	v_rcp_f32_e32 v106, v106
	v_rcp_f32_e32 v107, v107
	v_pk_add_f32 v[92:93], v[92:93], v[152:153]
	v_pk_add_f32 v[94:95], v[94:95], v[154:155]
	v_pk_add_f32 v[150:151], v[150:151], v[158:159]
	v_pk_add_f32 v[148:149], v[148:149], v[156:157]
	v_pk_fma_f32 v[94:95], v[138:139], v[94:95], v[142:143]
	v_pk_fma_f32 v[92:93], v[136:137], v[92:93], v[140:141]
	v_pk_fma_f32 v[94:95], v[134:135], v[150:151], v[94:95]
	v_pk_fma_f32 v[92:93], v[132:133], v[148:149], v[92:93]
	v_pk_fma_f32 v[94:95], v[82:83], v[114:115], v[94:95]
	v_pk_fma_f32 v[92:93], v[80:81], v[112:113], v[92:93]
	v_pk_mul_f32 v[88:89], v[88:89], v[104:105]
	v_pk_mul_f32 v[90:91], v[90:91], v[106:107]
	v_pk_mul_f32 v[88:89], v[92:93], v[88:89]
	v_pk_mul_f32 v[90:91], v[94:95], v[90:91]
	v_cvt_pk_bf16_f32 v88, v88, v89
	v_cvt_pk_bf16_f32 v89, v90, v91
	v_mul_u32_u24_e32 v90, s96, v160
	v_lshl_add_u32 v90, v190, 1, v90
	global_store_dwordx2 v90, v[88:89], s[36:37]
.LBB0_2280:
	s_or_b64 exec, exec, s[16:17]
	v_pk_mul_f32 v[78:79], v[78:79], v[194:195] op_sel_hi:[1,0]
	v_pk_mul_f32 v[76:77], v[76:77], v[194:195] op_sel_hi:[1,0]
	v_pk_mul_f32 v[66:67], v[66:67], v[194:195] op_sel_hi:[1,0]
	v_pk_mul_f32 v[64:65], v[64:65], v[194:195] op_sel_hi:[1,0]
	s_waitcnt lgkmcnt(0)
	v_mov_b32_dpp v92, v84 row_shl:15 row_mask:0xf bank_mask:0xf bound_ctrl:1
	v_mov_b32_dpp v84, v84 row_shl:14 row_mask:0xf bank_mask:0xf bound_ctrl:1
	v_mov_b32_dpp v144, v80 row_shl:15 row_mask:0xf bank_mask:0xf bound_ctrl:1
	v_mov_b32_dpp v108, v80 row_shl:14 row_mask:0xf bank_mask:0xf bound_ctrl:1
	v_mov_b32_dpp v93, v85 row_shl:15 row_mask:0xf bank_mask:0xf bound_ctrl:1
	v_mov_b32_dpp v85, v85 row_shl:14 row_mask:0xf bank_mask:0xf bound_ctrl:1
	v_mov_b32_dpp v145, v81 row_shl:15 row_mask:0xf bank_mask:0xf bound_ctrl:1
	v_mov_b32_dpp v109, v81 row_shl:14 row_mask:0xf bank_mask:0xf bound_ctrl:1
	v_mov_b32_dpp v104, v86 row_shl:15 row_mask:0xf bank_mask:0xf bound_ctrl:1
	v_mov_b32_dpp v86, v86 row_shl:14 row_mask:0xf bank_mask:0xf bound_ctrl:1
	v_mov_b32_dpp v150, v82 row_shl:15 row_mask:0xf bank_mask:0xf bound_ctrl:1
	v_mov_b32_dpp v82, v82 row_shl:14 row_mask:0xf bank_mask:0xf bound_ctrl:1
	v_mov_b32_dpp v105, v87 row_shl:15 row_mask:0xf bank_mask:0xf bound_ctrl:1
	v_mov_b32_dpp v87, v87 row_shl:14 row_mask:0xf bank_mask:0xf bound_ctrl:1
	v_mov_b32_dpp v151, v83 row_shl:15 row_mask:0xf bank_mask:0xf bound_ctrl:1
	v_mov_b32_dpp v83, v83 row_shl:14 row_mask:0xf bank_mask:0xf bound_ctrl:1
	v_add_f32_dpp v90, v76, v92 row_shr:1 row_mask:0xf bank_mask:0xf bound_ctrl:1
	v_add_f32_dpp v84, v76, v84 row_shr:2 row_mask:0xf bank_mask:0xf bound_ctrl:1
	v_add_f32_dpp v110, v64, v144 row_shr:1 row_mask:0xf bank_mask:0xf bound_ctrl:1
	v_add_f32_dpp v106, v64, v108 row_shr:2 row_mask:0xf bank_mask:0xf bound_ctrl:1
	v_add_f32_dpp v91, v77, v93 row_shr:1 row_mask:0xf bank_mask:0xf bound_ctrl:1
	v_add_f32_dpp v85, v77, v85 row_shr:2 row_mask:0xf bank_mask:0xf bound_ctrl:1
	v_add_f32_dpp v111, v65, v145 row_shr:1 row_mask:0xf bank_mask:0xf bound_ctrl:1
	v_add_f32_dpp v107, v65, v109 row_shr:2 row_mask:0xf bank_mask:0xf bound_ctrl:1
	v_add_f32_dpp v94, v78, v104 row_shr:1 row_mask:0xf bank_mask:0xf bound_ctrl:1
	v_add_f32_dpp v80, v78, v86 row_shr:2 row_mask:0xf bank_mask:0xf bound_ctrl:1
	v_add_f32_dpp v148, v66, v150 row_shr:1 row_mask:0xf bank_mask:0xf bound_ctrl:1
	v_add_f32_dpp v82, v66, v82 row_shr:2 row_mask:0xf bank_mask:0xf bound_ctrl:1
	v_add_f32_dpp v95, v79, v105 row_shr:1 row_mask:0xf bank_mask:0xf bound_ctrl:1
	v_add_f32_dpp v81, v79, v87 row_shr:2 row_mask:0xf bank_mask:0xf bound_ctrl:1
	v_add_f32_dpp v149, v67, v151 row_shr:1 row_mask:0xf bank_mask:0xf bound_ctrl:1
	v_add_f32_dpp v83, v67, v83 row_shr:2 row_mask:0xf bank_mask:0xf bound_ctrl:1
	v_cmp_gt_i32_e64 s[18:19], s79, v240
	v_add_u32_e32 v152, s33, v240
	s_and_saveexec_b64 s[16:17], s[18:19]
	s_cbranch_execz .LBB0_2282
	s_waitcnt vmcnt(0)
	v_pk_fma_f32 v[80:81], v[126:127], v[80:81], v[130:131]
	v_pk_fma_f32 v[80:81], v[122:123], v[94:95], v[80:81]
	v_pk_fma_f32 v[84:85], v[124:125], v[84:85], v[128:129]
	v_pk_fma_f32 v[80:81], v[78:79], v[118:119], v[80:81]
	v_pk_fma_f32 v[84:85], v[120:121], v[90:91], v[84:85]
	v_mul_f32_e32 v88, 0xbfb8aa3b, v80
	v_mul_f32_e32 v89, 0xbfb8aa3b, v81
	v_pk_fma_f32 v[84:85], v[76:77], v[116:117], v[84:85]
	v_exp_f32_e32 v88, v88
	v_exp_f32_e32 v89, v89
	v_mul_f32_e32 v86, 0xbfb8aa3b, v84
	v_mul_f32_e32 v87, 0xbfb8aa3b, v85
	v_exp_f32_e32 v86, v86
	v_exp_f32_e32 v87, v87
	v_add_f32_e32 v88, 1.0, v88
	v_add_f32_e32 v89, 1.0, v89
	v_rcp_f32_e32 v88, v88
	v_rcp_f32_e32 v89, v89
	v_add_f32_e32 v86, 1.0, v86
	v_add_f32_e32 v87, 1.0, v87
	v_pk_fma_f32 v[82:83], v[138:139], v[82:83], v[142:143]
	v_rcp_f32_e32 v86, v86
	v_rcp_f32_e32 v87, v87
	v_pk_fma_f32 v[82:83], v[134:135], v[148:149], v[82:83]
	v_pk_fma_f32 v[106:107], v[136:137], v[106:107], v[140:141]
	v_pk_fma_f32 v[82:83], v[66:67], v[114:115], v[82:83]
	v_pk_mul_f32 v[80:81], v[80:81], v[88:89]
	v_pk_fma_f32 v[106:107], v[132:133], v[110:111], v[106:107]
	v_pk_mul_f32 v[80:81], v[82:83], v[80:81]
	v_pk_fma_f32 v[90:91], v[64:65], v[112:113], v[106:107]
	v_pk_mul_f32 v[84:85], v[84:85], v[86:87]
	v_cvt_pk_bf16_f32 v83, v80, v81
	v_pk_mul_f32 v[84:85], v[90:91], v[84:85]
	v_mul_u32_u24_e32 v80, s96, v152
	v_cvt_pk_bf16_f32 v82, v84, v85
	v_lshl_add_u32 v80, v190, 1, v80
	global_store_dwordx2 v80, v[82:83], s[36:37]
.LBB0_2282:
	s_or_b64 exec, exec, s[16:17]
	v_pk_mul_f32 v[62:63], v[62:63], v[192:193] op_sel_hi:[1,0]
	v_pk_mul_f32 v[60:61], v[60:61], v[192:193] op_sel_hi:[1,0]
	v_pk_mul_f32 v[58:59], v[58:59], v[192:193] op_sel_hi:[1,0]
	v_pk_mul_f32 v[56:57], v[56:57], v[192:193] op_sel_hi:[1,0]
	v_mov_b32_dpp v84, v76 row_shl:15 row_mask:0xf bank_mask:0xf bound_ctrl:1
	v_mov_b32_dpp v76, v76 row_shl:14 row_mask:0xf bank_mask:0xf bound_ctrl:1
	v_mov_b32_dpp v104, v64 row_shl:15 row_mask:0xf bank_mask:0xf bound_ctrl:1
	v_mov_b32_dpp v92, v64 row_shl:14 row_mask:0xf bank_mask:0xf bound_ctrl:1
	v_mov_b32_dpp v85, v77 row_shl:15 row_mask:0xf bank_mask:0xf bound_ctrl:1
	v_mov_b32_dpp v77, v77 row_shl:14 row_mask:0xf bank_mask:0xf bound_ctrl:1
	v_mov_b32_dpp v105, v65 row_shl:15 row_mask:0xf bank_mask:0xf bound_ctrl:1
	v_mov_b32_dpp v93, v65 row_shl:14 row_mask:0xf bank_mask:0xf bound_ctrl:1
	v_mov_b32_dpp v88, v78 row_shl:15 row_mask:0xf bank_mask:0xf bound_ctrl:1
	v_mov_b32_dpp v78, v78 row_shl:14 row_mask:0xf bank_mask:0xf bound_ctrl:1
	v_mov_b32_dpp v110, v66 row_shl:15 row_mask:0xf bank_mask:0xf bound_ctrl:1
	v_mov_b32_dpp v66, v66 row_shl:14 row_mask:0xf bank_mask:0xf bound_ctrl:1
	v_mov_b32_dpp v89, v79 row_shl:15 row_mask:0xf bank_mask:0xf bound_ctrl:1
	v_mov_b32_dpp v79, v79 row_shl:14 row_mask:0xf bank_mask:0xf bound_ctrl:1
	v_mov_b32_dpp v111, v67 row_shl:15 row_mask:0xf bank_mask:0xf bound_ctrl:1
	v_mov_b32_dpp v67, v67 row_shl:14 row_mask:0xf bank_mask:0xf bound_ctrl:1
	v_add_f32_dpp v82, v60, v84 row_shr:1 row_mask:0xf bank_mask:0xf bound_ctrl:1
	v_add_f32_dpp v76, v60, v76 row_shr:2 row_mask:0xf bank_mask:0xf bound_ctrl:1
	v_add_f32_dpp v94, v56, v104 row_shr:1 row_mask:0xf bank_mask:0xf bound_ctrl:1
	v_add_f32_dpp v90, v56, v92 row_shr:2 row_mask:0xf bank_mask:0xf bound_ctrl:1
	v_add_f32_dpp v83, v61, v85 row_shr:1 row_mask:0xf bank_mask:0xf bound_ctrl:1
	v_add_f32_dpp v77, v61, v77 row_shr:2 row_mask:0xf bank_mask:0xf bound_ctrl:1
	v_add_f32_dpp v95, v57, v105 row_shr:1 row_mask:0xf bank_mask:0xf bound_ctrl:1
	v_add_f32_dpp v91, v57, v93 row_shr:2 row_mask:0xf bank_mask:0xf bound_ctrl:1
	v_add_f32_dpp v86, v62, v88 row_shr:1 row_mask:0xf bank_mask:0xf bound_ctrl:1
	v_add_f32_dpp v64, v62, v78 row_shr:2 row_mask:0xf bank_mask:0xf bound_ctrl:1
	v_add_f32_dpp v108, v58, v110 row_shr:1 row_mask:0xf bank_mask:0xf bound_ctrl:1
	v_add_f32_dpp v66, v58, v66 row_shr:2 row_mask:0xf bank_mask:0xf bound_ctrl:1
	v_add_f32_dpp v87, v63, v89 row_shr:1 row_mask:0xf bank_mask:0xf bound_ctrl:1
	v_add_f32_dpp v65, v63, v79 row_shr:2 row_mask:0xf bank_mask:0xf bound_ctrl:1
	v_add_f32_dpp v109, v59, v111 row_shr:1 row_mask:0xf bank_mask:0xf bound_ctrl:1
	v_add_f32_dpp v67, v59, v67 row_shr:2 row_mask:0xf bank_mask:0xf bound_ctrl:1
	v_cmp_gt_i32_e64 s[16:17], s79, v203
	v_add_u32_e32 v144, s33, v203
	s_and_saveexec_b64 s[26:27], s[16:17]
	s_cbranch_execz .LBB0_2284
	s_waitcnt vmcnt(0)
	v_pk_fma_f32 v[64:65], v[126:127], v[64:65], v[130:131]
	v_pk_fma_f32 v[64:65], v[122:123], v[86:87], v[64:65]
	v_pk_fma_f32 v[76:77], v[124:125], v[76:77], v[128:129]
	v_pk_fma_f32 v[64:65], v[62:63], v[118:119], v[64:65]
	v_pk_fma_f32 v[76:77], v[120:121], v[82:83], v[76:77]
	v_mul_f32_e32 v80, 0xbfb8aa3b, v64
	v_mul_f32_e32 v81, 0xbfb8aa3b, v65
	v_pk_fma_f32 v[76:77], v[60:61], v[116:117], v[76:77]
	v_exp_f32_e32 v80, v80
	v_exp_f32_e32 v81, v81
	v_mul_f32_e32 v78, 0xbfb8aa3b, v76
	v_mul_f32_e32 v79, 0xbfb8aa3b, v77
	v_exp_f32_e32 v78, v78
	v_exp_f32_e32 v79, v79
	v_add_f32_e32 v80, 1.0, v80
	v_add_f32_e32 v81, 1.0, v81
	v_rcp_f32_e32 v80, v80
	v_rcp_f32_e32 v81, v81
	v_add_f32_e32 v78, 1.0, v78
	v_add_f32_e32 v79, 1.0, v79
	v_pk_fma_f32 v[66:67], v[138:139], v[66:67], v[142:143]
	v_rcp_f32_e32 v78, v78
	v_rcp_f32_e32 v79, v79
	v_pk_fma_f32 v[66:67], v[134:135], v[108:109], v[66:67]
	v_pk_fma_f32 v[90:91], v[136:137], v[90:91], v[140:141]
	v_pk_fma_f32 v[66:67], v[58:59], v[114:115], v[66:67]
	v_pk_mul_f32 v[64:65], v[64:65], v[80:81]
	v_pk_fma_f32 v[90:91], v[132:133], v[94:95], v[90:91]
	v_pk_mul_f32 v[64:65], v[66:67], v[64:65]
	v_pk_fma_f32 v[82:83], v[56:57], v[112:113], v[90:91]
	v_pk_mul_f32 v[76:77], v[76:77], v[78:79]
	v_cvt_pk_bf16_f32 v67, v64, v65
	v_pk_mul_f32 v[76:77], v[82:83], v[76:77]
	v_mul_u32_u24_e32 v64, s96, v144
	v_cvt_pk_bf16_f32 v66, v76, v77
	v_lshl_add_u32 v64, v190, 1, v64
	global_store_dwordx2 v64, v[66:67], s[36:37]

.LBB0_2294:
	v_mov_b32_e32 v203, v202
	v_mov_b32_e32 v104, v202
	v_mov_b32_e32 v105, v202
	v_pk_mul_f32 v[54:55], v[54:55], v[104:105]
	v_pk_mul_f32 v[52:53], v[52:53], v[202:203]
	v_pk_mul_f32 v[50:51], v[50:51], v[104:105]
	v_pk_mul_f32 v[48:49], v[48:49], v[202:203]
	s_waitcnt lgkmcnt(0)
	v_mov_b32_dpp v108, v52 row_shr:1 row_mask:0xf bank_mask:0xf bound_ctrl:1
	v_mov_b32_dpp v104, v52 row_shr:2 row_mask:0xf bank_mask:0xf bound_ctrl:1
	v_mov_b32_dpp v124, v48 row_shr:1 row_mask:0xf bank_mask:0xf bound_ctrl:1
	v_mov_b32_dpp v120, v48 row_shr:2 row_mask:0xf bank_mask:0xf bound_ctrl:1
	v_mov_b32_dpp v109, v53 row_shr:1 row_mask:0xf bank_mask:0xf bound_ctrl:1
	v_mov_b32_dpp v105, v53 row_shr:2 row_mask:0xf bank_mask:0xf bound_ctrl:1
	v_mov_b32_dpp v125, v49 row_shr:1 row_mask:0xf bank_mask:0xf bound_ctrl:1
	v_mov_b32_dpp v121, v49 row_shr:2 row_mask:0xf bank_mask:0xf bound_ctrl:1
	v_mov_b32_dpp v110, v54 row_shr:1 row_mask:0xf bank_mask:0xf bound_ctrl:1
	v_mov_b32_dpp v106, v54 row_shr:2 row_mask:0xf bank_mask:0xf bound_ctrl:1
	v_mov_b32_dpp v126, v50 row_shr:1 row_mask:0xf bank_mask:0xf bound_ctrl:1
	v_mov_b32_dpp v122, v50 row_shr:2 row_mask:0xf bank_mask:0xf bound_ctrl:1
	v_mov_b32_dpp v111, v55 row_shr:1 row_mask:0xf bank_mask:0xf bound_ctrl:1
	v_mov_b32_dpp v107, v55 row_shr:2 row_mask:0xf bank_mask:0xf bound_ctrl:1
	v_mov_b32_dpp v127, v51 row_shr:1 row_mask:0xf bank_mask:0xf bound_ctrl:1
	v_mov_b32_dpp v123, v51 row_shr:2 row_mask:0xf bank_mask:0xf bound_ctrl:1
	s_and_saveexec_b64 s[20:21], s[0:1]
	s_cbranch_execz .LBB0_2296
	v_pk_add_f32 v[96:97], v[96:97], v[104:105]
	v_pk_add_f32 v[98:99], v[98:99], v[106:107]
	v_pk_add_f32 v[110:111], v[114:115], v[110:111]
	v_pk_add_f32 v[108:109], v[112:113], v[108:109]
	v_pk_fma_f32 v[98:99], v[78:79], v[98:99], v[82:83]
	v_pk_fma_f32 v[96:97], v[76:77], v[96:97], v[80:81]
	v_pk_fma_f32 v[98:99], v[66:67], v[110:111], v[98:99]
	v_pk_fma_f32 v[96:97], v[64:65], v[108:109], v[96:97]
	v_pk_fma_f32 v[98:99], v[54:55], v[62:63], v[98:99]
	v_pk_fma_f32 v[96:97], v[52:53], v[60:61], v[96:97]
	v_mul_f32_e32 v106, 0xbfb8aa3b, v98
	v_mul_f32_e32 v104, 0xbfb8aa3b, v96
	v_mul_f32_e32 v105, 0xbfb8aa3b, v97
	v_mul_f32_e32 v107, 0xbfb8aa3b, v99
	v_exp_f32_e32 v104, v104
	v_exp_f32_e32 v105, v105
	v_exp_f32_e32 v106, v106
	v_exp_f32_e32 v107, v107
	v_add_f32_e32 v104, 1.0, v104
	v_add_f32_e32 v105, 1.0, v105
	v_add_f32_e32 v106, 1.0, v106
	v_add_f32_e32 v107, 1.0, v107
	v_rcp_f32_e32 v104, v104
	v_rcp_f32_e32 v105, v105
	v_rcp_f32_e32 v106, v106
	v_rcp_f32_e32 v107, v107
	v_pk_add_f32 v[100:101], v[100:101], v[120:121]
	v_pk_add_f32 v[102:103], v[102:103], v[122:123]
	v_pk_add_f32 v[118:119], v[118:119], v[126:127]
	v_pk_add_f32 v[116:117], v[116:117], v[124:125]
	v_pk_fma_f32 v[102:103], v[90:91], v[102:103], v[94:95]
	v_pk_fma_f32 v[100:101], v[88:89], v[100:101], v[92:93]
	v_pk_fma_f32 v[102:103], v[86:87], v[118:119], v[102:103]
	v_pk_fma_f32 v[100:101], v[84:85], v[116:117], v[100:101]
	v_pk_fma_f32 v[102:103], v[50:51], v[58:59], v[102:103]
	v_pk_fma_f32 v[100:101], v[48:49], v[56:57], v[100:101]
	v_pk_mul_f32 v[96:97], v[96:97], v[104:105]
	v_pk_mul_f32 v[98:99], v[98:99], v[106:107]
	v_pk_mul_f32 v[96:97], v[100:101], v[96:97]
	v_pk_mul_f32 v[98:99], v[102:103], v[98:99]
	v_cvt_pk_bf16_f32 v96, v96, v97
	v_cvt_pk_bf16_f32 v97, v98, v99
	v_mul_u32_u24_e32 v98, s96, v199
	v_lshl_add_u32 v98, v190, 1, v98
	global_store_dwordx2 v98, v[96:97], s[36:37] offset:8
.LBB0_2296:
	s_or_b64 exec, exec, s[20:21]
	v_mov_b32_e32 v201, v200
	v_mov_b32_e32 v96, v200
	v_mov_b32_e32 v97, v200
	v_pk_mul_f32 v[46:47], v[46:47], v[96:97]
	v_pk_mul_f32 v[44:45], v[44:45], v[200:201]
	v_pk_mul_f32 v[34:35], v[34:35], v[96:97]
	v_pk_mul_f32 v[32:33], v[32:33], v[200:201]
	v_mov_b32_dpp v100, v52 row_shl:15 row_mask:0xf bank_mask:0xf bound_ctrl:1
	v_mov_b32_dpp v52, v52 row_shl:14 row_mask:0xf bank_mask:0xf bound_ctrl:1
	v_mov_b32_dpp v112, v48 row_shl:15 row_mask:0xf bank_mask:0xf bound_ctrl:1
	v_mov_b32_dpp v108, v48 row_shl:14 row_mask:0xf bank_mask:0xf bound_ctrl:1
	v_mov_b32_dpp v101, v53 row_shl:15 row_mask:0xf bank_mask:0xf bound_ctrl:1
	v_mov_b32_dpp v53, v53 row_shl:14 row_mask:0xf bank_mask:0xf bound_ctrl:1
	v_mov_b32_dpp v113, v49 row_shl:15 row_mask:0xf bank_mask:0xf bound_ctrl:1
	v_mov_b32_dpp v109, v49 row_shl:14 row_mask:0xf bank_mask:0xf bound_ctrl:1
	v_mov_b32_dpp v104, v54 row_shl:15 row_mask:0xf bank_mask:0xf bound_ctrl:1
	v_mov_b32_dpp v54, v54 row_shl:14 row_mask:0xf bank_mask:0xf bound_ctrl:1
	v_mov_b32_dpp v118, v50 row_shl:15 row_mask:0xf bank_mask:0xf bound_ctrl:1
	v_mov_b32_dpp v50, v50 row_shl:14 row_mask:0xf bank_mask:0xf bound_ctrl:1
	v_mov_b32_dpp v105, v55 row_shl:15 row_mask:0xf bank_mask:0xf bound_ctrl:1
	v_mov_b32_dpp v55, v55 row_shl:14 row_mask:0xf bank_mask:0xf bound_ctrl:1
	v_mov_b32_dpp v119, v51 row_shl:15 row_mask:0xf bank_mask:0xf bound_ctrl:1
	v_mov_b32_dpp v51, v51 row_shl:14 row_mask:0xf bank_mask:0xf bound_ctrl:1
	v_add_f32_dpp v98, v44, v100 row_shr:1 row_mask:0xf bank_mask:0xf bound_ctrl:1
	v_add_f32_dpp v52, v44, v52 row_shr:2 row_mask:0xf bank_mask:0xf bound_ctrl:1
	v_add_f32_dpp v110, v32, v112 row_shr:1 row_mask:0xf bank_mask:0xf bound_ctrl:1
	v_add_f32_dpp v106, v32, v108 row_shr:2 row_mask:0xf bank_mask:0xf bound_ctrl:1
	v_add_f32_dpp v99, v45, v101 row_shr:1 row_mask:0xf bank_mask:0xf bound_ctrl:1
	v_add_f32_dpp v53, v45, v53 row_shr:2 row_mask:0xf bank_mask:0xf bound_ctrl:1
	v_add_f32_dpp v111, v33, v113 row_shr:1 row_mask:0xf bank_mask:0xf bound_ctrl:1
	v_add_f32_dpp v107, v33, v109 row_shr:2 row_mask:0xf bank_mask:0xf bound_ctrl:1
	v_add_f32_dpp v102, v46, v104 row_shr:1 row_mask:0xf bank_mask:0xf bound_ctrl:1
	v_add_f32_dpp v48, v46, v54 row_shr:2 row_mask:0xf bank_mask:0xf bound_ctrl:1
	v_add_f32_dpp v116, v34, v118 row_shr:1 row_mask:0xf bank_mask:0xf bound_ctrl:1
	v_add_f32_dpp v50, v34, v50 row_shr:2 row_mask:0xf bank_mask:0xf bound_ctrl:1
	v_add_f32_dpp v103, v47, v105 row_shr:1 row_mask:0xf bank_mask:0xf bound_ctrl:1
	v_add_f32_dpp v49, v47, v55 row_shr:2 row_mask:0xf bank_mask:0xf bound_ctrl:1
	v_add_f32_dpp v117, v35, v119 row_shr:1 row_mask:0xf bank_mask:0xf bound_ctrl:1
	v_add_f32_dpp v51, v35, v51 row_shr:2 row_mask:0xf bank_mask:0xf bound_ctrl:1
	s_and_saveexec_b64 s[0:1], s[12:13]
	s_cbranch_execz .LBB0_2298
	v_pk_fma_f32 v[48:49], v[78:79], v[48:49], v[82:83]
	v_pk_fma_f32 v[48:49], v[66:67], v[102:103], v[48:49]
	v_pk_fma_f32 v[52:53], v[76:77], v[52:53], v[80:81]
	v_pk_fma_f32 v[48:49], v[46:47], v[62:63], v[48:49]
	v_pk_fma_f32 v[52:53], v[64:65], v[98:99], v[52:53]
	v_mul_f32_e32 v96, 0xbfb8aa3b, v48
	v_mul_f32_e32 v97, 0xbfb8aa3b, v49
	v_pk_fma_f32 v[52:53], v[44:45], v[60:61], v[52:53]
	v_exp_f32_e32 v96, v96
	v_exp_f32_e32 v97, v97
	v_mul_f32_e32 v54, 0xbfb8aa3b, v52
	v_mul_f32_e32 v55, 0xbfb8aa3b, v53
	v_exp_f32_e32 v54, v54
	v_exp_f32_e32 v55, v55
	v_add_f32_e32 v96, 1.0, v96
	v_add_f32_e32 v97, 1.0, v97
	v_rcp_f32_e32 v96, v96
	v_rcp_f32_e32 v97, v97
	v_add_f32_e32 v54, 1.0, v54
	v_add_f32_e32 v55, 1.0, v55
	v_pk_fma_f32 v[50:51], v[90:91], v[50:51], v[94:95]
	v_rcp_f32_e32 v54, v54
	v_rcp_f32_e32 v55, v55
	v_pk_fma_f32 v[50:51], v[86:87], v[116:117], v[50:51]
	v_pk_fma_f32 v[106:107], v[88:89], v[106:107], v[92:93]
	v_pk_fma_f32 v[50:51], v[34:35], v[58:59], v[50:51]
	v_pk_mul_f32 v[48:49], v[48:49], v[96:97]
	v_pk_fma_f32 v[106:107], v[84:85], v[110:111], v[106:107]
	v_pk_mul_f32 v[48:49], v[50:51], v[48:49]
	v_pk_fma_f32 v[98:99], v[32:33], v[56:57], v[106:107]
	v_pk_mul_f32 v[52:53], v[52:53], v[54:55]
	v_cvt_pk_bf16_f32 v51, v48, v49
	v_pk_mul_f32 v[52:53], v[98:99], v[52:53]
	v_mul_u32_u24_e32 v48, s96, v197
	v_cvt_pk_bf16_f32 v50, v52, v53
	v_lshl_add_u32 v48, v190, 1, v48
	global_store_dwordx2 v48, v[50:51], s[36:37] offset:8
.LBB0_2298:
	s_or_b64 exec, exec, s[0:1]
	v_mov_b32_e32 v199, v198
	v_mov_b32_e32 v48, v198
	v_mov_b32_e32 v49, v198
	v_pk_mul_f32 v[30:31], v[30:31], v[48:49]
	v_pk_mul_f32 v[28:29], v[28:29], v[198:199]
	v_pk_mul_f32 v[26:27], v[26:27], v[48:49]
	v_pk_mul_f32 v[24:25], v[24:25], v[198:199]
	v_mov_b32_dpp v52, v44 row_shl:15 row_mask:0xf bank_mask:0xf bound_ctrl:1
	v_mov_b32_dpp v44, v44 row_shl:14 row_mask:0xf bank_mask:0xf bound_ctrl:1
	v_mov_b32_dpp v104, v32 row_shl:15 row_mask:0xf bank_mask:0xf bound_ctrl:1
	v_mov_b32_dpp v100, v32 row_shl:14 row_mask:0xf bank_mask:0xf bound_ctrl:1
	v_mov_b32_dpp v53, v45 row_shl:15 row_mask:0xf bank_mask:0xf bound_ctrl:1
	v_mov_b32_dpp v45, v45 row_shl:14 row_mask:0xf bank_mask:0xf bound_ctrl:1
	v_mov_b32_dpp v105, v33 row_shl:15 row_mask:0xf bank_mask:0xf bound_ctrl:1
	v_mov_b32_dpp v101, v33 row_shl:14 row_mask:0xf bank_mask:0xf bound_ctrl:1
	v_mov_b32_dpp v96, v46 row_shl:15 row_mask:0xf bank_mask:0xf bound_ctrl:1
	v_mov_b32_dpp v46, v46 row_shl:14 row_mask:0xf bank_mask:0xf bound_ctrl:1
	v_mov_b32_dpp v110, v34 row_shl:15 row_mask:0xf bank_mask:0xf bound_ctrl:1
	v_mov_b32_dpp v34, v34 row_shl:14 row_mask:0xf bank_mask:0xf bound_ctrl:1
	v_mov_b32_dpp v97, v47 row_shl:15 row_mask:0xf bank_mask:0xf bound_ctrl:1
	v_mov_b32_dpp v47, v47 row_shl:14 row_mask:0xf bank_mask:0xf bound_ctrl:1
	v_mov_b32_dpp v111, v35 row_shl:15 row_mask:0xf bank_mask:0xf bound_ctrl:1
	v_mov_b32_dpp v35, v35 row_shl:14 row_mask:0xf bank_mask:0xf bound_ctrl:1
	v_add_f32_dpp v50, v28, v52 row_shr:1 row_mask:0xf bank_mask:0xf bound_ctrl:1
	v_add_f32_dpp v44, v28, v44 row_shr:2 row_mask:0xf bank_mask:0xf bound_ctrl:1
	v_add_f32_dpp v102, v24, v104 row_shr:1 row_mask:0xf bank_mask:0xf bound_ctrl:1
	v_add_f32_dpp v98, v24, v100 row_shr:2 row_mask:0xf bank_mask:0xf bound_ctrl:1
	v_add_f32_dpp v51, v29, v53 row_shr:1 row_mask:0xf bank_mask:0xf bound_ctrl:1
	v_add_f32_dpp v45, v29, v45 row_shr:2 row_mask:0xf bank_mask:0xf bound_ctrl:1
	v_add_f32_dpp v103, v25, v105 row_shr:1 row_mask:0xf bank_mask:0xf bound_ctrl:1
	v_add_f32_dpp v99, v25, v101 row_shr:2 row_mask:0xf bank_mask:0xf bound_ctrl:1
	v_add_f32_dpp v54, v30, v96 row_shr:1 row_mask:0xf bank_mask:0xf bound_ctrl:1
	v_add_f32_dpp v32, v30, v46 row_shr:2 row_mask:0xf bank_mask:0xf bound_ctrl:1
	v_add_f32_dpp v108, v26, v110 row_shr:1 row_mask:0xf bank_mask:0xf bound_ctrl:1
	v_add_f32_dpp v34, v26, v34 row_shr:2 row_mask:0xf bank_mask:0xf bound_ctrl:1
	v_add_f32_dpp v55, v31, v97 row_shr:1 row_mask:0xf bank_mask:0xf bound_ctrl:1
	v_add_f32_dpp v33, v31, v47 row_shr:2 row_mask:0xf bank_mask:0xf bound_ctrl:1
	v_add_f32_dpp v109, v27, v111 row_shr:1 row_mask:0xf bank_mask:0xf bound_ctrl:1
	v_add_f32_dpp v35, v27, v35 row_shr:2 row_mask:0xf bank_mask:0xf bound_ctrl:1
	s_and_saveexec_b64 s[0:1], s[14:15]
	s_cbranch_execz .LBB0_2300
	v_pk_fma_f32 v[32:33], v[78:79], v[32:33], v[82:83]
	v_pk_fma_f32 v[32:33], v[66:67], v[54:55], v[32:33]
	v_pk_fma_f32 v[44:45], v[76:77], v[44:45], v[80:81]
	v_pk_fma_f32 v[32:33], v[30:31], v[62:63], v[32:33]
	v_pk_fma_f32 v[44:45], v[64:65], v[50:51], v[44:45]
	v_mul_f32_e32 v48, 0xbfb8aa3b, v32
	v_mul_f32_e32 v49, 0xbfb8aa3b, v33
	v_pk_fma_f32 v[44:45], v[28:29], v[60:61], v[44:45]
	v_exp_f32_e32 v48, v48
	v_exp_f32_e32 v49, v49
	v_mul_f32_e32 v46, 0xbfb8aa3b, v44
	v_mul_f32_e32 v47, 0xbfb8aa3b, v45
	v_exp_f32_e32 v46, v46
	v_exp_f32_e32 v47, v47
	v_add_f32_e32 v48, 1.0, v48
	v_add_f32_e32 v49, 1.0, v49
	v_rcp_f32_e32 v48, v48
	v_rcp_f32_e32 v49, v49
	v_add_f32_e32 v46, 1.0, v46
	v_add_f32_e32 v47, 1.0, v47
	v_pk_fma_f32 v[34:35], v[90:91], v[34:35], v[94:95]
	v_rcp_f32_e32 v46, v46
	v_rcp_f32_e32 v47, v47
	v_pk_fma_f32 v[34:35], v[86:87], v[108:109], v[34:35]
	v_pk_fma_f32 v[98:99], v[88:89], v[98:99], v[92:93]
	v_pk_fma_f32 v[34:35], v[26:27], v[58:59], v[34:35]
	v_pk_mul_f32 v[32:33], v[32:33], v[48:49]
	v_pk_fma_f32 v[98:99], v[84:85], v[102:103], v[98:99]
	v_pk_mul_f32 v[32:33], v[34:35], v[32:33]
	v_pk_fma_f32 v[50:51], v[24:25], v[56:57], v[98:99]
	v_pk_mul_f32 v[44:45], v[44:45], v[46:47]
	v_cvt_pk_bf16_f32 v35, v32, v33
	v_pk_mul_f32 v[44:45], v[50:51], v[44:45]
	v_mul_u32_u24_e32 v32, s96, v195
	v_cvt_pk_bf16_f32 v34, v44, v45
	v_lshl_add_u32 v32, v190, 1, v32
	global_store_dwordx2 v32, v[34:35], s[36:37] offset:8
.LBB0_2300:
	s_or_b64 exec, exec, s[0:1]
	v_mov_b32_dpp v44, v28 row_shl:15 row_mask:0xf bank_mask:0xf bound_ctrl:1
	v_mov_b32_dpp v28, v28 row_shl:14 row_mask:0xf bank_mask:0xf bound_ctrl:1
	v_mov_b32_dpp v96, v24 row_shl:15 row_mask:0xf bank_mask:0xf bound_ctrl:1
	v_mov_b32_dpp v52, v24 row_shl:14 row_mask:0xf bank_mask:0xf bound_ctrl:1
	v_mov_b32_dpp v45, v29 row_shl:15 row_mask:0xf bank_mask:0xf bound_ctrl:1
	v_mov_b32_dpp v29, v29 row_shl:14 row_mask:0xf bank_mask:0xf bound_ctrl:1
	v_mov_b32_dpp v97, v25 row_shl:15 row_mask:0xf bank_mask:0xf bound_ctrl:1
	v_mov_b32_dpp v53, v25 row_shl:14 row_mask:0xf bank_mask:0xf bound_ctrl:1
	v_mov_b32_dpp v48, v30 row_shl:15 row_mask:0xf bank_mask:0xf bound_ctrl:1
	v_mov_b32_dpp v30, v30 row_shl:14 row_mask:0xf bank_mask:0xf bound_ctrl:1
	v_mov_b32_dpp v102, v26 row_shl:15 row_mask:0xf bank_mask:0xf bound_ctrl:1
	v_mov_b32_dpp v26, v26 row_shl:14 row_mask:0xf bank_mask:0xf bound_ctrl:1
	v_mov_b32_dpp v49, v31 row_shl:15 row_mask:0xf bank_mask:0xf bound_ctrl:1
	v_mov_b32_dpp v31, v31 row_shl:14 row_mask:0xf bank_mask:0xf bound_ctrl:1
	v_mov_b32_dpp v103, v27 row_shl:15 row_mask:0xf bank_mask:0xf bound_ctrl:1
	v_mov_b32_dpp v27, v27 row_shl:14 row_mask:0xf bank_mask:0xf bound_ctrl:1
	v_add_f32_dpp v34, v72, v44 row_shr:1 row_mask:0xf bank_mask:0xf bound_ctrl:1
	v_add_f32_dpp v28, v72, v28 row_shr:2 row_mask:0xf bank_mask:0xf bound_ctrl:1
	v_add_f32_dpp v54, v68, v96 row_shr:1 row_mask:0xf bank_mask:0xf bound_ctrl:1
	v_add_f32_dpp v50, v68, v52 row_shr:2 row_mask:0xf bank_mask:0xf bound_ctrl:1
	v_add_f32_dpp v35, v73, v45 row_shr:1 row_mask:0xf bank_mask:0xf bound_ctrl:1
	v_add_f32_dpp v29, v73, v29 row_shr:2 row_mask:0xf bank_mask:0xf bound_ctrl:1
	v_add_f32_dpp v55, v69, v97 row_shr:1 row_mask:0xf bank_mask:0xf bound_ctrl:1
	v_add_f32_dpp v51, v69, v53 row_shr:2 row_mask:0xf bank_mask:0xf bound_ctrl:1
	v_add_f32_dpp v46, v74, v48 row_shr:1 row_mask:0xf bank_mask:0xf bound_ctrl:1
	v_add_f32_dpp v24, v74, v30 row_shr:2 row_mask:0xf bank_mask:0xf bound_ctrl:1
	v_add_f32_dpp v100, v70, v102 row_shr:1 row_mask:0xf bank_mask:0xf bound_ctrl:1
	v_add_f32_dpp v26, v70, v26 row_shr:2 row_mask:0xf bank_mask:0xf bound_ctrl:1
	v_add_f32_dpp v47, v75, v49 row_shr:1 row_mask:0xf bank_mask:0xf bound_ctrl:1
	v_add_f32_dpp v25, v75, v31 row_shr:2 row_mask:0xf bank_mask:0xf bound_ctrl:1
	v_add_f32_dpp v101, v71, v103 row_shr:1 row_mask:0xf bank_mask:0xf bound_ctrl:1
	v_add_f32_dpp v27, v71, v27 row_shr:2 row_mask:0xf bank_mask:0xf bound_ctrl:1
	s_and_saveexec_b64 s[0:1], s[22:23]
	s_cbranch_execz .LBB0_2302
	v_pk_fma_f32 v[24:25], v[78:79], v[24:25], v[82:83]
	v_pk_fma_f32 v[24:25], v[66:67], v[46:47], v[24:25]
	v_pk_fma_f32 v[28:29], v[76:77], v[28:29], v[80:81]
	v_pk_fma_f32 v[24:25], v[74:75], v[62:63], v[24:25]
	v_pk_fma_f32 v[28:29], v[64:65], v[34:35], v[28:29]
	v_mul_f32_e32 v32, 0xbfb8aa3b, v24
	v_mul_f32_e32 v33, 0xbfb8aa3b, v25
	v_pk_fma_f32 v[28:29], v[72:73], v[60:61], v[28:29]
	v_exp_f32_e32 v32, v32
	v_exp_f32_e32 v33, v33
	v_mul_f32_e32 v30, 0xbfb8aa3b, v28
	v_mul_f32_e32 v31, 0xbfb8aa3b, v29
	v_exp_f32_e32 v30, v30
	v_exp_f32_e32 v31, v31
	v_add_f32_e32 v32, 1.0, v32
	v_add_f32_e32 v33, 1.0, v33
	v_rcp_f32_e32 v32, v32
	v_rcp_f32_e32 v33, v33
	v_add_f32_e32 v30, 1.0, v30
	v_add_f32_e32 v31, 1.0, v31
	v_pk_fma_f32 v[26:27], v[90:91], v[26:27], v[94:95]
	v_rcp_f32_e32 v30, v30
	v_rcp_f32_e32 v31, v31
	v_pk_fma_f32 v[26:27], v[86:87], v[100:101], v[26:27]
	v_pk_fma_f32 v[50:51], v[88:89], v[50:51], v[92:93]
	v_pk_fma_f32 v[26:27], v[70:71], v[58:59], v[26:27]
	v_pk_mul_f32 v[24:25], v[24:25], v[32:33]
	v_pk_fma_f32 v[50:51], v[84:85], v[54:55], v[50:51]
	v_pk_mul_f32 v[24:25], v[26:27], v[24:25]
	v_pk_fma_f32 v[34:35], v[68:69], v[56:57], v[50:51]
	v_pk_mul_f32 v[28:29], v[28:29], v[30:31]
	v_cvt_pk_bf16_f32 v27, v24, v25
	v_pk_mul_f32 v[28:29], v[34:35], v[28:29]
	v_mul_u32_u24_e32 v24, s96, v168
	v_cvt_pk_bf16_f32 v26, v28, v29
	v_lshl_add_u32 v24, v190, 1, v24
	global_store_dwordx2 v24, v[26:27], s[36:37] offset:8

.LBB0_2308:
	s_or_b64 exec, exec, s[0:1]
	v_mov_b32_e32 v197, v196
	s_waitcnt lgkmcnt(0)
	v_mov_b32_e32 v32, v196
	v_mov_b32_e32 v33, v196
	v_pk_mul_f32 v[22:23], v[22:23], v[32:33]
	v_pk_mul_f32 v[20:21], v[20:21], v[196:197]
	v_pk_mul_f32 v[18:19], v[18:19], v[32:33]
	v_pk_mul_f32 v[16:17], v[16:17], v[196:197]
	v_mov_b32_dpp v44, v20 row_shr:1 row_mask:0xf bank_mask:0xf bound_ctrl:1
	v_mov_b32_dpp v32, v20 row_shr:2 row_mask:0xf bank_mask:0xf bound_ctrl:1
	v_mov_b32_dpp v72, v16 row_shr:1 row_mask:0xf bank_mask:0xf bound_ctrl:1
	v_mov_b32_dpp v68, v16 row_shr:2 row_mask:0xf bank_mask:0xf bound_ctrl:1
	v_mov_b32_dpp v45, v21 row_shr:1 row_mask:0xf bank_mask:0xf bound_ctrl:1
	v_mov_b32_dpp v33, v21 row_shr:2 row_mask:0xf bank_mask:0xf bound_ctrl:1
	v_mov_b32_dpp v73, v17 row_shr:1 row_mask:0xf bank_mask:0xf bound_ctrl:1
	v_mov_b32_dpp v69, v17 row_shr:2 row_mask:0xf bank_mask:0xf bound_ctrl:1
	v_mov_b32_dpp v46, v22 row_shr:1 row_mask:0xf bank_mask:0xf bound_ctrl:1
	v_mov_b32_dpp v34, v22 row_shr:2 row_mask:0xf bank_mask:0xf bound_ctrl:1
	v_mov_b32_dpp v74, v18 row_shr:1 row_mask:0xf bank_mask:0xf bound_ctrl:1
	v_mov_b32_dpp v70, v18 row_shr:2 row_mask:0xf bank_mask:0xf bound_ctrl:1
	v_mov_b32_dpp v47, v23 row_shr:1 row_mask:0xf bank_mask:0xf bound_ctrl:1
	v_mov_b32_dpp v35, v23 row_shr:2 row_mask:0xf bank_mask:0xf bound_ctrl:1
	v_mov_b32_dpp v75, v19 row_shr:1 row_mask:0xf bank_mask:0xf bound_ctrl:1
	v_mov_b32_dpp v71, v19 row_shr:2 row_mask:0xf bank_mask:0xf bound_ctrl:1
	s_and_saveexec_b64 s[0:1], s[24:25]
	s_cbranch_execz .LBB0_2310
	v_pk_add_f32 v[24:25], v[24:25], v[32:33]
	v_pk_add_f32 v[26:27], v[26:27], v[34:35]
	v_pk_add_f32 v[46:47], v[50:51], v[46:47]
	v_pk_add_f32 v[44:45], v[48:49], v[44:45]
	v_pk_fma_f32 v[26:27], v[78:79], v[26:27], v[82:83]
	v_pk_fma_f32 v[24:25], v[76:77], v[24:25], v[80:81]
	v_pk_fma_f32 v[26:27], v[66:67], v[46:47], v[26:27]
	v_pk_fma_f32 v[24:25], v[64:65], v[44:45], v[24:25]
	v_pk_fma_f32 v[26:27], v[22:23], v[62:63], v[26:27]
	v_pk_fma_f32 v[24:25], v[20:21], v[60:61], v[24:25]
	v_mul_f32_e32 v34, 0xbfb8aa3b, v26
	v_mul_f32_e32 v32, 0xbfb8aa3b, v24
	v_mul_f32_e32 v33, 0xbfb8aa3b, v25
	v_mul_f32_e32 v35, 0xbfb8aa3b, v27
	v_exp_f32_e32 v32, v32
	v_exp_f32_e32 v33, v33
	v_exp_f32_e32 v34, v34
	v_exp_f32_e32 v35, v35
	v_add_f32_e32 v32, 1.0, v32
	v_add_f32_e32 v33, 1.0, v33
	v_add_f32_e32 v34, 1.0, v34
	v_add_f32_e32 v35, 1.0, v35
	v_rcp_f32_e32 v32, v32
	v_rcp_f32_e32 v33, v33
	v_rcp_f32_e32 v34, v34
	v_rcp_f32_e32 v35, v35
	v_pk_add_f32 v[28:29], v[28:29], v[68:69]
	v_pk_add_f32 v[30:31], v[30:31], v[70:71]
	v_pk_add_f32 v[54:55], v[54:55], v[74:75]
	v_pk_add_f32 v[52:53], v[52:53], v[72:73]
	v_pk_fma_f32 v[30:31], v[90:91], v[30:31], v[94:95]
	v_pk_fma_f32 v[28:29], v[88:89], v[28:29], v[92:93]
	v_pk_fma_f32 v[30:31], v[86:87], v[54:55], v[30:31]
	v_pk_fma_f32 v[28:29], v[84:85], v[52:53], v[28:29]
	v_pk_fma_f32 v[30:31], v[18:19], v[58:59], v[30:31]
	v_pk_fma_f32 v[28:29], v[16:17], v[56:57], v[28:29]
	v_pk_mul_f32 v[24:25], v[24:25], v[32:33]
	v_pk_mul_f32 v[26:27], v[26:27], v[34:35]
	v_pk_mul_f32 v[24:25], v[28:29], v[24:25]
	v_pk_mul_f32 v[26:27], v[30:31], v[26:27]
	v_cvt_pk_bf16_f32 v24, v24, v25
	v_cvt_pk_bf16_f32 v25, v26, v27
	v_mul_u32_u24_e32 v26, s96, v160
	v_lshl_add_u32 v26, v190, 1, v26
	global_store_dwordx2 v26, v[24:25], s[36:37] offset:8
.LBB0_2310:
	s_or_b64 exec, exec, s[0:1]
	v_mov_b32_e32 v195, v194
	v_mov_b32_e32 v24, v194
	v_mov_b32_e32 v25, v194
	v_pk_mul_f32 v[14:15], v[14:15], v[24:25]
	v_pk_mul_f32 v[12:13], v[12:13], v[194:195]
	v_pk_mul_f32 v[10:11], v[10:11], v[24:25]
	v_pk_mul_f32 v[8:9], v[8:9], v[194:195]
	v_mov_b32_dpp v28, v20 row_shl:15 row_mask:0xf bank_mask:0xf bound_ctrl:1
	v_mov_b32_dpp v20, v20 row_shl:14 row_mask:0xf bank_mask:0xf bound_ctrl:1
	v_mov_b32_dpp v48, v16 row_shl:15 row_mask:0xf bank_mask:0xf bound_ctrl:1
	v_mov_b32_dpp v44, v16 row_shl:14 row_mask:0xf bank_mask:0xf bound_ctrl:1
	v_mov_b32_dpp v29, v21 row_shl:15 row_mask:0xf bank_mask:0xf bound_ctrl:1
	v_mov_b32_dpp v21, v21 row_shl:14 row_mask:0xf bank_mask:0xf bound_ctrl:1
	v_mov_b32_dpp v49, v17 row_shl:15 row_mask:0xf bank_mask:0xf bound_ctrl:1
	v_mov_b32_dpp v45, v17 row_shl:14 row_mask:0xf bank_mask:0xf bound_ctrl:1
	v_mov_b32_dpp v32, v22 row_shl:15 row_mask:0xf bank_mask:0xf bound_ctrl:1
	v_mov_b32_dpp v22, v22 row_shl:14 row_mask:0xf bank_mask:0xf bound_ctrl:1
	v_mov_b32_dpp v54, v18 row_shl:15 row_mask:0xf bank_mask:0xf bound_ctrl:1
	v_mov_b32_dpp v18, v18 row_shl:14 row_mask:0xf bank_mask:0xf bound_ctrl:1
	v_mov_b32_dpp v33, v23 row_shl:15 row_mask:0xf bank_mask:0xf bound_ctrl:1
	v_mov_b32_dpp v23, v23 row_shl:14 row_mask:0xf bank_mask:0xf bound_ctrl:1
	v_mov_b32_dpp v55, v19 row_shl:15 row_mask:0xf bank_mask:0xf bound_ctrl:1
	v_mov_b32_dpp v19, v19 row_shl:14 row_mask:0xf bank_mask:0xf bound_ctrl:1
	v_add_f32_dpp v26, v12, v28 row_shr:1 row_mask:0xf bank_mask:0xf bound_ctrl:1
	v_add_f32_dpp v20, v12, v20 row_shr:2 row_mask:0xf bank_mask:0xf bound_ctrl:1
	v_add_f32_dpp v46, v8, v48 row_shr:1 row_mask:0xf bank_mask:0xf bound_ctrl:1
	v_add_f32_dpp v34, v8, v44 row_shr:2 row_mask:0xf bank_mask:0xf bound_ctrl:1
	v_add_f32_dpp v27, v13, v29 row_shr:1 row_mask:0xf bank_mask:0xf bound_ctrl:1
	v_add_f32_dpp v21, v13, v21 row_shr:2 row_mask:0xf bank_mask:0xf bound_ctrl:1
	v_add_f32_dpp v47, v9, v49 row_shr:1 row_mask:0xf bank_mask:0xf bound_ctrl:1
	v_add_f32_dpp v35, v9, v45 row_shr:2 row_mask:0xf bank_mask:0xf bound_ctrl:1
	v_add_f32_dpp v30, v14, v32 row_shr:1 row_mask:0xf bank_mask:0xf bound_ctrl:1
	v_add_f32_dpp v16, v14, v22 row_shr:2 row_mask:0xf bank_mask:0xf bound_ctrl:1
	v_add_f32_dpp v52, v10, v54 row_shr:1 row_mask:0xf bank_mask:0xf bound_ctrl:1
	v_add_f32_dpp v18, v10, v18 row_shr:2 row_mask:0xf bank_mask:0xf bound_ctrl:1
	v_add_f32_dpp v31, v15, v33 row_shr:1 row_mask:0xf bank_mask:0xf bound_ctrl:1
	v_add_f32_dpp v17, v15, v23 row_shr:2 row_mask:0xf bank_mask:0xf bound_ctrl:1
	v_add_f32_dpp v53, v11, v55 row_shr:1 row_mask:0xf bank_mask:0xf bound_ctrl:1
	v_add_f32_dpp v19, v11, v19 row_shr:2 row_mask:0xf bank_mask:0xf bound_ctrl:1
	s_and_saveexec_b64 s[0:1], s[18:19]
	s_cbranch_execz .LBB0_2312
	v_pk_fma_f32 v[16:17], v[78:79], v[16:17], v[82:83]
	v_pk_fma_f32 v[16:17], v[66:67], v[30:31], v[16:17]
	v_pk_fma_f32 v[20:21], v[76:77], v[20:21], v[80:81]
	v_pk_fma_f32 v[16:17], v[14:15], v[62:63], v[16:17]
	v_pk_fma_f32 v[20:21], v[64:65], v[26:27], v[20:21]
	v_mul_f32_e32 v24, 0xbfb8aa3b, v16
	v_mul_f32_e32 v25, 0xbfb8aa3b, v17
	v_pk_fma_f32 v[20:21], v[12:13], v[60:61], v[20:21]
	v_exp_f32_e32 v24, v24
	v_exp_f32_e32 v25, v25
	v_mul_f32_e32 v22, 0xbfb8aa3b, v20
	v_mul_f32_e32 v23, 0xbfb8aa3b, v21
	v_exp_f32_e32 v22, v22
	v_exp_f32_e32 v23, v23
	v_add_f32_e32 v24, 1.0, v24
	v_add_f32_e32 v25, 1.0, v25
	v_rcp_f32_e32 v24, v24
	v_rcp_f32_e32 v25, v25
	v_add_f32_e32 v22, 1.0, v22
	v_add_f32_e32 v23, 1.0, v23
	v_pk_fma_f32 v[18:19], v[90:91], v[18:19], v[94:95]
	v_rcp_f32_e32 v22, v22
	v_rcp_f32_e32 v23, v23
	v_pk_fma_f32 v[18:19], v[86:87], v[52:53], v[18:19]
	v_pk_fma_f32 v[34:35], v[88:89], v[34:35], v[92:93]
	v_pk_fma_f32 v[18:19], v[10:11], v[58:59], v[18:19]
	v_pk_mul_f32 v[16:17], v[16:17], v[24:25]
	v_pk_fma_f32 v[34:35], v[84:85], v[46:47], v[34:35]
	v_pk_mul_f32 v[16:17], v[18:19], v[16:17]
	v_pk_fma_f32 v[26:27], v[8:9], v[56:57], v[34:35]
	v_pk_mul_f32 v[20:21], v[20:21], v[22:23]
	v_cvt_pk_bf16_f32 v19, v16, v17
	v_pk_mul_f32 v[20:21], v[26:27], v[20:21]
	v_mul_u32_u24_e32 v16, s96, v152
	v_cvt_pk_bf16_f32 v18, v20, v21
	v_lshl_add_u32 v16, v190, 1, v16
	global_store_dwordx2 v16, v[18:19], s[36:37] offset:8
.LBB0_2312:
	s_or_b64 exec, exec, s[0:1]
	v_mov_b32_e32 v193, v192
	v_mov_b32_e32 v16, v192
	v_mov_b32_e32 v17, v192
	v_pk_mul_f32 v[6:7], v[6:7], v[16:17]
	v_pk_mul_f32 v[4:5], v[4:5], v[192:193]
	v_pk_mul_f32 v[2:3], v[2:3], v[16:17]
	v_pk_mul_f32 v[0:1], v[0:1], v[192:193]
	v_mov_b32_dpp v20, v12 row_shl:15 row_mask:0xf bank_mask:0xf bound_ctrl:1
	v_mov_b32_dpp v12, v12 row_shl:14 row_mask:0xf bank_mask:0xf bound_ctrl:1
	v_mov_b32_dpp v32, v8 row_shl:15 row_mask:0xf bank_mask:0xf bound_ctrl:1
	v_mov_b32_dpp v28, v8 row_shl:14 row_mask:0xf bank_mask:0xf bound_ctrl:1
	v_mov_b32_dpp v21, v13 row_shl:15 row_mask:0xf bank_mask:0xf bound_ctrl:1
	v_mov_b32_dpp v13, v13 row_shl:14 row_mask:0xf bank_mask:0xf bound_ctrl:1
	v_mov_b32_dpp v33, v9 row_shl:15 row_mask:0xf bank_mask:0xf bound_ctrl:1
	v_mov_b32_dpp v29, v9 row_shl:14 row_mask:0xf bank_mask:0xf bound_ctrl:1
	v_mov_b32_dpp v24, v14 row_shl:15 row_mask:0xf bank_mask:0xf bound_ctrl:1
	v_mov_b32_dpp v14, v14 row_shl:14 row_mask:0xf bank_mask:0xf bound_ctrl:1
	v_mov_b32_dpp v46, v10 row_shl:15 row_mask:0xf bank_mask:0xf bound_ctrl:1
	v_mov_b32_dpp v10, v10 row_shl:14 row_mask:0xf bank_mask:0xf bound_ctrl:1
	v_mov_b32_dpp v25, v15 row_shl:15 row_mask:0xf bank_mask:0xf bound_ctrl:1
	v_mov_b32_dpp v15, v15 row_shl:14 row_mask:0xf bank_mask:0xf bound_ctrl:1
	v_mov_b32_dpp v47, v11 row_shl:15 row_mask:0xf bank_mask:0xf bound_ctrl:1
	v_mov_b32_dpp v11, v11 row_shl:14 row_mask:0xf bank_mask:0xf bound_ctrl:1
	v_add_f32_dpp v18, v4, v20 row_shr:1 row_mask:0xf bank_mask:0xf bound_ctrl:1
	v_add_f32_dpp v12, v4, v12 row_shr:2 row_mask:0xf bank_mask:0xf bound_ctrl:1
	v_add_f32_dpp v30, v0, v32 row_shr:1 row_mask:0xf bank_mask:0xf bound_ctrl:1
	v_add_f32_dpp v26, v0, v28 row_shr:2 row_mask:0xf bank_mask:0xf bound_ctrl:1
	v_add_f32_dpp v19, v5, v21 row_shr:1 row_mask:0xf bank_mask:0xf bound_ctrl:1
	v_add_f32_dpp v13, v5, v13 row_shr:2 row_mask:0xf bank_mask:0xf bound_ctrl:1
	v_add_f32_dpp v31, v1, v33 row_shr:1 row_mask:0xf bank_mask:0xf bound_ctrl:1
	v_add_f32_dpp v27, v1, v29 row_shr:2 row_mask:0xf bank_mask:0xf bound_ctrl:1
	v_add_f32_dpp v22, v6, v24 row_shr:1 row_mask:0xf bank_mask:0xf bound_ctrl:1
	v_add_f32_dpp v8, v6, v14 row_shr:2 row_mask:0xf bank_mask:0xf bound_ctrl:1
	v_add_f32_dpp v44, v2, v46 row_shr:1 row_mask:0xf bank_mask:0xf bound_ctrl:1
	v_add_f32_dpp v10, v2, v10 row_shr:2 row_mask:0xf bank_mask:0xf bound_ctrl:1
	v_add_f32_dpp v23, v7, v25 row_shr:1 row_mask:0xf bank_mask:0xf bound_ctrl:1
	v_add_f32_dpp v9, v7, v15 row_shr:2 row_mask:0xf bank_mask:0xf bound_ctrl:1
	v_add_f32_dpp v45, v3, v47 row_shr:1 row_mask:0xf bank_mask:0xf bound_ctrl:1
	v_add_f32_dpp v11, v3, v11 row_shr:2 row_mask:0xf bank_mask:0xf bound_ctrl:1
	s_and_saveexec_b64 s[0:1], s[16:17]
	s_cbranch_execz .LBB0_2314
	v_pk_fma_f32 v[8:9], v[78:79], v[8:9], v[82:83]
	v_pk_fma_f32 v[8:9], v[66:67], v[22:23], v[8:9]
	v_pk_fma_f32 v[12:13], v[76:77], v[12:13], v[80:81]
	v_pk_fma_f32 v[8:9], v[6:7], v[62:63], v[8:9]
	v_pk_fma_f32 v[12:13], v[64:65], v[18:19], v[12:13]
	v_mul_f32_e32 v16, 0xbfb8aa3b, v8
	v_mul_f32_e32 v17, 0xbfb8aa3b, v9
	v_pk_fma_f32 v[12:13], v[4:5], v[60:61], v[12:13]
	v_exp_f32_e32 v16, v16
	v_exp_f32_e32 v17, v17
	v_mul_f32_e32 v14, 0xbfb8aa3b, v12
	v_mul_f32_e32 v15, 0xbfb8aa3b, v13
	v_exp_f32_e32 v14, v14
	v_exp_f32_e32 v15, v15
	v_add_f32_e32 v16, 1.0, v16
	v_add_f32_e32 v17, 1.0, v17
	v_rcp_f32_e32 v16, v16
	v_rcp_f32_e32 v17, v17
	v_add_f32_e32 v14, 1.0, v14
	v_add_f32_e32 v15, 1.0, v15
	v_pk_fma_f32 v[10:11], v[90:91], v[10:11], v[94:95]
	v_rcp_f32_e32 v14, v14
	v_rcp_f32_e32 v15, v15
	v_pk_fma_f32 v[10:11], v[86:87], v[44:45], v[10:11]
	v_pk_fma_f32 v[26:27], v[88:89], v[26:27], v[92:93]
	v_pk_fma_f32 v[10:11], v[2:3], v[58:59], v[10:11]
	v_pk_mul_f32 v[8:9], v[8:9], v[16:17]
	v_pk_fma_f32 v[26:27], v[84:85], v[30:31], v[26:27]
	v_pk_mul_f32 v[8:9], v[10:11], v[8:9]
	v_pk_fma_f32 v[18:19], v[0:1], v[56:57], v[26:27]
	v_pk_mul_f32 v[12:13], v[12:13], v[14:15]
	v_cvt_pk_bf16_f32 v11, v8, v9
	v_pk_mul_f32 v[12:13], v[18:19], v[12:13]
	v_mul_u32_u24_e32 v8, s96, v144
	v_cvt_pk_bf16_f32 v10, v12, v13
	v_lshl_add_u32 v8, v190, 1, v8
	global_store_dwordx2 v8, v[10:11], s[36:37] offset:8
.LBB0_2314:
	s_or_b64 exec, exec, s[0:1]
	v_mov_b32_dpp v12, v4 row_shl:15 row_mask:0xf bank_mask:0xf bound_ctrl:1
	v_mov_b32_dpp v4, v4 row_shl:14 row_mask:0xf bank_mask:0xf bound_ctrl:1
	v_mov_b32_dpp v24, v0 row_shl:15 row_mask:0xf bank_mask:0xf bound_ctrl:1
	v_mov_b32_dpp v20, v0 row_shl:14 row_mask:0xf bank_mask:0xf bound_ctrl:1
	v_mov_b32_dpp v13, v5 row_shl:15 row_mask:0xf bank_mask:0xf bound_ctrl:1
	v_mov_b32_dpp v5, v5 row_shl:14 row_mask:0xf bank_mask:0xf bound_ctrl:1
	v_mov_b32_dpp v25, v1 row_shl:15 row_mask:0xf bank_mask:0xf bound_ctrl:1
	v_mov_b32_dpp v21, v1 row_shl:14 row_mask:0xf bank_mask:0xf bound_ctrl:1
	v_mov_b32_dpp v16, v6 row_shl:15 row_mask:0xf bank_mask:0xf bound_ctrl:1
	v_mov_b32_dpp v6, v6 row_shl:14 row_mask:0xf bank_mask:0xf bound_ctrl:1
	v_mov_b32_dpp v30, v2 row_shl:15 row_mask:0xf bank_mask:0xf bound_ctrl:1
	v_mov_b32_dpp v2, v2 row_shl:14 row_mask:0xf bank_mask:0xf bound_ctrl:1
	v_mov_b32_dpp v17, v7 row_shl:15 row_mask:0xf bank_mask:0xf bound_ctrl:1
	v_mov_b32_dpp v7, v7 row_shl:14 row_mask:0xf bank_mask:0xf bound_ctrl:1
	v_mov_b32_dpp v31, v3 row_shl:15 row_mask:0xf bank_mask:0xf bound_ctrl:1
	v_mov_b32_dpp v3, v3 row_shl:14 row_mask:0xf bank_mask:0xf bound_ctrl:1
	v_add_f32_dpp v10, v40, v12 row_shr:1 row_mask:0xf bank_mask:0xf bound_ctrl:1
	v_add_f32_dpp v4, v40, v4 row_shr:2 row_mask:0xf bank_mask:0xf bound_ctrl:1
	v_add_f32_dpp v22, v36, v24 row_shr:1 row_mask:0xf bank_mask:0xf bound_ctrl:1
	v_add_f32_dpp v18, v36, v20 row_shr:2 row_mask:0xf bank_mask:0xf bound_ctrl:1
	v_add_f32_dpp v11, v41, v13 row_shr:1 row_mask:0xf bank_mask:0xf bound_ctrl:1
	v_add_f32_dpp v5, v41, v5 row_shr:2 row_mask:0xf bank_mask:0xf bound_ctrl:1
	v_add_f32_dpp v23, v37, v25 row_shr:1 row_mask:0xf bank_mask:0xf bound_ctrl:1
	v_add_f32_dpp v19, v37, v21 row_shr:2 row_mask:0xf bank_mask:0xf bound_ctrl:1
	v_add_f32_dpp v14, v42, v16 row_shr:1 row_mask:0xf bank_mask:0xf bound_ctrl:1
	v_add_f32_dpp v0, v42, v6 row_shr:2 row_mask:0xf bank_mask:0xf bound_ctrl:1
	v_add_f32_dpp v28, v38, v30 row_shr:1 row_mask:0xf bank_mask:0xf bound_ctrl:1
	v_add_f32_dpp v2, v38, v2 row_shr:2 row_mask:0xf bank_mask:0xf bound_ctrl:1
	v_add_f32_dpp v15, v43, v17 row_shr:1 row_mask:0xf bank_mask:0xf bound_ctrl:1
	v_add_f32_dpp v1, v43, v7 row_shr:2 row_mask:0xf bank_mask:0xf bound_ctrl:1
	v_add_f32_dpp v29, v39, v31 row_shr:1 row_mask:0xf bank_mask:0xf bound_ctrl:1
	v_add_f32_dpp v3, v39, v3 row_shr:2 row_mask:0xf bank_mask:0xf bound_ctrl:1
	s_and_saveexec_b64 s[0:1], s[26:27]
	s_cbranch_execz .LBB0_2316
	v_pk_fma_f32 v[0:1], v[78:79], v[0:1], v[82:83]
	v_pk_fma_f32 v[0:1], v[66:67], v[14:15], v[0:1]
	v_pk_fma_f32 v[4:5], v[76:77], v[4:5], v[80:81]
	v_pk_fma_f32 v[0:1], v[42:43], v[62:63], v[0:1]
	v_pk_fma_f32 v[4:5], v[64:65], v[10:11], v[4:5]
	v_mul_f32_e32 v8, 0xbfb8aa3b, v0
	v_mul_f32_e32 v9, 0xbfb8aa3b, v1
	v_pk_fma_f32 v[4:5], v[40:41], v[60:61], v[4:5]
	v_exp_f32_e32 v8, v8
	v_exp_f32_e32 v9, v9
	v_mul_f32_e32 v6, 0xbfb8aa3b, v4
	v_mul_f32_e32 v7, 0xbfb8aa3b, v5
	v_exp_f32_e32 v6, v6
	v_exp_f32_e32 v7, v7
	v_add_f32_e32 v8, 1.0, v8
	v_add_f32_e32 v9, 1.0, v9
	v_rcp_f32_e32 v8, v8
	v_rcp_f32_e32 v9, v9
	v_add_f32_e32 v6, 1.0, v6
	v_add_f32_e32 v7, 1.0, v7
	v_pk_fma_f32 v[2:3], v[90:91], v[2:3], v[94:95]
	v_rcp_f32_e32 v6, v6
	v_rcp_f32_e32 v7, v7
	v_pk_fma_f32 v[2:3], v[86:87], v[28:29], v[2:3]
	v_pk_fma_f32 v[18:19], v[88:89], v[18:19], v[92:93]
	v_pk_fma_f32 v[2:3], v[38:39], v[58:59], v[2:3]
	v_pk_mul_f32 v[0:1], v[0:1], v[8:9]
	v_pk_fma_f32 v[18:19], v[84:85], v[22:23], v[18:19]
	v_pk_mul_f32 v[0:1], v[2:3], v[0:1]
	v_pk_fma_f32 v[10:11], v[36:37], v[56:57], v[18:19]
	v_pk_mul_f32 v[4:5], v[4:5], v[6:7]
	v_cvt_pk_bf16_f32 v3, v0, v1
	v_pk_mul_f32 v[4:5], v[10:11], v[4:5]
	v_mul_u32_u24_e32 v0, s96, v145
	v_cvt_pk_bf16_f32 v2, v4, v5
	v_lshl_add_u32 v0, v190, 1, v0
	global_store_dwordx2 v0, v[2:3], s[36:37] offset:8
